# v43 + GEMM loops: dropped back-to-back s_setprio 0/1 pairs inside the MFMA stream and the redundant lgkmcnt(0) after the barrier
# baseline (speedup 1.0000x reference)
; #define PG8_STAGE(bufoff, gbase, voff) do { _Pragma("unroll") for (int _i = 0; _i < 2; ++_i) \
;         __builtin_amdgcn_global_load_lds((const unsigned*)((const char*)(gbase) + (voff)[_i]), (PG8_LAS unsigned*)(lds + (bufoff) + ldsw + _i * 8192), 16, 0, 0); } while (0)
; #define PG8_LDA(dst, b, h) do { _Pragma("unroll") for (int m = 0; m < 4; ++m) _Pragma("unroll") for (int k = 0; k < 2; ++k) dst[m][k] = *(const PG8_LAS bf16x8*)(lds + PG8_SA(b, h) + aoff + m * 2048 + k * 1024); } while (0)
; #define PG8_LDB(dst, b, h) do { _Pragma("unroll") for (int n = 0; n < 2; ++n) _Pragma("unroll") for (int k = 0; k < 2; ++k) dst[n][k] = *(const PG8_LAS bf16x8*)(lds + PG8_SB(b, h) + boff + n * 2048 + k * 1024); } while (0)
; #define PG8_MMA(ai, bj, At, Bt) do { __builtin_amdgcn_s_setprio(1); _Pragma("unroll") for (int m = 0; m < 4; ++m) _Pragma("unroll") for (int n = 0; n < 2; ++n) _Pragma("unroll") for (int k = 0; k < 2; ++k) \
;         acc[ai][bj][m][n] = __builtin_amdgcn_mfma_f32_16x16x32_bf16(Bt[n][k], At[m][k], acc[ai][bj][m][n], 0, 0, 0); __builtin_amdgcn_s_setprio(0); } while (0)
; #define PG8_WAIT_V(n) asm volatile("s_waitcnt vmcnt(" #n ")" ::: "memory")
; #define PG8_WAIT_L(n) asm volatile("s_waitcnt lgkmcnt(" #n ")" ::: "memory")
; #define PG8_BAR __builtin_amdgcn_s_barrier()
; #define PG8_SCHED __builtin_amdgcn_sched_barrier(0)
; template <class Epi, class Sched, bool ALIGN_EPI = false, bool SP2 = false>
; __device__ __forceinline__ void gemm_phase(PG8_LAS unsigned char* lds, const Gemm g, const Sched& S, const Epi& E) {
;     ...
;             if constexpr (SP2) {
;             PG8_LDB(B0, 0, 0); PG8_LDB(B1, 0, 1); PG8_SCHED; PG8_LDA(At, 0, 0); PG8_STAGE(PG8_SA(1, 1), a1 + hstep, voffA);
;             PG8_WAIT_V(8); PG8_WAIT_L(0); PG8_BAR; PG8_MMA(0, 0, At, B0); PG8_MMA(0, 1, At, B1); PG8_BAR; PG8_SCHED;
;             PG8_LDA(At, 0, 1); PG8_STAGE(PG8_SB(0, 0), b2, voffB); PG8_STAGE(PG8_SB(0, 1), b2 + hstep, voffB); PG8_STAGE(PG8_SA(0, 0), a2, voffA);
;             PG8_WAIT_V(8); PG8_WAIT_L(0); PG8_BAR; PG8_MMA(1, 0, At, B0); PG8_MMA(1, 1, At, B1); PG8_BAR; PG8_SCHED;
.LBB0_38:
	s_add_i32 s79, s20, 2
	s_add_u32 s59, s18, 0x80
	s_addc_u32 s21, s19, 0
	s_add_i32 s76, 0, 0x10000
	s_cmp_eq_u32 s57, s20
	s_cselect_b32 s21, s7, s21
	s_cselect_b32 s20, s6, s59
	s_cselect_b32 s81, s17, s77
	s_cselect_b32 s80, s16, s75
	s_add_i32 s59, 0, 0x14000
	v_add_u32_e32 v158, s76, v151
	v_add_u32_e32 v174, s59, v151
	ds_read_b128 v[138:141], v158
	ds_read_b128 v[142:145], v158 offset:1024
	ds_read_b128 v[146:149], v158 offset:2048
	ds_read_b128 v[158:161], v158 offset:3072
	ds_read_b128 v[162:165], v174
	ds_read_b128 v[166:169], v174 offset:1024
	ds_read_b128 v[170:173], v174 offset:2048
	ds_read_b128 v[174:177], v174 offset:3072
	v_lshl_add_u64 v[226:227], s[18:19], 0, v[132:133]
	s_add_i32 m0, s50, 0xc000
	ds_read_b128 v[178:181], v153
	ds_read_b128 v[198:201], v153 offset:1024
	ds_read_b128 v[202:205], v153 offset:2048
	ds_read_b128 v[206:209], v153 offset:3072
	ds_read_b128 v[210:213], v153 offset:4096
	ds_read_b128 v[214:217], v153 offset:5120
	ds_read_b128 v[218:221], v153 offset:6144
	ds_read_b128 v[222:225], v153 offset:7168
	global_load_lds_dwordx4 v[226:227], off
	v_lshl_add_u64 v[226:227], s[18:19], 0, v[134:135]
	s_add_i32 m0, s50, 0xe000
	s_nop 0
	global_load_lds_dwordx4 v[226:227], off
	s_waitcnt vmcnt(8)
	s_waitcnt lgkmcnt(0)
	s_barrier
	s_setprio 1
	v_mfma_f32_16x16x32_bf16 v[126:129], v[138:141], v[178:181], v[126:129]
	v_mfma_f32_16x16x32_bf16 v[122:125], v[146:149], v[178:181], v[122:125]
	v_mfma_f32_16x16x32_bf16 v[118:121], v[138:141], v[202:205], v[118:121]
	v_mfma_f32_16x16x32_bf16 v[114:117], v[146:149], v[202:205], v[114:117]
	v_mfma_f32_16x16x32_bf16 v[104:107], v[138:141], v[210:213], v[104:107]
	v_mfma_f32_16x16x32_bf16 v[96:99], v[146:149], v[210:213], v[96:99]
	v_mfma_f32_16x16x32_bf16 v[88:91], v[138:141], v[218:221], v[88:91]
	v_mfma_f32_16x16x32_bf16 v[80:83], v[146:149], v[218:221], v[80:83]
	v_mfma_f32_16x16x32_bf16 v[126:129], v[142:145], v[198:201], v[126:129]
	v_mfma_f32_16x16x32_bf16 v[122:125], v[158:161], v[198:201], v[122:125]
	v_mfma_f32_16x16x32_bf16 v[118:121], v[142:145], v[206:209], v[118:121]
	v_mfma_f32_16x16x32_bf16 v[114:117], v[158:161], v[206:209], v[114:117]
	v_mfma_f32_16x16x32_bf16 v[104:107], v[142:145], v[214:217], v[104:107]
	v_mfma_f32_16x16x32_bf16 v[96:99], v[158:161], v[214:217], v[96:99]
	v_mfma_f32_16x16x32_bf16 v[88:91], v[142:145], v[222:225], v[88:91]
	v_mfma_f32_16x16x32_bf16 v[80:83], v[158:161], v[222:225], v[80:83]
	v_mfma_f32_16x16x32_bf16 v[108:111], v[162:165], v[178:181], v[108:111]
	v_mfma_f32_16x16x32_bf16 v[100:103], v[170:173], v[178:181], v[100:103]
	v_mfma_f32_16x16x32_bf16 v[92:95], v[162:165], v[202:205], v[92:95]
	v_mfma_f32_16x16x32_bf16 v[84:87], v[170:173], v[202:205], v[84:87]
	v_mfma_f32_16x16x32_bf16 v[76:79], v[162:165], v[210:213], v[76:79]
	v_mfma_f32_16x16x32_bf16 v[72:75], v[170:173], v[210:213], v[72:75]
	v_mfma_f32_16x16x32_bf16 v[68:71], v[162:165], v[218:221], v[68:71]
	v_mfma_f32_16x16x32_bf16 v[64:67], v[170:173], v[218:221], v[64:67]
	v_mfma_f32_16x16x32_bf16 v[108:111], v[166:169], v[198:201], v[108:111]
	v_mfma_f32_16x16x32_bf16 v[100:103], v[174:177], v[198:201], v[100:103]
	v_mfma_f32_16x16x32_bf16 v[92:95], v[166:169], v[206:209], v[92:95]
	v_mfma_f32_16x16x32_bf16 v[84:87], v[174:177], v[206:209], v[84:87]
	v_mfma_f32_16x16x32_bf16 v[76:79], v[166:169], v[214:217], v[76:79]
	v_mfma_f32_16x16x32_bf16 v[72:75], v[174:177], v[214:217], v[72:75]
	v_mfma_f32_16x16x32_bf16 v[68:71], v[166:169], v[222:225], v[68:71]
	v_mfma_f32_16x16x32_bf16 v[64:67], v[174:177], v[222:225], v[64:67]
	s_setprio 0
	s_barrier
	s_add_i32 s76, s76, s23
	v_lshl_add_u64 v[226:227], s[80:81], 0, v[112:113]
	s_mov_b32 m0, s76
	ds_read_b128 v[178:181], v153 offset:16384
	ds_read_b128 v[198:201], v153 offset:17408
	ds_read_b128 v[202:205], v153 offset:18432
	ds_read_b128 v[206:209], v153 offset:19456
	ds_read_b128 v[210:213], v153 offset:20480
	ds_read_b128 v[214:217], v153 offset:21504
	ds_read_b128 v[218:221], v153 offset:22528
	ds_read_b128 v[222:225], v153 offset:23552
	global_load_lds_dwordx4 v[226:227], off
	s_add_i32 m0, s76, 0x2000
	v_lshl_add_u64 v[228:229], s[80:81], 0, v[130:131]
	s_add_u32 s80, s80, s8
	s_addc_u32 s81, s81, s9
	s_add_i32 s59, s59, s23
	global_load_lds_dwordx4 v[228:229], off
	v_lshl_add_u64 v[234:235], s[80:81], 0, v[112:113]
	s_mov_b32 m0, s59
	v_lshl_add_u64 v[236:237], s[80:81], 0, v[130:131]
	global_load_lds_dwordx4 v[234:235], off
	s_add_i32 m0, s59, 0x2000
	v_lshl_add_u64 v[238:239], s[20:21], 0, v[112:113]
	global_load_lds_dwordx4 v[236:237], off
	s_mov_b32 m0, s50
	v_lshl_add_u64 v[240:241], s[20:21], 0, v[130:131]
	global_load_lds_dwordx4 v[238:239], off
	s_mov_b32 m0, s51
	s_nop 0
	global_load_lds_dwordx4 v[240:241], off
	s_waitcnt vmcnt(8)
	s_waitcnt lgkmcnt(0)
	s_barrier
; #define PG8_STAGE(bufoff, gbase, voff) do { _Pragma("unroll") for (int _i = 0; _i < 2; ++_i) \
;         __builtin_amdgcn_global_load_lds((const unsigned*)((const char*)(gbase) + (voff)[_i]), (PG8_LAS unsigned*)(lds + (bufoff) + ldsw + _i * 8192), 16, 0, 0); } while (0)
; #define PG8_LDA(dst, b, h) do { _Pragma("unroll") for (int m = 0; m < 4; ++m) _Pragma("unroll") for (int k = 0; k < 2; ++k) dst[m][k] = *(const PG8_LAS bf16x8*)(lds + PG8_SA(b, h) + aoff + m * 2048 + k * 1024); } while (0)
; #define PG8_LDB(dst, b, h) do { _Pragma("unroll") for (int n = 0; n < 2; ++n) _Pragma("unroll") for (int k = 0; k < 2; ++k) dst[n][k] = *(const PG8_LAS bf16x8*)(lds + PG8_SB(b, h) + boff + n * 2048 + k * 1024); } while (0)
; #define PG8_MMA(ai, bj, At, Bt) do { __builtin_amdgcn_s_setprio(1); _Pragma("unroll") for (int m = 0; m < 4; ++m) _Pragma("unroll") for (int n = 0; n < 2; ++n) _Pragma("unroll") for (int k = 0; k < 2; ++k) \
;         acc[ai][bj][m][n] = __builtin_amdgcn_mfma_f32_16x16x32_bf16(Bt[n][k], At[m][k], acc[ai][bj][m][n], 0, 0, 0); __builtin_amdgcn_s_setprio(0); } while (0)
; #define PG8_WAIT_V(n) asm volatile("s_waitcnt vmcnt(" #n ")" ::: "memory")
; #define PG8_WAIT_L(n) asm volatile("s_waitcnt lgkmcnt(" #n ")" ::: "memory")
; #define PG8_BAR __builtin_amdgcn_s_barrier()
; #define PG8_SCHED __builtin_amdgcn_sched_barrier(0)
; template <class Epi, class Sched, bool ALIGN_EPI = false, bool SP2 = false>
; __device__ __forceinline__ void gemm_phase(PG8_LAS unsigned char* lds, const Gemm g, const Sched& S, const Epi& E) {
;     ...
;             PG8_WAIT_V(8); PG8_WAIT_L(0); PG8_BAR; PG8_MMA(0, 0, At, B0); PG8_MMA(0, 1, At, B1); PG8_BAR; PG8_SCHED;
;             PG8_LDA(At, 0, 1); PG8_STAGE(PG8_SB(0, 0), b2, voffB); PG8_STAGE(PG8_SB(0, 1), b2 + hstep, voffB); PG8_STAGE(PG8_SA(0, 0), a2, voffA);
;             PG8_WAIT_V(8); PG8_WAIT_L(0); PG8_BAR; PG8_MMA(1, 0, At, B0); PG8_MMA(1, 1, At, B1); PG8_BAR; PG8_SCHED;
;             PG8_LDB(B0, 1, 0); PG8_LDB(B1, 1, 1); PG8_SCHED; PG8_LDA(At, 1, 0); PG8_STAGE(PG8_SA(0, 1), a2 + hstep, voffA);
;             PG8_WAIT_V(8); PG8_WAIT_L(0); PG8_BAR; PG8_MMA(0, 0, At, B0); PG8_MMA(0, 1, At, B1); PG8_BAR; PG8_SCHED;
	s_setprio 1
	v_mfma_f32_16x16x32_bf16 v[60:63], v[138:141], v[178:181], v[60:63]
	v_mfma_f32_16x16x32_bf16 v[56:59], v[146:149], v[178:181], v[56:59]
	v_mfma_f32_16x16x32_bf16 v[52:55], v[138:141], v[202:205], v[52:55]
	v_mfma_f32_16x16x32_bf16 v[48:51], v[146:149], v[202:205], v[48:51]
	v_mfma_f32_16x16x32_bf16 v[40:43], v[138:141], v[210:213], v[40:43]
	v_mfma_f32_16x16x32_bf16 v[32:35], v[146:149], v[210:213], v[32:35]
	v_mfma_f32_16x16x32_bf16 v[24:27], v[138:141], v[218:221], v[24:27]
	v_mfma_f32_16x16x32_bf16 v[16:19], v[146:149], v[218:221], v[16:19]
	v_mfma_f32_16x16x32_bf16 v[60:63], v[142:145], v[198:201], v[60:63]
	v_mfma_f32_16x16x32_bf16 v[56:59], v[158:161], v[198:201], v[56:59]
	v_mfma_f32_16x16x32_bf16 v[52:55], v[142:145], v[206:209], v[52:55]
	v_mfma_f32_16x16x32_bf16 v[48:51], v[158:161], v[206:209], v[48:51]
	v_mfma_f32_16x16x32_bf16 v[40:43], v[142:145], v[214:217], v[40:43]
	v_mfma_f32_16x16x32_bf16 v[32:35], v[158:161], v[214:217], v[32:35]
	v_mfma_f32_16x16x32_bf16 v[24:27], v[142:145], v[222:225], v[24:27]
	v_mfma_f32_16x16x32_bf16 v[16:19], v[158:161], v[222:225], v[16:19]
	v_mfma_f32_16x16x32_bf16 v[44:47], v[162:165], v[178:181], v[44:47]
	v_mfma_f32_16x16x32_bf16 v[36:39], v[170:173], v[178:181], v[36:39]
	v_mfma_f32_16x16x32_bf16 v[28:31], v[162:165], v[202:205], v[28:31]
	v_mfma_f32_16x16x32_bf16 v[20:23], v[170:173], v[202:205], v[20:23]
	v_mfma_f32_16x16x32_bf16 v[12:15], v[162:165], v[210:213], v[12:15]
	v_mfma_f32_16x16x32_bf16 v[8:11], v[170:173], v[210:213], v[8:11]
	v_mfma_f32_16x16x32_bf16 v[4:7], v[162:165], v[218:221], v[4:7]
	v_mfma_f32_16x16x32_bf16 v[0:3], v[170:173], v[218:221], v[0:3]
	v_mfma_f32_16x16x32_bf16 v[44:47], v[166:169], v[198:201], v[44:47]
	v_mfma_f32_16x16x32_bf16 v[36:39], v[174:177], v[198:201], v[36:39]
	v_mfma_f32_16x16x32_bf16 v[28:31], v[166:169], v[206:209], v[28:31]
	v_mfma_f32_16x16x32_bf16 v[20:23], v[174:177], v[206:209], v[20:23]
	v_mfma_f32_16x16x32_bf16 v[12:15], v[166:169], v[214:217], v[12:15]
	v_mfma_f32_16x16x32_bf16 v[8:11], v[174:177], v[214:217], v[8:11]
	v_mfma_f32_16x16x32_bf16 v[4:7], v[166:169], v[222:225], v[4:7]
	v_mfma_f32_16x16x32_bf16 v[0:3], v[174:177], v[222:225], v[0:3]
	s_setprio 0
	s_barrier
	s_add_i32 s59, 0, 0x18000
	s_add_i32 s76, 0, 0x1c000
	v_add_u32_e32 v158, s59, v151
	v_add_u32_e32 v174, s76, v151
	ds_read_b128 v[138:141], v158
	ds_read_b128 v[142:145], v158 offset:1024
	ds_read_b128 v[146:149], v158 offset:2048
	ds_read_b128 v[158:161], v158 offset:3072
	ds_read_b128 v[162:165], v174
	ds_read_b128 v[166:169], v174 offset:1024
	ds_read_b128 v[170:173], v174 offset:2048
	ds_read_b128 v[174:177], v174 offset:3072
	s_add_u32 s20, s20, s8
	s_addc_u32 s21, s21, s9
	s_mov_b32 m0, s54
	v_lshl_add_u64 v[242:243], s[20:21], 0, v[112:113]
	ds_read_b128 v[178:181], v153 offset:32768
	ds_read_b128 v[198:201], v153 offset:33792
	ds_read_b128 v[202:205], v153 offset:34816
	ds_read_b128 v[206:209], v153 offset:35840
	ds_read_b128 v[210:213], v153 offset:36864
	ds_read_b128 v[214:217], v153 offset:37888
	ds_read_b128 v[218:221], v153 offset:38912
	ds_read_b128 v[222:225], v153 offset:39936
	global_load_lds_dwordx4 v[242:243], off
	v_lshl_add_u64 v[242:243], s[20:21], 0, v[130:131]
	s_mov_b32 m0, s55
	s_nop 0
	global_load_lds_dwordx4 v[242:243], off
	s_waitcnt vmcnt(8)
	s_waitcnt lgkmcnt(0)
	s_barrier
	s_setprio 1
	v_mfma_f32_16x16x32_bf16 v[126:129], v[138:141], v[178:181], v[126:129]
	v_mfma_f32_16x16x32_bf16 v[122:125], v[146:149], v[178:181], v[122:125]
	v_mfma_f32_16x16x32_bf16 v[118:121], v[138:141], v[202:205], v[118:121]
	v_mfma_f32_16x16x32_bf16 v[114:117], v[146:149], v[202:205], v[114:117]
	v_mfma_f32_16x16x32_bf16 v[104:107], v[138:141], v[210:213], v[104:107]
	v_mfma_f32_16x16x32_bf16 v[96:99], v[146:149], v[210:213], v[96:99]
	v_mfma_f32_16x16x32_bf16 v[88:91], v[138:141], v[218:221], v[88:91]
	v_mfma_f32_16x16x32_bf16 v[80:83], v[146:149], v[218:221], v[80:83]
	v_mfma_f32_16x16x32_bf16 v[126:129], v[142:145], v[198:201], v[126:129]
	v_mfma_f32_16x16x32_bf16 v[122:125], v[158:161], v[198:201], v[122:125]
	v_mfma_f32_16x16x32_bf16 v[118:121], v[142:145], v[206:209], v[118:121]
	v_mfma_f32_16x16x32_bf16 v[114:117], v[158:161], v[206:209], v[114:117]
	v_mfma_f32_16x16x32_bf16 v[104:107], v[142:145], v[214:217], v[104:107]
	v_mfma_f32_16x16x32_bf16 v[96:99], v[158:161], v[214:217], v[96:99]
	v_mfma_f32_16x16x32_bf16 v[88:91], v[142:145], v[222:225], v[88:91]
	v_mfma_f32_16x16x32_bf16 v[80:83], v[158:161], v[222:225], v[80:83]
	v_mfma_f32_16x16x32_bf16 v[108:111], v[162:165], v[178:181], v[108:111]
	v_mfma_f32_16x16x32_bf16 v[100:103], v[170:173], v[178:181], v[100:103]
	v_mfma_f32_16x16x32_bf16 v[92:95], v[162:165], v[202:205], v[92:95]
	v_mfma_f32_16x16x32_bf16 v[84:87], v[170:173], v[202:205], v[84:87]
	v_mfma_f32_16x16x32_bf16 v[76:79], v[162:165], v[210:213], v[76:79]
	v_mfma_f32_16x16x32_bf16 v[72:75], v[170:173], v[210:213], v[72:75]
	v_mfma_f32_16x16x32_bf16 v[68:71], v[162:165], v[218:221], v[68:71]
	v_mfma_f32_16x16x32_bf16 v[64:67], v[170:173], v[218:221], v[64:67]
	v_mfma_f32_16x16x32_bf16 v[108:111], v[166:169], v[198:201], v[108:111]
	v_mfma_f32_16x16x32_bf16 v[100:103], v[174:177], v[198:201], v[100:103]
	v_mfma_f32_16x16x32_bf16 v[92:95], v[166:169], v[206:209], v[92:95]
	v_mfma_f32_16x16x32_bf16 v[84:87], v[174:177], v[206:209], v[84:87]
	v_mfma_f32_16x16x32_bf16 v[76:79], v[166:169], v[214:217], v[76:79]
	v_mfma_f32_16x16x32_bf16 v[72:75], v[174:177], v[214:217], v[72:75]
	v_mfma_f32_16x16x32_bf16 v[68:71], v[166:169], v[222:225], v[68:71]
	v_mfma_f32_16x16x32_bf16 v[64:67], v[174:177], v[222:225], v[64:67]
	s_setprio 0
	s_barrier
; #define PG8_STAGE(bufoff, gbase, voff) do { _Pragma("unroll") for (int _i = 0; _i < 2; ++_i) \
;         __builtin_amdgcn_global_load_lds((const unsigned*)((const char*)(gbase) + (voff)[_i]), (PG8_LAS unsigned*)(lds + (bufoff) + ldsw + _i * 8192), 16, 0, 0); } while (0)
; #define PG8_LDA(dst, b, h) do { _Pragma("unroll") for (int m = 0; m < 4; ++m) _Pragma("unroll") for (int k = 0; k < 2; ++k) dst[m][k] = *(const PG8_LAS bf16x8*)(lds + PG8_SA(b, h) + aoff + m * 2048 + k * 1024); } while (0)
; #define PG8_LDB(dst, b, h) do { _Pragma("unroll") for (int n = 0; n < 2; ++n) _Pragma("unroll") for (int k = 0; k < 2; ++k) dst[n][k] = *(const PG8_LAS bf16x8*)(lds + PG8_SB(b, h) + boff + n * 2048 + k * 1024); } while (0)
; #define PG8_MMA(ai, bj, At, Bt) do { __builtin_amdgcn_s_setprio(1); _Pragma("unroll") for (int m = 0; m < 4; ++m) _Pragma("unroll") for (int n = 0; n < 2; ++n) _Pragma("unroll") for (int k = 0; k < 2; ++k) \
;         acc[ai][bj][m][n] = __builtin_amdgcn_mfma_f32_16x16x32_bf16(Bt[n][k], At[m][k], acc[ai][bj][m][n], 0, 0, 0); __builtin_amdgcn_s_setprio(0); } while (0)
; #define PG8_WAIT_V(n) asm volatile("s_waitcnt vmcnt(" #n ")" ::: "memory")
; #define PG8_WAIT_L(n) asm volatile("s_waitcnt lgkmcnt(" #n ")" ::: "memory")
; #define PG8_BAR __builtin_amdgcn_s_barrier()
; #define PG8_SCHED __builtin_amdgcn_sched_barrier(0)
; template <class Epi, class Sched, bool ALIGN_EPI = false, bool SP2 = false>
; __device__ __forceinline__ void gemm_phase(PG8_LAS unsigned char* lds, const Gemm g, const Sched& S, const Epi& E) {
;     ...
;         for (int t = 0; t < nt; t += 2) {
;     ...
;             PG8_WAIT_V(8); PG8_WAIT_L(0); PG8_BAR; PG8_MMA(1, 0, At, B0); PG8_MMA(1, 1, At, B1); PG8_BAR; PG8_SCHED;
;             PG8_LDB(B0, 1, 0); PG8_LDB(B1, 1, 1); PG8_SCHED; PG8_LDA(At, 1, 0); PG8_STAGE(PG8_SA(0, 1), a2 + hstep, voffA);
;             PG8_WAIT_V(8); PG8_WAIT_L(0); PG8_BAR; PG8_MMA(0, 0, At, B0); PG8_MMA(0, 1, At, B1); PG8_BAR; PG8_SCHED;
;             PG8_LDA(At, 1, 1); PG8_STAGE(PG8_SB(1, 0), b3, voffB); PG8_STAGE(PG8_SB(1, 1), b3 + hstep, voffB); PG8_STAGE(PG8_SA(1, 0), a3, voffA);
;             PG8_WAIT_V(8); PG8_WAIT_L(0); PG8_BAR; PG8_MMA(1, 0, At, B0); PG8_MMA(1, 1, At, B1); PG8_BAR; PG8_SCHED;
	s_add_i32 s20, s59, s23
	v_lshl_add_u64 v[226:227], v[226:227], 0, s[52:53]
	s_mov_b32 m0, s20
	ds_read_b128 v[178:181], v153 offset:49152
	ds_read_b128 v[198:201], v153 offset:50176
	ds_read_b128 v[202:205], v153 offset:51200
	ds_read_b128 v[206:209], v153 offset:52224
	ds_read_b128 v[210:213], v153 offset:53248
	ds_read_b128 v[214:217], v153 offset:54272
	ds_read_b128 v[218:221], v153 offset:55296
	ds_read_b128 v[222:225], v153 offset:56320
	global_load_lds_dwordx4 v[226:227], off
	v_lshl_add_u64 v[226:227], v[228:229], 0, s[52:53]
	s_add_i32 m0, s20, 0x2000
	s_add_i32 s20, s76, s23
	global_load_lds_dwordx4 v[226:227], off
	v_lshl_add_u64 v[226:227], v[234:235], 0, s[52:53]
	s_mov_b32 m0, s20
	s_nop 0
	global_load_lds_dwordx4 v[226:227], off
	v_lshl_add_u64 v[226:227], v[236:237], 0, s[52:53]
	s_add_i32 m0, s20, 0x2000
	s_nop 0
	global_load_lds_dwordx4 v[226:227], off
	v_lshl_add_u64 v[226:227], v[238:239], 0, s[52:53]
	s_mov_b32 m0, s3
	s_nop 0
	global_load_lds_dwordx4 v[226:227], off
	v_lshl_add_u64 v[226:227], v[240:241], 0, s[52:53]
	s_mov_b32 m0, s56
	s_nop 0
	global_load_lds_dwordx4 v[226:227], off
	s_waitcnt vmcnt(8)
	s_waitcnt lgkmcnt(0)
	s_barrier
	s_setprio 1
	v_mfma_f32_16x16x32_bf16 v[60:63], v[138:141], v[178:181], v[60:63]
	v_mfma_f32_16x16x32_bf16 v[56:59], v[146:149], v[178:181], v[56:59]
	v_mfma_f32_16x16x32_bf16 v[52:55], v[138:141], v[202:205], v[52:55]
	v_mfma_f32_16x16x32_bf16 v[48:51], v[146:149], v[202:205], v[48:51]
	v_mfma_f32_16x16x32_bf16 v[40:43], v[138:141], v[210:213], v[40:43]
	v_mfma_f32_16x16x32_bf16 v[32:35], v[146:149], v[210:213], v[32:35]
	v_mfma_f32_16x16x32_bf16 v[24:27], v[138:141], v[218:221], v[24:27]
	v_mfma_f32_16x16x32_bf16 v[16:19], v[146:149], v[218:221], v[16:19]
	v_mfma_f32_16x16x32_bf16 v[60:63], v[142:145], v[198:201], v[60:63]
	v_mfma_f32_16x16x32_bf16 v[56:59], v[158:161], v[198:201], v[56:59]
	v_mfma_f32_16x16x32_bf16 v[52:55], v[142:145], v[206:209], v[52:55]
	v_mfma_f32_16x16x32_bf16 v[48:51], v[158:161], v[206:209], v[48:51]
	v_mfma_f32_16x16x32_bf16 v[40:43], v[142:145], v[214:217], v[40:43]
	v_mfma_f32_16x16x32_bf16 v[32:35], v[158:161], v[214:217], v[32:35]
	v_mfma_f32_16x16x32_bf16 v[24:27], v[142:145], v[222:225], v[24:27]
	v_mfma_f32_16x16x32_bf16 v[16:19], v[158:161], v[222:225], v[16:19]
	v_mfma_f32_16x16x32_bf16 v[44:47], v[162:165], v[178:181], v[44:47]
	v_mfma_f32_16x16x32_bf16 v[36:39], v[170:173], v[178:181], v[36:39]
	v_mfma_f32_16x16x32_bf16 v[28:31], v[162:165], v[202:205], v[28:31]
	v_mfma_f32_16x16x32_bf16 v[20:23], v[170:173], v[202:205], v[20:23]
	v_mfma_f32_16x16x32_bf16 v[12:15], v[162:165], v[210:213], v[12:15]
	v_mfma_f32_16x16x32_bf16 v[8:11], v[170:173], v[210:213], v[8:11]
	v_mfma_f32_16x16x32_bf16 v[4:7], v[162:165], v[218:221], v[4:7]
	v_mfma_f32_16x16x32_bf16 v[0:3], v[170:173], v[218:221], v[0:3]
	v_mfma_f32_16x16x32_bf16 v[44:47], v[166:169], v[198:201], v[44:47]
	v_mfma_f32_16x16x32_bf16 v[36:39], v[174:177], v[198:201], v[36:39]
	v_mfma_f32_16x16x32_bf16 v[28:31], v[166:169], v[206:209], v[28:31]
	v_mfma_f32_16x16x32_bf16 v[20:23], v[174:177], v[206:209], v[20:23]
	v_mfma_f32_16x16x32_bf16 v[12:15], v[166:169], v[214:217], v[12:15]
	v_mfma_f32_16x16x32_bf16 v[8:11], v[174:177], v[214:217], v[8:11]
	v_mfma_f32_16x16x32_bf16 v[4:7], v[166:169], v[222:225], v[4:7]
	v_mfma_f32_16x16x32_bf16 v[0:3], v[174:177], v[222:225], v[0:3]
	s_setprio 0
	s_barrier
	s_add_u32 s18, s18, 0x100
	s_addc_u32 s19, s19, 0
	s_add_u32 s75, s75, 0x100
	s_addc_u32 s77, s77, 0
	s_cmp_ge_i32 s79, s2
	s_mov_b32 s20, s79
	s_cbranch_scc0 .LBB0_38
;     __device__ __forceinline__ void operator()(const f32x4 (&acc)[2][2][4][2], const pg8::Unit& u, int wr, int wc, int fr, int fq) const {
;         const int col0 = u.pn * 256 + wc * 32 + 4 * fq;
; #pragma unroll
;         for (int ai = 0; ai < 2; ++ai)
; #pragma unroll
;             for (int m = 0; m < 4; ++m) {
;                 const size_t off = (size_t)(u.pm * 256 + ai * 128 + wr * 64 + m * 16 + fr) * DM + col0;
; #pragma unroll
;                 for (int bj = 0; bj < 2; ++bj)
; #pragma unroll
;                     for (int n = 0; n < 2; ++n) { const f32x4 b = *(const f32x4*)(base + off + bj * 128 + n * 16); *(f32x4*)(out + off + bj * 128 + n * 16) = b + acc[ai][bj][m][n] * scale; }
;             }
;     }
	v_pk_mul_f32 v[146:147], v[128:129], 0.5 op_sel_hi:[1,0]
	v_pk_mul_f32 v[148:149], v[126:127], 0.5 op_sel_hi:[1,0]
	v_pk_mul_f32 v[138:139], v[124:125], 0.5 op_sel_hi:[1,0]
	v_pk_mul_f32 v[140:141], v[122:123], 0.5 op_sel_hi:[1,0]
	v_pk_mul_f32 v[142:143], v[110:111], 0.5 op_sel_hi:[1,0]
	v_pk_mul_f32 v[144:145], v[108:109], 0.5 op_sel_hi:[1,0]
	v_pk_mul_f32 v[126:127], v[102:103], 0.5 op_sel_hi:[1,0]
	v_pk_mul_f32 v[128:129], v[100:101], 0.5 op_sel_hi:[1,0]
	v_pk_mul_f32 v[120:121], v[120:121], 0.5 op_sel_hi:[1,0]
	v_pk_mul_f32 v[118:119], v[118:119], 0.5 op_sel_hi:[1,0]
	v_pk_mul_f32 v[108:109], v[116:117], 0.5 op_sel_hi:[1,0]
	v_pk_mul_f32 v[110:111], v[114:115], 0.5 op_sel_hi:[1,0]
	v_pk_mul_f32 v[114:115], v[94:95], 0.5 op_sel_hi:[1,0]
	v_pk_mul_f32 v[116:117], v[92:93], 0.5 op_sel_hi:[1,0]
	v_pk_mul_f32 v[122:123], v[86:87], 0.5 op_sel_hi:[1,0]
	v_pk_mul_f32 v[124:125], v[84:85], 0.5 op_sel_hi:[1,0]
	v_pk_mul_f32 v[100:101], v[106:107], 0.5 op_sel_hi:[1,0]
	v_pk_mul_f32 v[102:103], v[104:105], 0.5 op_sel_hi:[1,0]
	v_pk_mul_f32 v[92:93], v[98:99], 0.5 op_sel_hi:[1,0]
	v_pk_mul_f32 v[94:95], v[96:97], 0.5 op_sel_hi:[1,0]
	v_pk_mul_f32 v[96:97], v[78:79], 0.5 op_sel_hi:[1,0]
	v_pk_mul_f32 v[98:99], v[76:77], 0.5 op_sel_hi:[1,0]
	v_pk_mul_f32 v[104:105], v[74:75], 0.5 op_sel_hi:[1,0]
	v_pk_mul_f32 v[106:107], v[72:73], 0.5 op_sel_hi:[1,0]
	v_pk_mul_f32 v[84:85], v[90:91], 0.5 op_sel_hi:[1,0]
	v_pk_mul_f32 v[86:87], v[88:89], 0.5 op_sel_hi:[1,0]
	v_pk_mul_f32 v[76:77], v[82:83], 0.5 op_sel_hi:[1,0]
	v_pk_mul_f32 v[78:79], v[80:81], 0.5 op_sel_hi:[1,0]
	v_pk_mul_f32 v[80:81], v[70:71], 0.5 op_sel_hi:[1,0]
	v_pk_mul_f32 v[82:83], v[68:69], 0.5 op_sel_hi:[1,0]
	v_pk_mul_f32 v[88:89], v[66:67], 0.5 op_sel_hi:[1,0]
	v_pk_mul_f32 v[90:91], v[64:65], 0.5 op_sel_hi:[1,0]
	v_pk_mul_f32 v[62:63], v[62:63], 0.5 op_sel_hi:[1,0]
	v_pk_mul_f32 v[60:61], v[60:61], 0.5 op_sel_hi:[1,0]
	v_pk_mul_f32 v[64:65], v[58:59], 0.5 op_sel_hi:[1,0]
	v_pk_mul_f32 v[66:67], v[56:57], 0.5 op_sel_hi:[1,0]
	v_pk_mul_f32 v[68:69], v[46:47], 0.5 op_sel_hi:[1,0]
	v_pk_mul_f32 v[70:71], v[44:45], 0.5 op_sel_hi:[1,0]
	v_pk_mul_f32 v[72:73], v[38:39], 0.5 op_sel_hi:[1,0]
	v_pk_mul_f32 v[74:75], v[36:37], 0.5 op_sel_hi:[1,0]
	v_pk_mul_f32 v[44:45], v[54:55], 0.5 op_sel_hi:[1,0]
	v_pk_mul_f32 v[46:47], v[52:53], 0.5 op_sel_hi:[1,0]
	v_pk_mul_f32 v[50:51], v[50:51], 0.5 op_sel_hi:[1,0]
	v_pk_mul_f32 v[48:49], v[48:49], 0.5 op_sel_hi:[1,0]
	v_pk_mul_f32 v[52:53], v[30:31], 0.5 op_sel_hi:[1,0]
	v_pk_mul_f32 v[54:55], v[28:29], 0.5 op_sel_hi:[1,0]
	v_pk_mul_f32 v[56:57], v[22:23], 0.5 op_sel_hi:[1,0]
	v_pk_mul_f32 v[58:59], v[20:21], 0.5 op_sel_hi:[1,0]
	v_pk_mul_f32 v[28:29], v[42:43], 0.5 op_sel_hi:[1,0]
	v_pk_mul_f32 v[30:31], v[40:41], 0.5 op_sel_hi:[1,0]
	v_pk_mul_f32 v[34:35], v[34:35], 0.5 op_sel_hi:[1,0]
	v_pk_mul_f32 v[32:33], v[32:33], 0.5 op_sel_hi:[1,0]
	v_pk_mul_f32 v[36:37], v[14:15], 0.5 op_sel_hi:[1,0]
	v_pk_mul_f32 v[38:39], v[12:13], 0.5 op_sel_hi:[1,0]
	v_pk_mul_f32 v[40:41], v[10:11], 0.5 op_sel_hi:[1,0]
	v_pk_mul_f32 v[42:43], v[8:9], 0.5 op_sel_hi:[1,0]
	v_pk_mul_f32 v[20:21], v[26:27], 0.5 op_sel_hi:[1,0]
	v_pk_mul_f32 v[22:23], v[24:25], 0.5 op_sel_hi:[1,0]
	v_pk_mul_f32 v[8:9], v[18:19], 0.5 op_sel_hi:[1,0]
	v_pk_mul_f32 v[12:13], v[16:17], 0.5 op_sel_hi:[1,0]
	v_pk_mul_f32 v[10:11], v[6:7], 0.5 op_sel_hi:[1,0]
	v_pk_mul_f32 v[14:15], v[4:5], 0.5 op_sel_hi:[1,0]
	v_pk_mul_f32 v[6:7], v[2:3], 0.5 op_sel_hi:[1,0]
	v_pk_mul_f32 v[4:5], v[0:1], 0.5 op_sel_hi:[1,0]
	v_readlane_b32 s75, v255, 7

; #define PG8_STAGE(bufoff, gbase, voff) do { _Pragma("unroll") for (int _i = 0; _i < 2; ++_i) \
;         __builtin_amdgcn_global_load_lds((const unsigned*)((const char*)(gbase) + (voff)[_i]), (PG8_LAS unsigned*)(lds + (bufoff) + ldsw + _i * 8192), 16, 0, 0); } while (0)
; #define PG8_LDA(dst, b, h) do { _Pragma("unroll") for (int m = 0; m < 4; ++m) _Pragma("unroll") for (int k = 0; k < 2; ++k) dst[m][k] = *(const PG8_LAS bf16x8*)(lds + PG8_SA(b, h) + aoff + m * 2048 + k * 1024); } while (0)
; #define PG8_LDB(dst, b, h) do { _Pragma("unroll") for (int n = 0; n < 2; ++n) _Pragma("unroll") for (int k = 0; k < 2; ++k) dst[n][k] = *(const PG8_LAS bf16x8*)(lds + PG8_SB(b, h) + boff + n * 2048 + k * 1024); } while (0)
; #define PG8_MMA(ai, bj, At, Bt) do { __builtin_amdgcn_s_setprio(1); _Pragma("unroll") for (int m = 0; m < 4; ++m) _Pragma("unroll") for (int n = 0; n < 2; ++n) _Pragma("unroll") for (int k = 0; k < 2; ++k) \
;         acc[ai][bj][m][n] = __builtin_amdgcn_mfma_f32_16x16x32_bf16(Bt[n][k], At[m][k], acc[ai][bj][m][n], 0, 0, 0); __builtin_amdgcn_s_setprio(0); } while (0)
; #define PG8_WAIT_V(n) asm volatile("s_waitcnt vmcnt(" #n ")" ::: "memory")
; #define PG8_WAIT_L(n) asm volatile("s_waitcnt lgkmcnt(" #n ")" ::: "memory")
; #define PG8_BAR __builtin_amdgcn_s_barrier()
; #define PG8_SCHED __builtin_amdgcn_sched_barrier(0)
; template <class Epi, class Sched, bool ALIGN_EPI = false, bool SP2 = false>
; __device__ __forceinline__ void gemm_phase(PG8_LAS unsigned char* lds, const Gemm g, const Sched& S, const Epi& E) {
;     ...
;             if constexpr (SP2) {
;             PG8_LDB(B0, 0, 0); PG8_LDB(B1, 0, 1); PG8_SCHED; PG8_LDA(At, 0, 0); PG8_STAGE(PG8_SA(1, 1), a1 + hstep, voffA);
;             PG8_WAIT_V(8); PG8_WAIT_L(0); PG8_BAR; PG8_MMA(0, 0, At, B0); PG8_MMA(0, 1, At, B1); PG8_BAR; PG8_SCHED;
;             PG8_LDA(At, 0, 1); PG8_STAGE(PG8_SB(0, 0), b2, voffB); PG8_STAGE(PG8_SB(0, 1), b2 + hstep, voffB); PG8_STAGE(PG8_SA(0, 0), a2, voffA);
;             PG8_WAIT_V(8); PG8_WAIT_L(0); PG8_BAR; PG8_MMA(1, 0, At, B0); PG8_MMA(1, 1, At, B1); PG8_BAR; PG8_SCHED;
.LBB0_72:
	s_add_i32 s81, s22, 2
	s_add_u32 s59, s20, 0x80
	s_addc_u32 s23, s21, 0
	s_add_i32 s76, 0, 0x10000
	s_cmp_eq_u32 s65, s22
	s_cselect_b32 s23, s7, s23
	s_cselect_b32 s22, s6, s59
	v_add_u32_e32 v152, s76, v141
	s_cselect_b32 s83, s19, s80
	s_cselect_b32 s82, s18, s79
	s_add_i32 s59, 0, 0x14000
	ds_read_b128 v[136:139], v152
	ds_read_b128 v[144:147], v152 offset:1024
	ds_read_b128 v[148:151], v152 offset:2048
	ds_read_b128 v[158:161], v152 offset:3072
	v_add_u32_e32 v152, s59, v141
	ds_read_b128 v[162:165], v152
	ds_read_b128 v[166:169], v152 offset:1024
	ds_read_b128 v[170:173], v152 offset:2048
	ds_read_b128 v[174:177], v152 offset:3072
	v_lshl_add_u64 v[152:153], s[20:21], 0, v[132:133]
	s_add_i32 m0, s50, 0xc000
	ds_read_b128 v[178:181], v143
	ds_read_b128 v[198:201], v143 offset:1024
	ds_read_b128 v[202:205], v143 offset:2048
	ds_read_b128 v[206:209], v143 offset:3072
	ds_read_b128 v[210:213], v143 offset:4096
	ds_read_b128 v[214:217], v143 offset:5120
	ds_read_b128 v[218:221], v143 offset:6144
	ds_read_b128 v[222:225], v143 offset:7168
	global_load_lds_dwordx4 v[152:153], off
	v_lshl_add_u64 v[152:153], s[20:21], 0, v[134:135]
	s_add_i32 m0, s50, 0xe000
	s_nop 0
	global_load_lds_dwordx4 v[152:153], off
	s_waitcnt vmcnt(8)
	s_waitcnt lgkmcnt(0)
	s_barrier
	s_setprio 1
	v_mfma_f32_16x16x32_bf16 v[126:129], v[136:139], v[178:181], v[126:129]
	v_mfma_f32_16x16x32_bf16 v[122:125], v[148:151], v[178:181], v[122:125]
	v_mfma_f32_16x16x32_bf16 v[108:111], v[136:139], v[202:205], v[108:111]
	v_mfma_f32_16x16x32_bf16 v[104:107], v[148:151], v[202:205], v[104:107]
	v_mfma_f32_16x16x32_bf16 v[92:95], v[136:139], v[210:213], v[92:95]
	v_mfma_f32_16x16x32_bf16 v[88:91], v[148:151], v[210:213], v[88:91]
	v_mfma_f32_16x16x32_bf16 v[76:79], v[136:139], v[218:221], v[76:79]
	v_mfma_f32_16x16x32_bf16 v[72:75], v[148:151], v[218:221], v[72:75]
	v_mfma_f32_16x16x32_bf16 v[126:129], v[144:147], v[198:201], v[126:129]
	v_mfma_f32_16x16x32_bf16 v[122:125], v[158:161], v[198:201], v[122:125]
	v_mfma_f32_16x16x32_bf16 v[108:111], v[144:147], v[206:209], v[108:111]
	v_mfma_f32_16x16x32_bf16 v[104:107], v[158:161], v[206:209], v[104:107]
	v_mfma_f32_16x16x32_bf16 v[92:95], v[144:147], v[214:217], v[92:95]
	v_mfma_f32_16x16x32_bf16 v[88:91], v[158:161], v[214:217], v[88:91]
	v_mfma_f32_16x16x32_bf16 v[76:79], v[144:147], v[222:225], v[76:79]
	v_mfma_f32_16x16x32_bf16 v[72:75], v[158:161], v[222:225], v[72:75]
	v_mfma_f32_16x16x32_bf16 v[118:121], v[162:165], v[178:181], v[118:121]
	v_mfma_f32_16x16x32_bf16 v[114:117], v[170:173], v[178:181], v[114:117]
	v_mfma_f32_16x16x32_bf16 v[100:103], v[162:165], v[202:205], v[100:103]
	v_mfma_f32_16x16x32_bf16 v[96:99], v[170:173], v[202:205], v[96:99]
	v_mfma_f32_16x16x32_bf16 v[84:87], v[162:165], v[210:213], v[84:87]
	v_mfma_f32_16x16x32_bf16 v[80:83], v[170:173], v[210:213], v[80:83]
	v_mfma_f32_16x16x32_bf16 v[68:71], v[162:165], v[218:221], v[68:71]
	v_mfma_f32_16x16x32_bf16 v[64:67], v[170:173], v[218:221], v[64:67]
	v_mfma_f32_16x16x32_bf16 v[118:121], v[166:169], v[198:201], v[118:121]
	v_mfma_f32_16x16x32_bf16 v[114:117], v[174:177], v[198:201], v[114:117]
	v_mfma_f32_16x16x32_bf16 v[100:103], v[166:169], v[206:209], v[100:103]
	v_mfma_f32_16x16x32_bf16 v[96:99], v[174:177], v[206:209], v[96:99]
	v_mfma_f32_16x16x32_bf16 v[84:87], v[166:169], v[214:217], v[84:87]
	v_mfma_f32_16x16x32_bf16 v[80:83], v[174:177], v[214:217], v[80:83]
	v_mfma_f32_16x16x32_bf16 v[68:71], v[166:169], v[222:225], v[68:71]
	v_mfma_f32_16x16x32_bf16 v[64:67], v[174:177], v[222:225], v[64:67]
	s_setprio 0
	s_barrier
	s_add_i32 s76, s76, s25
	v_lshl_add_u64 v[152:153], s[82:83], 0, v[112:113]
	s_mov_b32 m0, s76
	ds_read_b128 v[178:181], v143 offset:16384
	ds_read_b128 v[198:201], v143 offset:17408
	ds_read_b128 v[202:205], v143 offset:18432
	ds_read_b128 v[206:209], v143 offset:19456
	ds_read_b128 v[210:213], v143 offset:20480
	ds_read_b128 v[214:217], v143 offset:21504
	ds_read_b128 v[218:221], v143 offset:22528
	ds_read_b128 v[222:225], v143 offset:23552
	global_load_lds_dwordx4 v[152:153], off
	s_add_i32 m0, s76, 0x2000
	v_lshl_add_u64 v[226:227], s[82:83], 0, v[130:131]
	s_add_u32 s82, s82, s10
	s_addc_u32 s83, s83, s11
	s_add_i32 s59, s59, s25
	global_load_lds_dwordx4 v[226:227], off
	v_lshl_add_u64 v[228:229], s[82:83], 0, v[112:113]
	s_mov_b32 m0, s59
	v_lshl_add_u64 v[234:235], s[82:83], 0, v[130:131]
	global_load_lds_dwordx4 v[228:229], off
	s_add_i32 m0, s59, 0x2000
	v_lshl_add_u64 v[236:237], s[22:23], 0, v[112:113]
	global_load_lds_dwordx4 v[234:235], off
	s_mov_b32 m0, s50
	v_lshl_add_u64 v[238:239], s[22:23], 0, v[130:131]
	global_load_lds_dwordx4 v[236:237], off
	s_mov_b32 m0, s51
	s_nop 0
	global_load_lds_dwordx4 v[238:239], off
	s_waitcnt vmcnt(8)
	s_waitcnt lgkmcnt(0)
	s_barrier
; #define PG8_STAGE(bufoff, gbase, voff) do { _Pragma("unroll") for (int _i = 0; _i < 2; ++_i) \
;         __builtin_amdgcn_global_load_lds((const unsigned*)((const char*)(gbase) + (voff)[_i]), (PG8_LAS unsigned*)(lds + (bufoff) + ldsw + _i * 8192), 16, 0, 0); } while (0)
; #define PG8_LDA(dst, b, h) do { _Pragma("unroll") for (int m = 0; m < 4; ++m) _Pragma("unroll") for (int k = 0; k < 2; ++k) dst[m][k] = *(const PG8_LAS bf16x8*)(lds + PG8_SA(b, h) + aoff + m * 2048 + k * 1024); } while (0)
; #define PG8_LDB(dst, b, h) do { _Pragma("unroll") for (int n = 0; n < 2; ++n) _Pragma("unroll") for (int k = 0; k < 2; ++k) dst[n][k] = *(const PG8_LAS bf16x8*)(lds + PG8_SB(b, h) + boff + n * 2048 + k * 1024); } while (0)
; #define PG8_MMA(ai, bj, At, Bt) do { __builtin_amdgcn_s_setprio(1); _Pragma("unroll") for (int m = 0; m < 4; ++m) _Pragma("unroll") for (int n = 0; n < 2; ++n) _Pragma("unroll") for (int k = 0; k < 2; ++k) \
;         acc[ai][bj][m][n] = __builtin_amdgcn_mfma_f32_16x16x32_bf16(Bt[n][k], At[m][k], acc[ai][bj][m][n], 0, 0, 0); __builtin_amdgcn_s_setprio(0); } while (0)
; #define PG8_WAIT_V(n) asm volatile("s_waitcnt vmcnt(" #n ")" ::: "memory")
; #define PG8_WAIT_L(n) asm volatile("s_waitcnt lgkmcnt(" #n ")" ::: "memory")
; #define PG8_BAR __builtin_amdgcn_s_barrier()
; #define PG8_SCHED __builtin_amdgcn_sched_barrier(0)
; template <class Epi, class Sched, bool ALIGN_EPI = false, bool SP2 = false>
; __device__ __forceinline__ void gemm_phase(PG8_LAS unsigned char* lds, const Gemm g, const Sched& S, const Epi& E) {
;     ...
;             PG8_WAIT_V(8); PG8_WAIT_L(0); PG8_BAR; PG8_MMA(1, 0, At, B0); PG8_MMA(1, 1, At, B1); PG8_BAR; PG8_SCHED;
;             PG8_LDB(B0, 1, 0); PG8_LDB(B1, 1, 1); PG8_SCHED; PG8_LDA(At, 1, 0); PG8_STAGE(PG8_SA(0, 1), a2 + hstep, voffA);
;             PG8_WAIT_V(8); PG8_WAIT_L(0); PG8_BAR; PG8_MMA(0, 0, At, B0); PG8_MMA(0, 1, At, B1); PG8_BAR; PG8_SCHED;
	s_setprio 1
	v_mfma_f32_16x16x32_bf16 v[60:63], v[136:139], v[178:181], v[60:63]
	v_mfma_f32_16x16x32_bf16 v[56:59], v[148:151], v[178:181], v[56:59]
	v_mfma_f32_16x16x32_bf16 v[44:47], v[136:139], v[202:205], v[44:47]
	v_mfma_f32_16x16x32_bf16 v[40:43], v[148:151], v[202:205], v[40:43]
	v_mfma_f32_16x16x32_bf16 v[28:31], v[136:139], v[210:213], v[28:31]
	v_mfma_f32_16x16x32_bf16 v[24:27], v[148:151], v[210:213], v[24:27]
	v_mfma_f32_16x16x32_bf16 v[12:15], v[136:139], v[218:221], v[12:15]
	v_mfma_f32_16x16x32_bf16 v[8:11], v[148:151], v[218:221], v[8:11]
	v_mfma_f32_16x16x32_bf16 v[60:63], v[144:147], v[198:201], v[60:63]
	v_mfma_f32_16x16x32_bf16 v[56:59], v[158:161], v[198:201], v[56:59]
	v_mfma_f32_16x16x32_bf16 v[44:47], v[144:147], v[206:209], v[44:47]
	v_mfma_f32_16x16x32_bf16 v[40:43], v[158:161], v[206:209], v[40:43]
	v_mfma_f32_16x16x32_bf16 v[28:31], v[144:147], v[214:217], v[28:31]
	v_mfma_f32_16x16x32_bf16 v[24:27], v[158:161], v[214:217], v[24:27]
	v_mfma_f32_16x16x32_bf16 v[12:15], v[144:147], v[222:225], v[12:15]
	v_mfma_f32_16x16x32_bf16 v[8:11], v[158:161], v[222:225], v[8:11]
	v_mfma_f32_16x16x32_bf16 v[52:55], v[162:165], v[178:181], v[52:55]
	v_mfma_f32_16x16x32_bf16 v[48:51], v[170:173], v[178:181], v[48:51]
	v_mfma_f32_16x16x32_bf16 v[36:39], v[162:165], v[202:205], v[36:39]
	v_mfma_f32_16x16x32_bf16 v[32:35], v[170:173], v[202:205], v[32:35]
	v_mfma_f32_16x16x32_bf16 v[20:23], v[162:165], v[210:213], v[20:23]
	v_mfma_f32_16x16x32_bf16 v[16:19], v[170:173], v[210:213], v[16:19]
	v_mfma_f32_16x16x32_bf16 v[4:7], v[162:165], v[218:221], v[4:7]
	v_mfma_f32_16x16x32_bf16 v[0:3], v[170:173], v[218:221], v[0:3]
	v_mfma_f32_16x16x32_bf16 v[52:55], v[166:169], v[198:201], v[52:55]
	v_mfma_f32_16x16x32_bf16 v[48:51], v[174:177], v[198:201], v[48:51]
	v_mfma_f32_16x16x32_bf16 v[36:39], v[166:169], v[206:209], v[36:39]
	v_mfma_f32_16x16x32_bf16 v[32:35], v[174:177], v[206:209], v[32:35]
	v_mfma_f32_16x16x32_bf16 v[20:23], v[166:169], v[214:217], v[20:23]
	v_mfma_f32_16x16x32_bf16 v[16:19], v[174:177], v[214:217], v[16:19]
	v_mfma_f32_16x16x32_bf16 v[4:7], v[166:169], v[222:225], v[4:7]
	v_mfma_f32_16x16x32_bf16 v[0:3], v[174:177], v[222:225], v[0:3]
	s_setprio 0
	s_barrier
	s_add_i32 s59, 0, 0x18000
	s_add_i32 s76, 0, 0x1c000
	v_add_u32_e32 v158, s59, v141
	v_add_u32_e32 v174, s76, v141
	ds_read_b128 v[136:139], v158
	ds_read_b128 v[144:147], v158 offset:1024
	ds_read_b128 v[148:151], v158 offset:2048
	ds_read_b128 v[158:161], v158 offset:3072
	ds_read_b128 v[162:165], v174
	ds_read_b128 v[166:169], v174 offset:1024
	ds_read_b128 v[170:173], v174 offset:2048
	ds_read_b128 v[174:177], v174 offset:3072
	s_add_u32 s22, s22, s10
	s_addc_u32 s23, s23, s11
	s_mov_b32 m0, s54
	v_lshl_add_u64 v[240:241], s[22:23], 0, v[112:113]
	ds_read_b128 v[178:181], v143 offset:32768
	ds_read_b128 v[198:201], v143 offset:33792
	ds_read_b128 v[202:205], v143 offset:34816
	ds_read_b128 v[206:209], v143 offset:35840
	ds_read_b128 v[210:213], v143 offset:36864
	ds_read_b128 v[214:217], v143 offset:37888
	ds_read_b128 v[218:221], v143 offset:38912
	ds_read_b128 v[222:225], v143 offset:39936
	global_load_lds_dwordx4 v[240:241], off
	v_lshl_add_u64 v[240:241], s[22:23], 0, v[130:131]
	s_mov_b32 m0, s55
	s_nop 0
	global_load_lds_dwordx4 v[240:241], off
	s_waitcnt vmcnt(8)
	s_waitcnt lgkmcnt(0)
	s_barrier
	s_setprio 1
	v_mfma_f32_16x16x32_bf16 v[126:129], v[136:139], v[178:181], v[126:129]
	v_mfma_f32_16x16x32_bf16 v[122:125], v[148:151], v[178:181], v[122:125]
	v_mfma_f32_16x16x32_bf16 v[108:111], v[136:139], v[202:205], v[108:111]
	v_mfma_f32_16x16x32_bf16 v[104:107], v[148:151], v[202:205], v[104:107]
	v_mfma_f32_16x16x32_bf16 v[92:95], v[136:139], v[210:213], v[92:95]
	v_mfma_f32_16x16x32_bf16 v[88:91], v[148:151], v[210:213], v[88:91]
	v_mfma_f32_16x16x32_bf16 v[76:79], v[136:139], v[218:221], v[76:79]
	v_mfma_f32_16x16x32_bf16 v[72:75], v[148:151], v[218:221], v[72:75]
	v_mfma_f32_16x16x32_bf16 v[126:129], v[144:147], v[198:201], v[126:129]
	v_mfma_f32_16x16x32_bf16 v[122:125], v[158:161], v[198:201], v[122:125]
	v_mfma_f32_16x16x32_bf16 v[108:111], v[144:147], v[206:209], v[108:111]
	v_mfma_f32_16x16x32_bf16 v[104:107], v[158:161], v[206:209], v[104:107]
	v_mfma_f32_16x16x32_bf16 v[92:95], v[144:147], v[214:217], v[92:95]
	v_mfma_f32_16x16x32_bf16 v[88:91], v[158:161], v[214:217], v[88:91]
	v_mfma_f32_16x16x32_bf16 v[76:79], v[144:147], v[222:225], v[76:79]
	v_mfma_f32_16x16x32_bf16 v[72:75], v[158:161], v[222:225], v[72:75]
	v_mfma_f32_16x16x32_bf16 v[118:121], v[162:165], v[178:181], v[118:121]
	v_mfma_f32_16x16x32_bf16 v[114:117], v[170:173], v[178:181], v[114:117]
	v_mfma_f32_16x16x32_bf16 v[100:103], v[162:165], v[202:205], v[100:103]
	v_mfma_f32_16x16x32_bf16 v[96:99], v[170:173], v[202:205], v[96:99]
	v_mfma_f32_16x16x32_bf16 v[84:87], v[162:165], v[210:213], v[84:87]
	v_mfma_f32_16x16x32_bf16 v[80:83], v[170:173], v[210:213], v[80:83]
	v_mfma_f32_16x16x32_bf16 v[68:71], v[162:165], v[218:221], v[68:71]
	v_mfma_f32_16x16x32_bf16 v[64:67], v[170:173], v[218:221], v[64:67]
	v_mfma_f32_16x16x32_bf16 v[118:121], v[166:169], v[198:201], v[118:121]
	v_mfma_f32_16x16x32_bf16 v[114:117], v[174:177], v[198:201], v[114:117]
	v_mfma_f32_16x16x32_bf16 v[100:103], v[166:169], v[206:209], v[100:103]
	v_mfma_f32_16x16x32_bf16 v[96:99], v[174:177], v[206:209], v[96:99]
	v_mfma_f32_16x16x32_bf16 v[84:87], v[166:169], v[214:217], v[84:87]
	v_mfma_f32_16x16x32_bf16 v[80:83], v[174:177], v[214:217], v[80:83]
	v_mfma_f32_16x16x32_bf16 v[68:71], v[166:169], v[222:225], v[68:71]
	v_mfma_f32_16x16x32_bf16 v[64:67], v[174:177], v[222:225], v[64:67]
	s_setprio 0
	s_barrier
; #define PG8_STAGE(bufoff, gbase, voff) do { _Pragma("unroll") for (int _i = 0; _i < 2; ++_i) \
;         __builtin_amdgcn_global_load_lds((const unsigned*)((const char*)(gbase) + (voff)[_i]), (PG8_LAS unsigned*)(lds + (bufoff) + ldsw + _i * 8192), 16, 0, 0); } while (0)
; #define PG8_LDA(dst, b, h) do { _Pragma("unroll") for (int m = 0; m < 4; ++m) _Pragma("unroll") for (int k = 0; k < 2; ++k) dst[m][k] = *(const PG8_LAS bf16x8*)(lds + PG8_SA(b, h) + aoff + m * 2048 + k * 1024); } while (0)
; #define PG8_MMA(ai, bj, At, Bt) do { __builtin_amdgcn_s_setprio(1); _Pragma("unroll") for (int m = 0; m < 4; ++m) _Pragma("unroll") for (int n = 0; n < 2; ++n) _Pragma("unroll") for (int k = 0; k < 2; ++k) \
;         acc[ai][bj][m][n] = __builtin_amdgcn_mfma_f32_16x16x32_bf16(Bt[n][k], At[m][k], acc[ai][bj][m][n], 0, 0, 0); __builtin_amdgcn_s_setprio(0); } while (0)
; #define PG8_WAIT_V(n) asm volatile("s_waitcnt vmcnt(" #n ")" ::: "memory")
; #define PG8_WAIT_L(n) asm volatile("s_waitcnt lgkmcnt(" #n ")" ::: "memory")
; #define PG8_BAR __builtin_amdgcn_s_barrier()
; #define PG8_SCHED __builtin_amdgcn_sched_barrier(0)
; template <class Epi, class Sched, bool ALIGN_EPI = false, bool SP2 = false>
; __device__ __forceinline__ void gemm_phase(PG8_LAS unsigned char* lds, const Gemm g, const Sched& S, const Epi& E) {
;     ...
;             PG8_LDA(At, 1, 1); PG8_STAGE(PG8_SB(1, 0), b3, voffB); PG8_STAGE(PG8_SB(1, 1), b3 + hstep, voffB); PG8_STAGE(PG8_SA(1, 0), a3, voffA);
;             PG8_WAIT_V(8); PG8_WAIT_L(0); PG8_BAR; PG8_MMA(1, 0, At, B0); PG8_MMA(1, 1, At, B1); PG8_BAR; PG8_SCHED;
	s_add_i32 s22, s59, s25
	v_lshl_add_u64 v[152:153], v[152:153], 0, s[52:53]
	s_mov_b32 m0, s22
	ds_read_b128 v[178:181], v143 offset:49152
	ds_read_b128 v[198:201], v143 offset:50176
	ds_read_b128 v[202:205], v143 offset:51200
	ds_read_b128 v[206:209], v143 offset:52224
	ds_read_b128 v[210:213], v143 offset:53248
	ds_read_b128 v[214:217], v143 offset:54272
	ds_read_b128 v[218:221], v143 offset:55296
	ds_read_b128 v[222:225], v143 offset:56320
	global_load_lds_dwordx4 v[152:153], off
	v_lshl_add_u64 v[152:153], v[226:227], 0, s[52:53]
	s_add_i32 m0, s22, 0x2000
	s_add_i32 s22, s76, s25
	global_load_lds_dwordx4 v[152:153], off
	v_lshl_add_u64 v[152:153], v[228:229], 0, s[52:53]
	s_mov_b32 m0, s22
	s_nop 0
	global_load_lds_dwordx4 v[152:153], off
	v_lshl_add_u64 v[152:153], v[234:235], 0, s[52:53]
	s_add_i32 m0, s22, 0x2000
	s_nop 0
	global_load_lds_dwordx4 v[152:153], off
	v_lshl_add_u64 v[152:153], v[236:237], 0, s[52:53]
	s_mov_b32 m0, s57
	s_nop 0
	global_load_lds_dwordx4 v[152:153], off
	v_lshl_add_u64 v[152:153], v[238:239], 0, s[52:53]
	s_mov_b32 m0, s64
	s_nop 0
	global_load_lds_dwordx4 v[152:153], off
	s_waitcnt vmcnt(8)
	s_waitcnt lgkmcnt(0)
	s_barrier
	s_setprio 1
	v_mfma_f32_16x16x32_bf16 v[60:63], v[136:139], v[178:181], v[60:63]
	v_mfma_f32_16x16x32_bf16 v[56:59], v[148:151], v[178:181], v[56:59]
	v_mfma_f32_16x16x32_bf16 v[44:47], v[136:139], v[202:205], v[44:47]
	v_mfma_f32_16x16x32_bf16 v[40:43], v[148:151], v[202:205], v[40:43]
	v_mfma_f32_16x16x32_bf16 v[28:31], v[136:139], v[210:213], v[28:31]
	v_mfma_f32_16x16x32_bf16 v[24:27], v[148:151], v[210:213], v[24:27]
	v_mfma_f32_16x16x32_bf16 v[12:15], v[136:139], v[218:221], v[12:15]
	v_mfma_f32_16x16x32_bf16 v[8:11], v[148:151], v[218:221], v[8:11]
	v_mfma_f32_16x16x32_bf16 v[60:63], v[144:147], v[198:201], v[60:63]
	v_mfma_f32_16x16x32_bf16 v[56:59], v[158:161], v[198:201], v[56:59]
	v_mfma_f32_16x16x32_bf16 v[44:47], v[144:147], v[206:209], v[44:47]
	v_mfma_f32_16x16x32_bf16 v[40:43], v[158:161], v[206:209], v[40:43]
	v_mfma_f32_16x16x32_bf16 v[28:31], v[144:147], v[214:217], v[28:31]
	v_mfma_f32_16x16x32_bf16 v[24:27], v[158:161], v[214:217], v[24:27]
	v_mfma_f32_16x16x32_bf16 v[12:15], v[144:147], v[222:225], v[12:15]
	v_mfma_f32_16x16x32_bf16 v[8:11], v[158:161], v[222:225], v[8:11]
	v_mfma_f32_16x16x32_bf16 v[52:55], v[162:165], v[178:181], v[52:55]
	v_mfma_f32_16x16x32_bf16 v[48:51], v[170:173], v[178:181], v[48:51]
	v_mfma_f32_16x16x32_bf16 v[36:39], v[162:165], v[202:205], v[36:39]
	v_mfma_f32_16x16x32_bf16 v[32:35], v[170:173], v[202:205], v[32:35]
	v_mfma_f32_16x16x32_bf16 v[20:23], v[162:165], v[210:213], v[20:23]
	v_mfma_f32_16x16x32_bf16 v[16:19], v[170:173], v[210:213], v[16:19]
	v_mfma_f32_16x16x32_bf16 v[4:7], v[162:165], v[218:221], v[4:7]
	v_mfma_f32_16x16x32_bf16 v[0:3], v[170:173], v[218:221], v[0:3]
	v_mfma_f32_16x16x32_bf16 v[52:55], v[166:169], v[198:201], v[52:55]
	v_mfma_f32_16x16x32_bf16 v[48:51], v[174:177], v[198:201], v[48:51]
	v_mfma_f32_16x16x32_bf16 v[36:39], v[166:169], v[206:209], v[36:39]
	v_mfma_f32_16x16x32_bf16 v[32:35], v[174:177], v[206:209], v[32:35]
	v_mfma_f32_16x16x32_bf16 v[20:23], v[166:169], v[214:217], v[20:23]
	v_mfma_f32_16x16x32_bf16 v[16:19], v[174:177], v[214:217], v[16:19]
	v_mfma_f32_16x16x32_bf16 v[4:7], v[166:169], v[222:225], v[4:7]
	v_mfma_f32_16x16x32_bf16 v[0:3], v[174:177], v[222:225], v[0:3]
	s_setprio 0
	s_barrier
	s_add_u32 s20, s20, 0x100
	s_addc_u32 s21, s21, 0
	s_add_u32 s79, s79, 0x100
	s_addc_u32 s80, s80, 0
	s_cmp_ge_i32 s81, s56
	s_mov_b32 s22, s81
	s_cbranch_scc0 .LBB0_72

; #define PG8_STAGE(bufoff, gbase, voff) do { _Pragma("unroll") for (int _i = 0; _i < 2; ++_i) \
;         __builtin_amdgcn_global_load_lds((const unsigned*)((const char*)(gbase) + (voff)[_i]), (PG8_LAS unsigned*)(lds + (bufoff) + ldsw + _i * 8192), 16, 0, 0); } while (0)
; #define PG8_LDA(dst, b, h) do { _Pragma("unroll") for (int m = 0; m < 4; ++m) _Pragma("unroll") for (int k = 0; k < 2; ++k) dst[m][k] = *(const PG8_LAS bf16x8*)(lds + PG8_SA(b, h) + aoff + m * 2048 + k * 1024); } while (0)
; #define PG8_LDB(dst, b, h) do { _Pragma("unroll") for (int n = 0; n < 2; ++n) _Pragma("unroll") for (int k = 0; k < 2; ++k) dst[n][k] = *(const PG8_LAS bf16x8*)(lds + PG8_SB(b, h) + boff + n * 2048 + k * 1024); } while (0)
; #define PG8_MMA(ai, bj, At, Bt) do { __builtin_amdgcn_s_setprio(1); _Pragma("unroll") for (int m = 0; m < 4; ++m) _Pragma("unroll") for (int n = 0; n < 2; ++n) _Pragma("unroll") for (int k = 0; k < 2; ++k) \
;         acc[ai][bj][m][n] = __builtin_amdgcn_mfma_f32_16x16x32_bf16(Bt[n][k], At[m][k], acc[ai][bj][m][n], 0, 0, 0); __builtin_amdgcn_s_setprio(0); } while (0)
; #define PG8_WAIT_V(n) asm volatile("s_waitcnt vmcnt(" #n ")" ::: "memory")
; #define PG8_WAIT_L(n) asm volatile("s_waitcnt lgkmcnt(" #n ")" ::: "memory")
; #define PG8_BAR __builtin_amdgcn_s_barrier()
; #define PG8_SCHED __builtin_amdgcn_sched_barrier(0)
; template <class Epi, class Sched, bool ALIGN_EPI = false, bool SP2 = false>
; __device__ __forceinline__ void gemm_phase(PG8_LAS unsigned char* lds, const Gemm g, const Sched& S, const Epi& E) {
;     ...
;         for (int t = 0; t < nt; t += 2) {
;             const bool last = (t == nt - 2);
;             const char* a1 = cA + (size_t)(t + 1) * kstep;
;             const char* a2 = last ? nA : cA + (size_t)(t + 2) * kstep; const char* b2 = last ? nB : cB + (size_t)(t + 2) * kstep;
;             const char* a3 = a2 + kstep; const char* b3 = b2 + kstep;
;             if (last && has_next) S.a_ready(nxt);
;             if constexpr (SP2) {
;             PG8_LDB(B0, 0, 0); PG8_LDB(B1, 0, 1); PG8_SCHED; PG8_LDA(At, 0, 0); PG8_STAGE(PG8_SA(1, 1), a1 + hstep, voffA);
;             PG8_WAIT_V(8); PG8_WAIT_L(0); PG8_BAR; PG8_MMA(0, 0, At, B0); PG8_MMA(0, 1, At, B1); PG8_BAR; PG8_SCHED;
;             PG8_LDA(At, 0, 1); PG8_STAGE(PG8_SB(0, 0), b2, voffB); PG8_STAGE(PG8_SB(0, 1), b2 + hstep, voffB); PG8_STAGE(PG8_SA(0, 0), a2, voffA);
.LBB0_96:
	s_add_i32 s29, s24, 2
	s_add_u32 s56, s0, 0x80
	s_addc_u32 s25, s1, 0
	s_add_i32 s59, 0, 0x10000
	s_cmp_eq_u32 s83, s24
	s_cselect_b32 s25, s7, s25
	s_cselect_b32 s24, s6, s56
	v_add_u32_e32 v152, s59, v145
	s_cselect_b32 s57, s23, s28
	s_cselect_b32 s56, s22, s17
	s_add_i32 s74, 0, 0x14000
	ds_read_b128 v[140:143], v152
	ds_read_b128 v[148:151], v152 offset:1024
	ds_read_b128 v[158:161], v152 offset:2048
	ds_read_b128 v[162:165], v152 offset:3072
	v_add_u32_e32 v152, s74, v145
	ds_read_b128 v[166:169], v152
	ds_read_b128 v[170:173], v152 offset:1024
	ds_read_b128 v[174:177], v152 offset:2048
	ds_read_b128 v[178:181], v152 offset:3072
	v_lshl_add_u64 v[152:153], s[0:1], 0, v[136:137]
	s_add_i32 m0, s70, 0xc000
	ds_read_b128 v[198:201], v147
	ds_read_b128 v[202:205], v147 offset:1024
	ds_read_b128 v[206:209], v147 offset:2048
	ds_read_b128 v[210:213], v147 offset:3072
	ds_read_b128 v[214:217], v147 offset:4096
	ds_read_b128 v[218:221], v147 offset:5120
	ds_read_b128 v[222:225], v147 offset:6144
	ds_read_b128 v[226:229], v147 offset:7168
	global_load_lds_dwordx4 v[152:153], off
	v_lshl_add_u64 v[152:153], s[0:1], 0, v[138:139]
	s_add_i32 m0, s70, 0xe000
	s_nop 0
	global_load_lds_dwordx4 v[152:153], off
	s_waitcnt vmcnt(8)
	s_waitcnt lgkmcnt(0)
	s_barrier
	s_setprio 1
	v_mfma_f32_16x16x32_bf16 v[122:125], v[140:143], v[198:201], v[122:125]
	v_mfma_f32_16x16x32_bf16 v[114:117], v[158:161], v[198:201], v[114:117]
	v_mfma_f32_16x16x32_bf16 v[104:107], v[140:143], v[206:209], v[104:107]
	v_mfma_f32_16x16x32_bf16 v[96:99], v[158:161], v[206:209], v[96:99]
	v_mfma_f32_16x16x32_bf16 v[88:91], v[140:143], v[214:217], v[88:91]
	v_mfma_f32_16x16x32_bf16 v[80:83], v[158:161], v[214:217], v[80:83]
	v_mfma_f32_16x16x32_bf16 v[72:75], v[140:143], v[222:225], v[72:75]
	v_mfma_f32_16x16x32_bf16 v[64:67], v[158:161], v[222:225], v[64:67]
	v_mfma_f32_16x16x32_bf16 v[122:125], v[148:151], v[202:205], v[122:125]
	v_mfma_f32_16x16x32_bf16 v[114:117], v[162:165], v[202:205], v[114:117]
	v_mfma_f32_16x16x32_bf16 v[104:107], v[148:151], v[210:213], v[104:107]
	v_mfma_f32_16x16x32_bf16 v[96:99], v[162:165], v[210:213], v[96:99]
	v_mfma_f32_16x16x32_bf16 v[88:91], v[148:151], v[218:221], v[88:91]
	v_mfma_f32_16x16x32_bf16 v[80:83], v[162:165], v[218:221], v[80:83]
	v_mfma_f32_16x16x32_bf16 v[72:75], v[148:151], v[226:229], v[72:75]
	v_mfma_f32_16x16x32_bf16 v[64:67], v[162:165], v[226:229], v[64:67]
	v_mfma_f32_16x16x32_bf16 v[126:129], v[166:169], v[198:201], v[126:129]
	v_mfma_f32_16x16x32_bf16 v[118:121], v[174:177], v[198:201], v[118:121]
	v_mfma_f32_16x16x32_bf16 v[108:111], v[166:169], v[206:209], v[108:111]
	v_mfma_f32_16x16x32_bf16 v[100:103], v[174:177], v[206:209], v[100:103]
	v_mfma_f32_16x16x32_bf16 v[92:95], v[166:169], v[214:217], v[92:95]
	v_mfma_f32_16x16x32_bf16 v[84:87], v[174:177], v[214:217], v[84:87]
	v_mfma_f32_16x16x32_bf16 v[76:79], v[166:169], v[222:225], v[76:79]
	v_mfma_f32_16x16x32_bf16 v[68:71], v[174:177], v[222:225], v[68:71]
	v_mfma_f32_16x16x32_bf16 v[126:129], v[170:173], v[202:205], v[126:129]
	v_mfma_f32_16x16x32_bf16 v[118:121], v[178:181], v[202:205], v[118:121]
	v_mfma_f32_16x16x32_bf16 v[108:111], v[170:173], v[210:213], v[108:111]
	v_mfma_f32_16x16x32_bf16 v[100:103], v[178:181], v[210:213], v[100:103]
	v_mfma_f32_16x16x32_bf16 v[92:95], v[170:173], v[218:221], v[92:95]
	v_mfma_f32_16x16x32_bf16 v[84:87], v[178:181], v[218:221], v[84:87]
	v_mfma_f32_16x16x32_bf16 v[76:79], v[170:173], v[226:229], v[76:79]
	v_mfma_f32_16x16x32_bf16 v[68:71], v[178:181], v[226:229], v[68:71]
	s_setprio 0
	s_barrier
	s_add_i32 s59, s59, s49
	v_lshl_add_u64 v[152:153], s[56:57], 0, v[112:113]
	s_mov_b32 m0, s59
	ds_read_b128 v[198:201], v147 offset:16384
	ds_read_b128 v[202:205], v147 offset:17408
	ds_read_b128 v[206:209], v147 offset:18432
	ds_read_b128 v[210:213], v147 offset:19456
	ds_read_b128 v[214:217], v147 offset:20480
	ds_read_b128 v[218:221], v147 offset:21504
	ds_read_b128 v[222:225], v147 offset:22528
	ds_read_b128 v[226:229], v147 offset:23552
	global_load_lds_dwordx4 v[152:153], off
	s_add_i32 m0, s59, 0x2000
	v_lshl_add_u64 v[234:235], s[56:57], 0, v[130:131]
	s_add_u32 s56, s56, s12
	s_addc_u32 s57, s57, s13
	s_add_i32 s59, s74, s49
	global_load_lds_dwordx4 v[234:235], off
	v_lshl_add_u64 v[236:237], s[56:57], 0, v[112:113]
	s_mov_b32 m0, s59
	v_lshl_add_u64 v[238:239], s[56:57], 0, v[130:131]
	global_load_lds_dwordx4 v[236:237], off
	s_add_i32 m0, s59, 0x2000
	v_lshl_add_u64 v[240:241], s[24:25], 0, v[134:135]
	global_load_lds_dwordx4 v[238:239], off
	s_mov_b32 m0, s70
	v_lshl_add_u64 v[242:243], s[24:25], 0, v[132:133]
	global_load_lds_dwordx4 v[240:241], off
	s_mov_b32 m0, s71
	s_nop 0
	global_load_lds_dwordx4 v[242:243], off
	s_waitcnt vmcnt(8)
	s_waitcnt lgkmcnt(0)
	s_barrier
; #define PG8_STAGE(bufoff, gbase, voff) do { _Pragma("unroll") for (int _i = 0; _i < 2; ++_i) \
;         __builtin_amdgcn_global_load_lds((const unsigned*)((const char*)(gbase) + (voff)[_i]), (PG8_LAS unsigned*)(lds + (bufoff) + ldsw + _i * 8192), 16, 0, 0); } while (0)
; #define PG8_LDA(dst, b, h) do { _Pragma("unroll") for (int m = 0; m < 4; ++m) _Pragma("unroll") for (int k = 0; k < 2; ++k) dst[m][k] = *(const PG8_LAS bf16x8*)(lds + PG8_SA(b, h) + aoff + m * 2048 + k * 1024); } while (0)
; #define PG8_LDB(dst, b, h) do { _Pragma("unroll") for (int n = 0; n < 2; ++n) _Pragma("unroll") for (int k = 0; k < 2; ++k) dst[n][k] = *(const PG8_LAS bf16x8*)(lds + PG8_SB(b, h) + boff + n * 2048 + k * 1024); } while (0)
; #define PG8_MMA(ai, bj, At, Bt) do { __builtin_amdgcn_s_setprio(1); _Pragma("unroll") for (int m = 0; m < 4; ++m) _Pragma("unroll") for (int n = 0; n < 2; ++n) _Pragma("unroll") for (int k = 0; k < 2; ++k) \
;         acc[ai][bj][m][n] = __builtin_amdgcn_mfma_f32_16x16x32_bf16(Bt[n][k], At[m][k], acc[ai][bj][m][n], 0, 0, 0); __builtin_amdgcn_s_setprio(0); } while (0)
; #define PG8_WAIT_V(n) asm volatile("s_waitcnt vmcnt(" #n ")" ::: "memory")
; #define PG8_WAIT_L(n) asm volatile("s_waitcnt lgkmcnt(" #n ")" ::: "memory")
; #define PG8_BAR __builtin_amdgcn_s_barrier()
; #define PG8_SCHED __builtin_amdgcn_sched_barrier(0)
; template <class Epi, class Sched, bool ALIGN_EPI = false, bool SP2 = false>
; __device__ __forceinline__ void gemm_phase(PG8_LAS unsigned char* lds, const Gemm g, const Sched& S, const Epi& E) {
;     ...
;             PG8_WAIT_V(8); PG8_WAIT_L(0); PG8_BAR; PG8_MMA(1, 0, At, B0); PG8_MMA(1, 1, At, B1); PG8_BAR; PG8_SCHED;
;             PG8_LDB(B0, 1, 0); PG8_LDB(B1, 1, 1); PG8_SCHED; PG8_LDA(At, 1, 0); PG8_STAGE(PG8_SA(0, 1), a2 + hstep, voffA);
;             PG8_WAIT_V(8); PG8_WAIT_L(0); PG8_BAR; PG8_MMA(0, 0, At, B0); PG8_MMA(0, 1, At, B1); PG8_BAR; PG8_SCHED;
	s_setprio 1
	v_mfma_f32_16x16x32_bf16 v[56:59], v[140:143], v[198:201], v[56:59]
	v_mfma_f32_16x16x32_bf16 v[48:51], v[158:161], v[198:201], v[48:51]
	v_mfma_f32_16x16x32_bf16 v[40:43], v[140:143], v[206:209], v[40:43]
	v_mfma_f32_16x16x32_bf16 v[32:35], v[158:161], v[206:209], v[32:35]
	v_mfma_f32_16x16x32_bf16 v[24:27], v[140:143], v[214:217], v[24:27]
	v_mfma_f32_16x16x32_bf16 v[16:19], v[158:161], v[214:217], v[16:19]
	v_mfma_f32_16x16x32_bf16 v[8:11], v[140:143], v[222:225], v[8:11]
	v_mfma_f32_16x16x32_bf16 v[4:7], v[158:161], v[222:225], v[4:7]
	v_mfma_f32_16x16x32_bf16 v[56:59], v[148:151], v[202:205], v[56:59]
	v_mfma_f32_16x16x32_bf16 v[48:51], v[162:165], v[202:205], v[48:51]
	v_mfma_f32_16x16x32_bf16 v[40:43], v[148:151], v[210:213], v[40:43]
	v_mfma_f32_16x16x32_bf16 v[32:35], v[162:165], v[210:213], v[32:35]
	v_mfma_f32_16x16x32_bf16 v[24:27], v[148:151], v[218:221], v[24:27]
	v_mfma_f32_16x16x32_bf16 v[16:19], v[162:165], v[218:221], v[16:19]
	v_mfma_f32_16x16x32_bf16 v[8:11], v[148:151], v[226:229], v[8:11]
	v_mfma_f32_16x16x32_bf16 v[4:7], v[162:165], v[226:229], v[4:7]
	v_mfma_f32_16x16x32_bf16 v[60:63], v[166:169], v[198:201], v[60:63]
	v_mfma_f32_16x16x32_bf16 v[52:55], v[174:177], v[198:201], v[52:55]
	v_mfma_f32_16x16x32_bf16 v[44:47], v[166:169], v[206:209], v[44:47]
	v_mfma_f32_16x16x32_bf16 v[36:39], v[174:177], v[206:209], v[36:39]
	v_mfma_f32_16x16x32_bf16 v[28:31], v[166:169], v[214:217], v[28:31]
	v_mfma_f32_16x16x32_bf16 v[20:23], v[174:177], v[214:217], v[20:23]
	v_mfma_f32_16x16x32_bf16 v[12:15], v[166:169], v[222:225], v[12:15]
	v_mfma_f32_16x16x32_bf16 v[0:3], v[174:177], v[222:225], v[0:3]
	v_mfma_f32_16x16x32_bf16 v[60:63], v[170:173], v[202:205], v[60:63]
	v_mfma_f32_16x16x32_bf16 v[52:55], v[178:181], v[202:205], v[52:55]
	v_mfma_f32_16x16x32_bf16 v[44:47], v[170:173], v[210:213], v[44:47]
	v_mfma_f32_16x16x32_bf16 v[36:39], v[178:181], v[210:213], v[36:39]
	v_mfma_f32_16x16x32_bf16 v[28:31], v[170:173], v[218:221], v[28:31]
	v_mfma_f32_16x16x32_bf16 v[20:23], v[178:181], v[218:221], v[20:23]
	v_mfma_f32_16x16x32_bf16 v[12:15], v[170:173], v[226:229], v[12:15]
	v_mfma_f32_16x16x32_bf16 v[0:3], v[178:181], v[226:229], v[0:3]
	s_setprio 0
	s_barrier
	s_add_i32 s56, 0, 0x18000
	s_add_i32 s57, 0, 0x1c000
	v_add_u32_e32 v162, s56, v145
	v_add_u32_e32 v178, s57, v145
	ds_read_b128 v[140:143], v162
	ds_read_b128 v[148:151], v162 offset:1024
	ds_read_b128 v[158:161], v162 offset:2048
	ds_read_b128 v[162:165], v162 offset:3072
	ds_read_b128 v[166:169], v178
	ds_read_b128 v[170:173], v178 offset:1024
	ds_read_b128 v[174:177], v178 offset:2048
	ds_read_b128 v[178:181], v178 offset:3072
	s_add_u32 s24, s24, s12
	s_addc_u32 s25, s25, s13
	s_mov_b32 m0, s77
	v_lshl_add_u64 v[244:245], s[24:25], 0, v[134:135]
	ds_read_b128 v[198:201], v147 offset:32768
	ds_read_b128 v[202:205], v147 offset:33792
	ds_read_b128 v[206:209], v147 offset:34816
	ds_read_b128 v[210:213], v147 offset:35840
	ds_read_b128 v[214:217], v147 offset:36864
	ds_read_b128 v[218:221], v147 offset:37888
	ds_read_b128 v[222:225], v147 offset:38912
	ds_read_b128 v[226:229], v147 offset:39936
	global_load_lds_dwordx4 v[244:245], off
	v_lshl_add_u64 v[244:245], s[24:25], 0, v[132:133]
	s_mov_b32 m0, s79
	s_nop 0
	global_load_lds_dwordx4 v[244:245], off
	s_waitcnt vmcnt(8)
	s_waitcnt lgkmcnt(0)
	s_barrier
	s_setprio 1
	v_mfma_f32_16x16x32_bf16 v[122:125], v[140:143], v[198:201], v[122:125]
	v_mfma_f32_16x16x32_bf16 v[114:117], v[158:161], v[198:201], v[114:117]
	v_mfma_f32_16x16x32_bf16 v[104:107], v[140:143], v[206:209], v[104:107]
	v_mfma_f32_16x16x32_bf16 v[96:99], v[158:161], v[206:209], v[96:99]
	v_mfma_f32_16x16x32_bf16 v[88:91], v[140:143], v[214:217], v[88:91]
	v_mfma_f32_16x16x32_bf16 v[80:83], v[158:161], v[214:217], v[80:83]
	v_mfma_f32_16x16x32_bf16 v[72:75], v[140:143], v[222:225], v[72:75]
	v_mfma_f32_16x16x32_bf16 v[64:67], v[158:161], v[222:225], v[64:67]
	v_mfma_f32_16x16x32_bf16 v[122:125], v[148:151], v[202:205], v[122:125]
	v_mfma_f32_16x16x32_bf16 v[114:117], v[162:165], v[202:205], v[114:117]
	v_mfma_f32_16x16x32_bf16 v[104:107], v[148:151], v[210:213], v[104:107]
	v_mfma_f32_16x16x32_bf16 v[96:99], v[162:165], v[210:213], v[96:99]
	v_mfma_f32_16x16x32_bf16 v[88:91], v[148:151], v[218:221], v[88:91]
	v_mfma_f32_16x16x32_bf16 v[80:83], v[162:165], v[218:221], v[80:83]
	v_mfma_f32_16x16x32_bf16 v[72:75], v[148:151], v[226:229], v[72:75]
	v_mfma_f32_16x16x32_bf16 v[64:67], v[162:165], v[226:229], v[64:67]
	v_mfma_f32_16x16x32_bf16 v[126:129], v[166:169], v[198:201], v[126:129]
	v_mfma_f32_16x16x32_bf16 v[118:121], v[174:177], v[198:201], v[118:121]
	v_mfma_f32_16x16x32_bf16 v[108:111], v[166:169], v[206:209], v[108:111]
	v_mfma_f32_16x16x32_bf16 v[100:103], v[174:177], v[206:209], v[100:103]
	v_mfma_f32_16x16x32_bf16 v[92:95], v[166:169], v[214:217], v[92:95]
	v_mfma_f32_16x16x32_bf16 v[84:87], v[174:177], v[214:217], v[84:87]
	v_mfma_f32_16x16x32_bf16 v[76:79], v[166:169], v[222:225], v[76:79]
	v_mfma_f32_16x16x32_bf16 v[68:71], v[174:177], v[222:225], v[68:71]
	v_mfma_f32_16x16x32_bf16 v[126:129], v[170:173], v[202:205], v[126:129]
	v_mfma_f32_16x16x32_bf16 v[118:121], v[178:181], v[202:205], v[118:121]
	v_mfma_f32_16x16x32_bf16 v[108:111], v[170:173], v[210:213], v[108:111]
	v_mfma_f32_16x16x32_bf16 v[100:103], v[178:181], v[210:213], v[100:103]
	v_mfma_f32_16x16x32_bf16 v[92:95], v[170:173], v[218:221], v[92:95]
	v_mfma_f32_16x16x32_bf16 v[84:87], v[178:181], v[218:221], v[84:87]
	v_mfma_f32_16x16x32_bf16 v[76:79], v[170:173], v[226:229], v[76:79]
	v_mfma_f32_16x16x32_bf16 v[68:71], v[178:181], v[226:229], v[68:71]
	s_setprio 0
	s_barrier
; #define PG8_STAGE(bufoff, gbase, voff) do { _Pragma("unroll") for (int _i = 0; _i < 2; ++_i) \
;         __builtin_amdgcn_global_load_lds((const unsigned*)((const char*)(gbase) + (voff)[_i]), (PG8_LAS unsigned*)(lds + (bufoff) + ldsw + _i * 8192), 16, 0, 0); } while (0)
; #define PG8_LDA(dst, b, h) do { _Pragma("unroll") for (int m = 0; m < 4; ++m) _Pragma("unroll") for (int k = 0; k < 2; ++k) dst[m][k] = *(const PG8_LAS bf16x8*)(lds + PG8_SA(b, h) + aoff + m * 2048 + k * 1024); } while (0)
; #define PG8_MMA(ai, bj, At, Bt) do { __builtin_amdgcn_s_setprio(1); _Pragma("unroll") for (int m = 0; m < 4; ++m) _Pragma("unroll") for (int n = 0; n < 2; ++n) _Pragma("unroll") for (int k = 0; k < 2; ++k) \
;         acc[ai][bj][m][n] = __builtin_amdgcn_mfma_f32_16x16x32_bf16(Bt[n][k], At[m][k], acc[ai][bj][m][n], 0, 0, 0); __builtin_amdgcn_s_setprio(0); } while (0)
; #define PG8_WAIT_V(n) asm volatile("s_waitcnt vmcnt(" #n ")" ::: "memory")
; #define PG8_WAIT_L(n) asm volatile("s_waitcnt lgkmcnt(" #n ")" ::: "memory")
; #define PG8_BAR __builtin_amdgcn_s_barrier()
; #define PG8_SCHED __builtin_amdgcn_sched_barrier(0)
; template <class Epi, class Sched, bool ALIGN_EPI = false, bool SP2 = false>
; __device__ __forceinline__ void gemm_phase(PG8_LAS unsigned char* lds, const Gemm g, const Sched& S, const Epi& E) {
;     ...
;             PG8_LDA(At, 1, 1); PG8_STAGE(PG8_SB(1, 0), b3, voffB); PG8_STAGE(PG8_SB(1, 1), b3 + hstep, voffB); PG8_STAGE(PG8_SA(1, 0), a3, voffA);
;             PG8_WAIT_V(8); PG8_WAIT_L(0); PG8_BAR; PG8_MMA(1, 0, At, B0); PG8_MMA(1, 1, At, B1); PG8_BAR; PG8_SCHED;
	s_add_i32 s24, s56, s49
	v_lshl_add_u64 v[152:153], v[152:153], 0, s[52:53]
	s_mov_b32 m0, s24
	ds_read_b128 v[198:201], v147 offset:49152
	ds_read_b128 v[202:205], v147 offset:50176
	ds_read_b128 v[206:209], v147 offset:51200
	ds_read_b128 v[210:213], v147 offset:52224
	ds_read_b128 v[214:217], v147 offset:53248
	ds_read_b128 v[218:221], v147 offset:54272
	ds_read_b128 v[222:225], v147 offset:55296
	ds_read_b128 v[226:229], v147 offset:56320
	global_load_lds_dwordx4 v[152:153], off
	v_lshl_add_u64 v[152:153], v[234:235], 0, s[52:53]
	s_add_i32 m0, s24, 0x2000
	s_add_i32 s24, s57, s49
	global_load_lds_dwordx4 v[152:153], off
	v_lshl_add_u64 v[152:153], v[236:237], 0, s[52:53]
	s_mov_b32 m0, s24
	s_nop 0
	global_load_lds_dwordx4 v[152:153], off
	v_lshl_add_u64 v[152:153], v[238:239], 0, s[52:53]
	s_add_i32 m0, s24, 0x2000
	s_nop 0
	global_load_lds_dwordx4 v[152:153], off
	v_lshl_add_u64 v[152:153], v[240:241], 0, s[52:53]
	s_mov_b32 m0, s81
	s_nop 0
	global_load_lds_dwordx4 v[152:153], off
	v_lshl_add_u64 v[152:153], v[242:243], 0, s[52:53]
	s_mov_b32 m0, s82
	s_nop 0
	global_load_lds_dwordx4 v[152:153], off
	s_waitcnt vmcnt(8)
	s_waitcnt lgkmcnt(0)
	s_barrier
	s_setprio 1
	v_mfma_f32_16x16x32_bf16 v[56:59], v[140:143], v[198:201], v[56:59]
	v_mfma_f32_16x16x32_bf16 v[48:51], v[158:161], v[198:201], v[48:51]
	v_mfma_f32_16x16x32_bf16 v[40:43], v[140:143], v[206:209], v[40:43]
	v_mfma_f32_16x16x32_bf16 v[32:35], v[158:161], v[206:209], v[32:35]
	v_mfma_f32_16x16x32_bf16 v[24:27], v[140:143], v[214:217], v[24:27]
	v_mfma_f32_16x16x32_bf16 v[16:19], v[158:161], v[214:217], v[16:19]
	v_mfma_f32_16x16x32_bf16 v[8:11], v[140:143], v[222:225], v[8:11]
	v_mfma_f32_16x16x32_bf16 v[4:7], v[158:161], v[222:225], v[4:7]
	v_mfma_f32_16x16x32_bf16 v[56:59], v[148:151], v[202:205], v[56:59]
	v_mfma_f32_16x16x32_bf16 v[48:51], v[162:165], v[202:205], v[48:51]
	v_mfma_f32_16x16x32_bf16 v[40:43], v[148:151], v[210:213], v[40:43]
	v_mfma_f32_16x16x32_bf16 v[32:35], v[162:165], v[210:213], v[32:35]
	v_mfma_f32_16x16x32_bf16 v[24:27], v[148:151], v[218:221], v[24:27]
	v_mfma_f32_16x16x32_bf16 v[16:19], v[162:165], v[218:221], v[16:19]
	v_mfma_f32_16x16x32_bf16 v[8:11], v[148:151], v[226:229], v[8:11]
	v_mfma_f32_16x16x32_bf16 v[4:7], v[162:165], v[226:229], v[4:7]
	v_mfma_f32_16x16x32_bf16 v[60:63], v[166:169], v[198:201], v[60:63]
	v_mfma_f32_16x16x32_bf16 v[52:55], v[174:177], v[198:201], v[52:55]
	v_mfma_f32_16x16x32_bf16 v[44:47], v[166:169], v[206:209], v[44:47]
	v_mfma_f32_16x16x32_bf16 v[36:39], v[174:177], v[206:209], v[36:39]
	v_mfma_f32_16x16x32_bf16 v[28:31], v[166:169], v[214:217], v[28:31]
	v_mfma_f32_16x16x32_bf16 v[20:23], v[174:177], v[214:217], v[20:23]
	v_mfma_f32_16x16x32_bf16 v[12:15], v[166:169], v[222:225], v[12:15]
	v_mfma_f32_16x16x32_bf16 v[0:3], v[174:177], v[222:225], v[0:3]
	v_mfma_f32_16x16x32_bf16 v[60:63], v[170:173], v[202:205], v[60:63]
	v_mfma_f32_16x16x32_bf16 v[52:55], v[178:181], v[202:205], v[52:55]
	v_mfma_f32_16x16x32_bf16 v[44:47], v[170:173], v[210:213], v[44:47]
	v_mfma_f32_16x16x32_bf16 v[36:39], v[178:181], v[210:213], v[36:39]
	v_mfma_f32_16x16x32_bf16 v[28:31], v[170:173], v[218:221], v[28:31]
	v_mfma_f32_16x16x32_bf16 v[20:23], v[178:181], v[218:221], v[20:23]
	v_mfma_f32_16x16x32_bf16 v[12:15], v[170:173], v[226:229], v[12:15]
	v_mfma_f32_16x16x32_bf16 v[0:3], v[178:181], v[226:229], v[0:3]
	s_setprio 0
	s_barrier
	s_add_u32 s0, s0, 0x100
	s_addc_u32 s1, s1, 0
	s_add_u32 s17, s17, 0x100
	s_addc_u32 s28, s28, 0
	s_cmp_ge_i32 s29, s80
	s_mov_b32 s24, s29
	s_cbranch_scc0 .LBB0_96

; #define PG8_STAGE(bufoff, gbase, voff) do { _Pragma("unroll") for (int _i = 0; _i < 2; ++_i) \
;         __builtin_amdgcn_global_load_lds((const unsigned*)((const char*)(gbase) + (voff)[_i]), (PG8_LAS unsigned*)(lds + (bufoff) + ldsw + _i * 8192), 16, 0, 0); } while (0)
; #define PG8_LDA(dst, b, h) do { _Pragma("unroll") for (int m = 0; m < 4; ++m) _Pragma("unroll") for (int k = 0; k < 2; ++k) dst[m][k] = *(const PG8_LAS bf16x8*)(lds + PG8_SA(b, h) + aoff + m * 2048 + k * 1024); } while (0)
; #define PG8_LDB(dst, b, h) do { _Pragma("unroll") for (int n = 0; n < 2; ++n) _Pragma("unroll") for (int k = 0; k < 2; ++k) dst[n][k] = *(const PG8_LAS bf16x8*)(lds + PG8_SB(b, h) + boff + n * 2048 + k * 1024); } while (0)
; #define PG8_MMA(ai, bj, At, Bt) do { __builtin_amdgcn_s_setprio(1); _Pragma("unroll") for (int m = 0; m < 4; ++m) _Pragma("unroll") for (int n = 0; n < 2; ++n) _Pragma("unroll") for (int k = 0; k < 2; ++k) \
;         acc[ai][bj][m][n] = __builtin_amdgcn_mfma_f32_16x16x32_bf16(Bt[n][k], At[m][k], acc[ai][bj][m][n], 0, 0, 0); __builtin_amdgcn_s_setprio(0); } while (0)
; #define PG8_WAIT_V(n) asm volatile("s_waitcnt vmcnt(" #n ")" ::: "memory")
; #define PG8_WAIT_L(n) asm volatile("s_waitcnt lgkmcnt(" #n ")" ::: "memory")
; #define PG8_BAR __builtin_amdgcn_s_barrier()
; #define PG8_SCHED __builtin_amdgcn_sched_barrier(0)
; template <class Epi, class Sched, bool ALIGN_EPI = false, bool SP2 = false>
; __device__ __forceinline__ void gemm_phase(PG8_LAS unsigned char* lds, const Gemm g, const Sched& S, const Epi& E) {
;     ...
;         for (int t = 0; t < nt; t += 2) {
;             const bool last = (t == nt - 2);
;             const char* a1 = cA + (size_t)(t + 1) * kstep;
;             const char* a2 = last ? nA : cA + (size_t)(t + 2) * kstep; const char* b2 = last ? nB : cB + (size_t)(t + 2) * kstep;
;             const char* a3 = a2 + kstep; const char* b3 = b2 + kstep;
;             if (last && has_next) S.a_ready(nxt);
;             if constexpr (SP2) {
;             PG8_LDB(B0, 0, 0); PG8_LDB(B1, 0, 1); PG8_SCHED; PG8_LDA(At, 0, 0); PG8_STAGE(PG8_SA(1, 1), a1 + hstep, voffA);
;             PG8_WAIT_V(8); PG8_WAIT_L(0); PG8_BAR; PG8_MMA(0, 0, At, B0); PG8_MMA(0, 1, At, B1); PG8_BAR; PG8_SCHED;
;             PG8_LDA(At, 0, 1); PG8_STAGE(PG8_SB(0, 0), b2, voffB); PG8_STAGE(PG8_SB(0, 1), b2 + hstep, voffB); PG8_STAGE(PG8_SA(0, 0), a2, voffA);
.LBB0_441:
	s_add_i32 s25, s22, 2
	s_add_u32 s56, s0, 0x80
	s_addc_u32 s23, s1, 0
	s_add_i32 s74, 0, 0x10000
	s_cmp_eq_u32 s82, s22
	s_cselect_b32 s23, s7, s23
	s_cselect_b32 s22, s6, s56
	v_add_u32_e32 v112, s74, v159
	s_cselect_b32 s57, s21, s24
	s_cselect_b32 s56, s20, s15
	s_add_i32 s75, 0, 0x14000
	ds_read_b128 v[114:117], v112
	ds_read_b128 v[118:121], v112 offset:1024
	ds_read_b128 v[150:153], v112 offset:2048
	ds_read_b128 v[162:165], v112 offset:3072
	v_add_u32_e32 v112, s75, v159
	ds_read_b128 v[166:169], v112
	ds_read_b128 v[170:173], v112 offset:1024
	ds_read_b128 v[174:177], v112 offset:2048
	ds_read_b128 v[178:181], v112 offset:3072
	v_lshl_add_u64 v[234:235], s[0:1], 0, v[146:147]
	s_add_i32 m0, s64, 0xc000
	ds_read_b128 v[198:201], v161
	ds_read_b128 v[202:205], v161 offset:1024
	ds_read_b128 v[206:209], v161 offset:2048
	ds_read_b128 v[210:213], v161 offset:3072
	ds_read_b128 v[214:217], v161 offset:4096
	ds_read_b128 v[218:221], v161 offset:5120
	ds_read_b128 v[222:225], v161 offset:6144
	ds_read_b128 v[226:229], v161 offset:7168
	global_load_lds_dwordx4 v[234:235], off
	v_lshl_add_u64 v[234:235], s[0:1], 0, v[148:149]
	s_add_i32 m0, s64, 0xe000
	s_nop 0
	global_load_lds_dwordx4 v[234:235], off
	s_waitcnt vmcnt(8)
	s_waitcnt lgkmcnt(0)
	s_barrier
	s_setprio 1
	v_mfma_f32_16x16x32_bf16 v[134:137], v[114:117], v[198:201], v[134:137]
	v_mfma_f32_16x16x32_bf16 v[130:133], v[150:153], v[198:201], v[130:133]
	v_mfma_f32_16x16x32_bf16 v[126:129], v[114:117], v[206:209], v[126:129]
	v_mfma_f32_16x16x32_bf16 v[122:125], v[150:153], v[206:209], v[122:125]
	v_mfma_f32_16x16x32_bf16 v[108:111], v[114:117], v[214:217], v[108:111]
	v_mfma_f32_16x16x32_bf16 v[104:107], v[150:153], v[214:217], v[104:107]
	v_mfma_f32_16x16x32_bf16 v[100:103], v[114:117], v[222:225], v[100:103]
	v_mfma_f32_16x16x32_bf16 v[96:99], v[150:153], v[222:225], v[96:99]
	v_mfma_f32_16x16x32_bf16 v[134:137], v[118:121], v[202:205], v[134:137]
	v_mfma_f32_16x16x32_bf16 v[130:133], v[162:165], v[202:205], v[130:133]
	v_mfma_f32_16x16x32_bf16 v[126:129], v[118:121], v[210:213], v[126:129]
	v_mfma_f32_16x16x32_bf16 v[122:125], v[162:165], v[210:213], v[122:125]
	v_mfma_f32_16x16x32_bf16 v[108:111], v[118:121], v[218:221], v[108:111]
	v_mfma_f32_16x16x32_bf16 v[104:107], v[162:165], v[218:221], v[104:107]
	v_mfma_f32_16x16x32_bf16 v[100:103], v[118:121], v[226:229], v[100:103]
	v_mfma_f32_16x16x32_bf16 v[96:99], v[162:165], v[226:229], v[96:99]
	v_mfma_f32_16x16x32_bf16 v[60:63], v[166:169], v[198:201], v[60:63]
	v_mfma_f32_16x16x32_bf16 v[56:59], v[174:177], v[198:201], v[56:59]
	v_mfma_f32_16x16x32_bf16 v[52:55], v[166:169], v[206:209], v[52:55]
	v_mfma_f32_16x16x32_bf16 v[48:51], v[174:177], v[206:209], v[48:51]
	v_mfma_f32_16x16x32_bf16 v[44:47], v[166:169], v[214:217], v[44:47]
	v_mfma_f32_16x16x32_bf16 v[40:43], v[174:177], v[214:217], v[40:43]
	v_mfma_f32_16x16x32_bf16 v[36:39], v[166:169], v[222:225], v[36:39]
	v_mfma_f32_16x16x32_bf16 v[32:35], v[174:177], v[222:225], v[32:35]
	v_mfma_f32_16x16x32_bf16 v[60:63], v[170:173], v[202:205], v[60:63]
	v_mfma_f32_16x16x32_bf16 v[56:59], v[178:181], v[202:205], v[56:59]
	v_mfma_f32_16x16x32_bf16 v[52:55], v[170:173], v[210:213], v[52:55]
	v_mfma_f32_16x16x32_bf16 v[48:51], v[178:181], v[210:213], v[48:51]
	v_mfma_f32_16x16x32_bf16 v[44:47], v[170:173], v[218:221], v[44:47]
	v_mfma_f32_16x16x32_bf16 v[40:43], v[178:181], v[218:221], v[40:43]
	v_mfma_f32_16x16x32_bf16 v[36:39], v[170:173], v[226:229], v[36:39]
	v_mfma_f32_16x16x32_bf16 v[32:35], v[178:181], v[226:229], v[32:35]
	s_setprio 0
	s_barrier
	s_add_i32 s74, s74, s29
	v_lshl_add_u64 v[234:235], s[56:57], 0, v[142:143]
	s_mov_b32 m0, s74
	ds_read_b128 v[198:201], v161 offset:16384
	ds_read_b128 v[202:205], v161 offset:17408
	ds_read_b128 v[206:209], v161 offset:18432
	ds_read_b128 v[210:213], v161 offset:19456
	ds_read_b128 v[214:217], v161 offset:20480
	ds_read_b128 v[218:221], v161 offset:21504
	ds_read_b128 v[222:225], v161 offset:22528
	ds_read_b128 v[226:229], v161 offset:23552
	global_load_lds_dwordx4 v[234:235], off
	s_add_i32 m0, s74, 0x2000
	v_lshl_add_u64 v[236:237], s[56:57], 0, v[138:139]
	s_add_u32 s56, s56, s10
	s_addc_u32 s57, s57, s11
	s_add_i32 s74, s75, s29
	global_load_lds_dwordx4 v[236:237], off
	v_lshl_add_u64 v[238:239], s[56:57], 0, v[142:143]
	s_mov_b32 m0, s74
	v_lshl_add_u64 v[240:241], s[56:57], 0, v[138:139]
	global_load_lds_dwordx4 v[238:239], off
	s_add_i32 m0, s74, 0x2000
	v_lshl_add_u64 v[242:243], s[22:23], 0, v[144:145]
	global_load_lds_dwordx4 v[240:241], off
	s_mov_b32 m0, s64
	v_lshl_add_u64 v[244:245], s[22:23], 0, v[140:141]
	global_load_lds_dwordx4 v[242:243], off
	s_mov_b32 m0, s65
	s_nop 0
	global_load_lds_dwordx4 v[244:245], off
	s_waitcnt vmcnt(8)
	s_waitcnt lgkmcnt(0)
	s_barrier
; #define PG8_STAGE(bufoff, gbase, voff) do { _Pragma("unroll") for (int _i = 0; _i < 2; ++_i) \
;         __builtin_amdgcn_global_load_lds((const unsigned*)((const char*)(gbase) + (voff)[_i]), (PG8_LAS unsigned*)(lds + (bufoff) + ldsw + _i * 8192), 16, 0, 0); } while (0)
; #define PG8_LDA(dst, b, h) do { _Pragma("unroll") for (int m = 0; m < 4; ++m) _Pragma("unroll") for (int k = 0; k < 2; ++k) dst[m][k] = *(const PG8_LAS bf16x8*)(lds + PG8_SA(b, h) + aoff + m * 2048 + k * 1024); } while (0)
; #define PG8_LDB(dst, b, h) do { _Pragma("unroll") for (int n = 0; n < 2; ++n) _Pragma("unroll") for (int k = 0; k < 2; ++k) dst[n][k] = *(const PG8_LAS bf16x8*)(lds + PG8_SB(b, h) + boff + n * 2048 + k * 1024); } while (0)
; #define PG8_MMA(ai, bj, At, Bt) do { __builtin_amdgcn_s_setprio(1); _Pragma("unroll") for (int m = 0; m < 4; ++m) _Pragma("unroll") for (int n = 0; n < 2; ++n) _Pragma("unroll") for (int k = 0; k < 2; ++k) \
;         acc[ai][bj][m][n] = __builtin_amdgcn_mfma_f32_16x16x32_bf16(Bt[n][k], At[m][k], acc[ai][bj][m][n], 0, 0, 0); __builtin_amdgcn_s_setprio(0); } while (0)
; #define PG8_WAIT_V(n) asm volatile("s_waitcnt vmcnt(" #n ")" ::: "memory")
; #define PG8_WAIT_L(n) asm volatile("s_waitcnt lgkmcnt(" #n ")" ::: "memory")
; #define PG8_BAR __builtin_amdgcn_s_barrier()
; #define PG8_SCHED __builtin_amdgcn_sched_barrier(0)
; template <class Epi, class Sched, bool ALIGN_EPI = false, bool SP2 = false>
; __device__ __forceinline__ void gemm_phase(PG8_LAS unsigned char* lds, const Gemm g, const Sched& S, const Epi& E) {
;     ...
;             PG8_WAIT_V(8); PG8_WAIT_L(0); PG8_BAR; PG8_MMA(1, 0, At, B0); PG8_MMA(1, 1, At, B1); PG8_BAR; PG8_SCHED;
;             PG8_LDB(B0, 1, 0); PG8_LDB(B1, 1, 1); PG8_SCHED; PG8_LDA(At, 1, 0); PG8_STAGE(PG8_SA(0, 1), a2 + hstep, voffA);
;             PG8_WAIT_V(8); PG8_WAIT_L(0); PG8_BAR; PG8_MMA(0, 0, At, B0); PG8_MMA(0, 1, At, B1); PG8_BAR; PG8_SCHED;
	s_setprio 1
	v_mfma_f32_16x16x32_bf16 v[92:95], v[114:117], v[198:201], v[92:95]
	v_mfma_f32_16x16x32_bf16 v[88:91], v[150:153], v[198:201], v[88:91]
	v_mfma_f32_16x16x32_bf16 v[84:87], v[114:117], v[206:209], v[84:87]
	v_mfma_f32_16x16x32_bf16 v[80:83], v[150:153], v[206:209], v[80:83]
	v_mfma_f32_16x16x32_bf16 v[76:79], v[114:117], v[214:217], v[76:79]
	v_mfma_f32_16x16x32_bf16 v[72:75], v[150:153], v[214:217], v[72:75]
	v_mfma_f32_16x16x32_bf16 v[68:71], v[114:117], v[222:225], v[68:71]
	v_mfma_f32_16x16x32_bf16 v[64:67], v[150:153], v[222:225], v[64:67]
	v_mfma_f32_16x16x32_bf16 v[92:95], v[118:121], v[202:205], v[92:95]
	v_mfma_f32_16x16x32_bf16 v[88:91], v[162:165], v[202:205], v[88:91]
	v_mfma_f32_16x16x32_bf16 v[84:87], v[118:121], v[210:213], v[84:87]
	v_mfma_f32_16x16x32_bf16 v[80:83], v[162:165], v[210:213], v[80:83]
	v_mfma_f32_16x16x32_bf16 v[76:79], v[118:121], v[218:221], v[76:79]
	v_mfma_f32_16x16x32_bf16 v[72:75], v[162:165], v[218:221], v[72:75]
	v_mfma_f32_16x16x32_bf16 v[68:71], v[118:121], v[226:229], v[68:71]
	v_mfma_f32_16x16x32_bf16 v[64:67], v[162:165], v[226:229], v[64:67]
	v_mfma_f32_16x16x32_bf16 v[28:31], v[166:169], v[198:201], v[28:31]
	v_mfma_f32_16x16x32_bf16 v[24:27], v[174:177], v[198:201], v[24:27]
	v_mfma_f32_16x16x32_bf16 v[20:23], v[166:169], v[206:209], v[20:23]
	v_mfma_f32_16x16x32_bf16 v[16:19], v[174:177], v[206:209], v[16:19]
	v_mfma_f32_16x16x32_bf16 v[12:15], v[166:169], v[214:217], v[12:15]
	v_mfma_f32_16x16x32_bf16 v[8:11], v[174:177], v[214:217], v[8:11]
	v_mfma_f32_16x16x32_bf16 v[4:7], v[166:169], v[222:225], v[4:7]
	v_mfma_f32_16x16x32_bf16 v[0:3], v[174:177], v[222:225], v[0:3]
	v_mfma_f32_16x16x32_bf16 v[28:31], v[170:173], v[202:205], v[28:31]
	v_mfma_f32_16x16x32_bf16 v[24:27], v[178:181], v[202:205], v[24:27]
	v_mfma_f32_16x16x32_bf16 v[20:23], v[170:173], v[210:213], v[20:23]
	v_mfma_f32_16x16x32_bf16 v[16:19], v[178:181], v[210:213], v[16:19]
	v_mfma_f32_16x16x32_bf16 v[12:15], v[170:173], v[218:221], v[12:15]
	v_mfma_f32_16x16x32_bf16 v[8:11], v[178:181], v[218:221], v[8:11]
	v_mfma_f32_16x16x32_bf16 v[4:7], v[170:173], v[226:229], v[4:7]
	v_mfma_f32_16x16x32_bf16 v[0:3], v[178:181], v[226:229], v[0:3]
	s_setprio 0
	s_barrier
	s_add_i32 s56, 0, 0x18000
	v_add_u32_e32 v112, s56, v159
	s_add_i32 s57, 0, 0x1c000
	ds_read_b128 v[114:117], v112
	ds_read_b128 v[118:121], v112 offset:1024
	ds_read_b128 v[150:153], v112 offset:2048
	ds_read_b128 v[162:165], v112 offset:3072
	v_add_u32_e32 v112, s57, v159
	ds_read_b128 v[166:169], v112
	ds_read_b128 v[170:173], v112 offset:1024
	ds_read_b128 v[174:177], v112 offset:2048
	ds_read_b128 v[178:181], v112 offset:3072
	s_add_u32 s22, s22, s10
	s_addc_u32 s23, s23, s11
	s_mov_b32 m0, s70
	v_lshl_add_u64 v[246:247], s[22:23], 0, v[144:145]
	ds_read_b128 v[198:201], v161 offset:32768
	ds_read_b128 v[202:205], v161 offset:33792
	ds_read_b128 v[206:209], v161 offset:34816
	ds_read_b128 v[210:213], v161 offset:35840
	ds_read_b128 v[214:217], v161 offset:36864
	ds_read_b128 v[218:221], v161 offset:37888
	ds_read_b128 v[222:225], v161 offset:38912
	ds_read_b128 v[226:229], v161 offset:39936
	global_load_lds_dwordx4 v[246:247], off
	v_lshl_add_u64 v[246:247], s[22:23], 0, v[140:141]
	s_mov_b32 m0, s71
	s_nop 0
	global_load_lds_dwordx4 v[246:247], off
	s_waitcnt vmcnt(8)
	s_waitcnt lgkmcnt(0)
	s_barrier
	s_setprio 1
	v_mfma_f32_16x16x32_bf16 v[134:137], v[114:117], v[198:201], v[134:137]
	v_mfma_f32_16x16x32_bf16 v[130:133], v[150:153], v[198:201], v[130:133]
	v_mfma_f32_16x16x32_bf16 v[126:129], v[114:117], v[206:209], v[126:129]
	v_mfma_f32_16x16x32_bf16 v[122:125], v[150:153], v[206:209], v[122:125]
	v_mfma_f32_16x16x32_bf16 v[108:111], v[114:117], v[214:217], v[108:111]
	v_mfma_f32_16x16x32_bf16 v[104:107], v[150:153], v[214:217], v[104:107]
	v_mfma_f32_16x16x32_bf16 v[100:103], v[114:117], v[222:225], v[100:103]
	v_mfma_f32_16x16x32_bf16 v[96:99], v[150:153], v[222:225], v[96:99]
	v_mfma_f32_16x16x32_bf16 v[134:137], v[118:121], v[202:205], v[134:137]
	v_mfma_f32_16x16x32_bf16 v[130:133], v[162:165], v[202:205], v[130:133]
	v_mfma_f32_16x16x32_bf16 v[126:129], v[118:121], v[210:213], v[126:129]
	v_mfma_f32_16x16x32_bf16 v[122:125], v[162:165], v[210:213], v[122:125]
	v_mfma_f32_16x16x32_bf16 v[108:111], v[118:121], v[218:221], v[108:111]
	v_mfma_f32_16x16x32_bf16 v[104:107], v[162:165], v[218:221], v[104:107]
	v_mfma_f32_16x16x32_bf16 v[100:103], v[118:121], v[226:229], v[100:103]
	v_mfma_f32_16x16x32_bf16 v[96:99], v[162:165], v[226:229], v[96:99]
	v_mfma_f32_16x16x32_bf16 v[60:63], v[166:169], v[198:201], v[60:63]
	v_mfma_f32_16x16x32_bf16 v[56:59], v[174:177], v[198:201], v[56:59]
	v_mfma_f32_16x16x32_bf16 v[52:55], v[166:169], v[206:209], v[52:55]
	v_mfma_f32_16x16x32_bf16 v[48:51], v[174:177], v[206:209], v[48:51]
	v_mfma_f32_16x16x32_bf16 v[44:47], v[166:169], v[214:217], v[44:47]
	v_mfma_f32_16x16x32_bf16 v[40:43], v[174:177], v[214:217], v[40:43]
	v_mfma_f32_16x16x32_bf16 v[36:39], v[166:169], v[222:225], v[36:39]
	v_mfma_f32_16x16x32_bf16 v[32:35], v[174:177], v[222:225], v[32:35]
	v_mfma_f32_16x16x32_bf16 v[60:63], v[170:173], v[202:205], v[60:63]
	v_mfma_f32_16x16x32_bf16 v[56:59], v[178:181], v[202:205], v[56:59]
	v_mfma_f32_16x16x32_bf16 v[52:55], v[170:173], v[210:213], v[52:55]
	v_mfma_f32_16x16x32_bf16 v[48:51], v[178:181], v[210:213], v[48:51]
	v_mfma_f32_16x16x32_bf16 v[44:47], v[170:173], v[218:221], v[44:47]
	v_mfma_f32_16x16x32_bf16 v[40:43], v[178:181], v[218:221], v[40:43]
	v_mfma_f32_16x16x32_bf16 v[36:39], v[170:173], v[226:229], v[36:39]
	v_mfma_f32_16x16x32_bf16 v[32:35], v[178:181], v[226:229], v[32:35]
	s_setprio 0
	s_barrier
; #define PG8_STAGE(bufoff, gbase, voff) do { _Pragma("unroll") for (int _i = 0; _i < 2; ++_i) \
;         __builtin_amdgcn_global_load_lds((const unsigned*)((const char*)(gbase) + (voff)[_i]), (PG8_LAS unsigned*)(lds + (bufoff) + ldsw + _i * 8192), 16, 0, 0); } while (0)
; #define PG8_LDA(dst, b, h) do { _Pragma("unroll") for (int m = 0; m < 4; ++m) _Pragma("unroll") for (int k = 0; k < 2; ++k) dst[m][k] = *(const PG8_LAS bf16x8*)(lds + PG8_SA(b, h) + aoff + m * 2048 + k * 1024); } while (0)
; #define PG8_MMA(ai, bj, At, Bt) do { __builtin_amdgcn_s_setprio(1); _Pragma("unroll") for (int m = 0; m < 4; ++m) _Pragma("unroll") for (int n = 0; n < 2; ++n) _Pragma("unroll") for (int k = 0; k < 2; ++k) \
;         acc[ai][bj][m][n] = __builtin_amdgcn_mfma_f32_16x16x32_bf16(Bt[n][k], At[m][k], acc[ai][bj][m][n], 0, 0, 0); __builtin_amdgcn_s_setprio(0); } while (0)
; #define PG8_WAIT_V(n) asm volatile("s_waitcnt vmcnt(" #n ")" ::: "memory")
; #define PG8_WAIT_L(n) asm volatile("s_waitcnt lgkmcnt(" #n ")" ::: "memory")
; #define PG8_BAR __builtin_amdgcn_s_barrier()
; #define PG8_SCHED __builtin_amdgcn_sched_barrier(0)
; template <class Epi, class Sched, bool ALIGN_EPI = false, bool SP2 = false>
; __device__ __forceinline__ void gemm_phase(PG8_LAS unsigned char* lds, const Gemm g, const Sched& S, const Epi& E) {
;     ...
;             PG8_LDA(At, 1, 1); PG8_STAGE(PG8_SB(1, 0), b3, voffB); PG8_STAGE(PG8_SB(1, 1), b3 + hstep, voffB); PG8_STAGE(PG8_SA(1, 0), a3, voffA);
;             PG8_WAIT_V(8); PG8_WAIT_L(0); PG8_BAR; PG8_MMA(1, 0, At, B0); PG8_MMA(1, 1, At, B1); PG8_BAR; PG8_SCHED;
	s_add_i32 s22, s56, s29
	v_lshl_add_u64 v[234:235], v[234:235], 0, s[52:53]
	s_mov_b32 m0, s22
	ds_read_b128 v[198:201], v161 offset:49152
	ds_read_b128 v[202:205], v161 offset:50176
	ds_read_b128 v[206:209], v161 offset:51200
	ds_read_b128 v[210:213], v161 offset:52224
	ds_read_b128 v[214:217], v161 offset:53248
	ds_read_b128 v[218:221], v161 offset:54272
	ds_read_b128 v[222:225], v161 offset:55296
	ds_read_b128 v[226:229], v161 offset:56320
	global_load_lds_dwordx4 v[234:235], off
	v_lshl_add_u64 v[234:235], v[236:237], 0, s[52:53]
	s_add_i32 m0, s22, 0x2000
	s_add_i32 s22, s57, s29
	global_load_lds_dwordx4 v[234:235], off
	v_lshl_add_u64 v[234:235], v[238:239], 0, s[52:53]
	s_mov_b32 m0, s22
	s_nop 0
	global_load_lds_dwordx4 v[234:235], off
	v_lshl_add_u64 v[234:235], v[240:241], 0, s[52:53]
	s_add_i32 m0, s22, 0x2000
	s_nop 0
	global_load_lds_dwordx4 v[234:235], off
	v_lshl_add_u64 v[234:235], v[242:243], 0, s[52:53]
	s_mov_b32 m0, s81
	s_nop 0
	global_load_lds_dwordx4 v[234:235], off
	v_lshl_add_u64 v[234:235], v[244:245], 0, s[52:53]
	s_mov_b32 m0, s50
	s_nop 0
	global_load_lds_dwordx4 v[234:235], off
	s_waitcnt vmcnt(8)
	s_waitcnt lgkmcnt(0)
	s_barrier
	s_setprio 1
	v_mfma_f32_16x16x32_bf16 v[92:95], v[114:117], v[198:201], v[92:95]
	v_mfma_f32_16x16x32_bf16 v[88:91], v[150:153], v[198:201], v[88:91]
	v_mfma_f32_16x16x32_bf16 v[84:87], v[114:117], v[206:209], v[84:87]
	v_mfma_f32_16x16x32_bf16 v[80:83], v[150:153], v[206:209], v[80:83]
	v_mfma_f32_16x16x32_bf16 v[76:79], v[114:117], v[214:217], v[76:79]
	v_mfma_f32_16x16x32_bf16 v[72:75], v[150:153], v[214:217], v[72:75]
	v_mfma_f32_16x16x32_bf16 v[68:71], v[114:117], v[222:225], v[68:71]
	v_mfma_f32_16x16x32_bf16 v[64:67], v[150:153], v[222:225], v[64:67]
	v_mfma_f32_16x16x32_bf16 v[92:95], v[118:121], v[202:205], v[92:95]
	v_mfma_f32_16x16x32_bf16 v[88:91], v[162:165], v[202:205], v[88:91]
	v_mfma_f32_16x16x32_bf16 v[84:87], v[118:121], v[210:213], v[84:87]
	v_mfma_f32_16x16x32_bf16 v[80:83], v[162:165], v[210:213], v[80:83]
	v_mfma_f32_16x16x32_bf16 v[76:79], v[118:121], v[218:221], v[76:79]
	v_mfma_f32_16x16x32_bf16 v[72:75], v[162:165], v[218:221], v[72:75]
	v_mfma_f32_16x16x32_bf16 v[68:71], v[118:121], v[226:229], v[68:71]
	v_mfma_f32_16x16x32_bf16 v[64:67], v[162:165], v[226:229], v[64:67]
	v_mfma_f32_16x16x32_bf16 v[28:31], v[166:169], v[198:201], v[28:31]
	v_mfma_f32_16x16x32_bf16 v[24:27], v[174:177], v[198:201], v[24:27]
	v_mfma_f32_16x16x32_bf16 v[20:23], v[166:169], v[206:209], v[20:23]
	v_mfma_f32_16x16x32_bf16 v[16:19], v[174:177], v[206:209], v[16:19]
	v_mfma_f32_16x16x32_bf16 v[12:15], v[166:169], v[214:217], v[12:15]
	v_mfma_f32_16x16x32_bf16 v[8:11], v[174:177], v[214:217], v[8:11]
	v_mfma_f32_16x16x32_bf16 v[4:7], v[166:169], v[222:225], v[4:7]
	v_mfma_f32_16x16x32_bf16 v[0:3], v[174:177], v[222:225], v[0:3]
	v_mfma_f32_16x16x32_bf16 v[28:31], v[170:173], v[202:205], v[28:31]
	v_mfma_f32_16x16x32_bf16 v[24:27], v[178:181], v[202:205], v[24:27]
	v_mfma_f32_16x16x32_bf16 v[20:23], v[170:173], v[210:213], v[20:23]
	v_mfma_f32_16x16x32_bf16 v[16:19], v[178:181], v[210:213], v[16:19]
	v_mfma_f32_16x16x32_bf16 v[12:15], v[170:173], v[218:221], v[12:15]
	v_mfma_f32_16x16x32_bf16 v[8:11], v[178:181], v[218:221], v[8:11]
	v_mfma_f32_16x16x32_bf16 v[4:7], v[170:173], v[226:229], v[4:7]
	v_mfma_f32_16x16x32_bf16 v[0:3], v[178:181], v[226:229], v[0:3]
	s_setprio 0
	s_barrier
	s_add_u32 s0, s0, 0x100
	s_addc_u32 s1, s1, 0
	s_add_u32 s15, s15, 0x100
	s_addc_u32 s24, s24, 0
	s_cmp_ge_i32 s25, s77
	s_mov_b32 s22, s25
	s_cbranch_scc0 .LBB0_441
	v_readlane_b32 s75, v255, 7

; #define PG8_STAGE(bufoff, gbase, voff) do { _Pragma("unroll") for (int _i = 0; _i < 2; ++_i) \
;         __builtin_amdgcn_global_load_lds((const unsigned*)((const char*)(gbase) + (voff)[_i]), (PG8_LAS unsigned*)(lds + (bufoff) + ldsw + _i * 8192), 16, 0, 0); } while (0)
; #define PG8_LDA(dst, b, h) do { _Pragma("unroll") for (int m = 0; m < 4; ++m) _Pragma("unroll") for (int k = 0; k < 2; ++k) dst[m][k] = *(const PG8_LAS bf16x8*)(lds + PG8_SA(b, h) + aoff + m * 2048 + k * 1024); } while (0)
; #define PG8_LDB(dst, b, h) do { _Pragma("unroll") for (int n = 0; n < 2; ++n) _Pragma("unroll") for (int k = 0; k < 2; ++k) dst[n][k] = *(const PG8_LAS bf16x8*)(lds + PG8_SB(b, h) + boff + n * 2048 + k * 1024); } while (0)
; #define PG8_MMA(ai, bj, At, Bt) do { __builtin_amdgcn_s_setprio(1); _Pragma("unroll") for (int m = 0; m < 4; ++m) _Pragma("unroll") for (int n = 0; n < 2; ++n) _Pragma("unroll") for (int k = 0; k < 2; ++k) \
;         acc[ai][bj][m][n] = __builtin_amdgcn_mfma_f32_16x16x32_bf16(Bt[n][k], At[m][k], acc[ai][bj][m][n], 0, 0, 0); __builtin_amdgcn_s_setprio(0); } while (0)
; #define PG8_WAIT_V(n) asm volatile("s_waitcnt vmcnt(" #n ")" ::: "memory")
; #define PG8_WAIT_L(n) asm volatile("s_waitcnt lgkmcnt(" #n ")" ::: "memory")
; #define PG8_BAR __builtin_amdgcn_s_barrier()
; #define PG8_SCHED __builtin_amdgcn_sched_barrier(0)
; template <class Epi, class Sched, bool ALIGN_EPI = false, bool SP2 = false>
; __device__ __forceinline__ void gemm_phase(PG8_LAS unsigned char* lds, const Gemm g, const Sched& S, const Epi& E) {
;     ...
;         for (int t = 0; t < nt; t += 2) {
;             const bool last = (t == nt - 2);
;             const char* a1 = cA + (size_t)(t + 1) * kstep;
;             const char* a2 = last ? nA : cA + (size_t)(t + 2) * kstep; const char* b2 = last ? nB : cB + (size_t)(t + 2) * kstep;
;             const char* a3 = a2 + kstep; const char* b3 = b2 + kstep;
;             if (last && has_next) S.a_ready(nxt);
;             if constexpr (SP2) {
;             PG8_LDB(B0, 0, 0); PG8_LDB(B1, 0, 1); PG8_SCHED; PG8_LDA(At, 0, 0); PG8_STAGE(PG8_SA(1, 1), a1 + hstep, voffA);
;             PG8_WAIT_V(8); PG8_WAIT_L(0); PG8_BAR; PG8_MMA(0, 0, At, B0); PG8_MMA(0, 1, At, B1); PG8_BAR; PG8_SCHED;
;             PG8_LDA(At, 0, 1); PG8_STAGE(PG8_SB(0, 0), b2, voffB); PG8_STAGE(PG8_SB(0, 1), b2 + hstep, voffB); PG8_STAGE(PG8_SA(0, 0), a2, voffA);
.LBB0_465:
	s_add_i32 s29, s22, 2
	s_add_u32 s75, s6, 0x80
	s_addc_u32 s23, s7, 0
	s_add_i32 s14, 0, 0x10000
	s_cmp_eq_u32 s79, s22
	s_cselect_b32 s23, s1, s23
	s_cselect_b32 s22, s0, s75
	v_add_u32_e32 v112, s14, v160
	s_cselect_b32 vcc_hi, s21, s25
	s_cselect_b32 vcc_lo, s20, s24
	s_add_i32 s15, 0, 0x14000
	ds_read_b128 v[130:133], v112
	ds_read_b128 v[134:137], v112 offset:1024
	ds_read_b128 v[164:167], v112 offset:2048
	ds_read_b128 v[168:171], v112 offset:3072
	v_add_u32_e32 v112, s15, v160
	ds_read_b128 v[172:175], v112
	ds_read_b128 v[176:179], v112 offset:1024
	ds_read_b128 v[198:201], v112 offset:2048
	ds_read_b128 v[202:205], v112 offset:3072
	v_lshl_add_u64 v[152:153], s[6:7], 0, v[146:147]
	s_add_i32 m0, s50, 0xc000
	ds_read_b128 v[206:209], v162
	ds_read_b128 v[210:213], v162 offset:1024
	ds_read_b128 v[214:217], v162 offset:2048
	ds_read_b128 v[218:221], v162 offset:3072
	ds_read_b128 v[222:225], v162 offset:4096
	ds_read_b128 v[226:229], v162 offset:5120
	ds_read_b128 v[234:237], v162 offset:6144
	ds_read_b128 v[238:241], v162 offset:7168
	global_load_lds_dwordx4 v[152:153], off
	v_lshl_add_u64 v[152:153], s[6:7], 0, v[148:149]
	s_add_i32 m0, s50, 0xe000
	s_nop 0
	global_load_lds_dwordx4 v[152:153], off
	s_waitcnt vmcnt(8)
	s_waitcnt lgkmcnt(0)
	s_barrier
	s_setprio 1
	v_mfma_f32_16x16x32_bf16 v[126:129], v[130:133], v[206:209], v[126:129]
	v_mfma_f32_16x16x32_bf16 v[122:125], v[164:167], v[206:209], v[122:125]
	v_mfma_f32_16x16x32_bf16 v[118:121], v[130:133], v[214:217], v[118:121]
	v_mfma_f32_16x16x32_bf16 v[114:117], v[164:167], v[214:217], v[114:117]
	v_mfma_f32_16x16x32_bf16 v[108:111], v[130:133], v[222:225], v[108:111]
	v_mfma_f32_16x16x32_bf16 v[104:107], v[164:167], v[222:225], v[104:107]
	v_mfma_f32_16x16x32_bf16 v[100:103], v[130:133], v[234:237], v[100:103]
	v_mfma_f32_16x16x32_bf16 v[96:99], v[164:167], v[234:237], v[96:99]
	v_mfma_f32_16x16x32_bf16 v[126:129], v[134:137], v[210:213], v[126:129]
	v_mfma_f32_16x16x32_bf16 v[122:125], v[168:171], v[210:213], v[122:125]
	v_mfma_f32_16x16x32_bf16 v[118:121], v[134:137], v[218:221], v[118:121]
	v_mfma_f32_16x16x32_bf16 v[114:117], v[168:171], v[218:221], v[114:117]
	v_mfma_f32_16x16x32_bf16 v[108:111], v[134:137], v[226:229], v[108:111]
	v_mfma_f32_16x16x32_bf16 v[104:107], v[168:171], v[226:229], v[104:107]
	v_mfma_f32_16x16x32_bf16 v[100:103], v[134:137], v[238:241], v[100:103]
	v_mfma_f32_16x16x32_bf16 v[96:99], v[168:171], v[238:241], v[96:99]
	v_mfma_f32_16x16x32_bf16 v[60:63], v[172:175], v[206:209], v[60:63]
	v_mfma_f32_16x16x32_bf16 v[56:59], v[198:201], v[206:209], v[56:59]
	v_mfma_f32_16x16x32_bf16 v[52:55], v[172:175], v[214:217], v[52:55]
	v_mfma_f32_16x16x32_bf16 v[48:51], v[198:201], v[214:217], v[48:51]
	v_mfma_f32_16x16x32_bf16 v[44:47], v[172:175], v[222:225], v[44:47]
	v_mfma_f32_16x16x32_bf16 v[40:43], v[198:201], v[222:225], v[40:43]
	v_mfma_f32_16x16x32_bf16 v[36:39], v[172:175], v[234:237], v[36:39]
	v_mfma_f32_16x16x32_bf16 v[32:35], v[198:201], v[234:237], v[32:35]
	v_mfma_f32_16x16x32_bf16 v[60:63], v[176:179], v[210:213], v[60:63]
	v_mfma_f32_16x16x32_bf16 v[56:59], v[202:205], v[210:213], v[56:59]
	v_mfma_f32_16x16x32_bf16 v[52:55], v[176:179], v[218:221], v[52:55]
	v_mfma_f32_16x16x32_bf16 v[48:51], v[202:205], v[218:221], v[48:51]
	v_mfma_f32_16x16x32_bf16 v[44:47], v[176:179], v[226:229], v[44:47]
	v_mfma_f32_16x16x32_bf16 v[40:43], v[202:205], v[226:229], v[40:43]
	v_mfma_f32_16x16x32_bf16 v[36:39], v[176:179], v[238:241], v[36:39]
	v_mfma_f32_16x16x32_bf16 v[32:35], v[202:205], v[238:241], v[32:35]
	s_setprio 0
	s_barrier
	s_add_i32 s14, s14, s49
	v_lshl_add_u64 v[152:153], vcc, 0, v[140:141]
	s_mov_b32 m0, s14
	ds_read_b128 v[206:209], v162 offset:16384
	ds_read_b128 v[210:213], v162 offset:17408
	ds_read_b128 v[214:217], v162 offset:18432
	ds_read_b128 v[218:221], v162 offset:19456
	ds_read_b128 v[222:225], v162 offset:20480
	ds_read_b128 v[226:229], v162 offset:21504
	ds_read_b128 v[234:237], v162 offset:22528
	ds_read_b128 v[238:241], v162 offset:23552
	global_load_lds_dwordx4 v[152:153], off
	s_add_i32 m0, s14, 0x2000
	v_lshl_add_u64 v[158:159], vcc, 0, v[144:145]
	s_add_u32 vcc_lo, vcc_lo, s10
	s_addc_u32 vcc_hi, vcc_hi, s11
	s_add_i32 s14, s15, s49
	global_load_lds_dwordx4 v[158:159], off
	v_lshl_add_u64 v[180:181], vcc, 0, v[140:141]
	s_mov_b32 m0, s14
	v_lshl_add_u64 v[242:243], vcc, 0, v[144:145]
	global_load_lds_dwordx4 v[180:181], off
	s_add_i32 m0, s14, 0x2000
	v_lshl_add_u64 v[244:245], s[22:23], 0, v[138:139]
	global_load_lds_dwordx4 v[242:243], off
	s_mov_b32 m0, s50
	v_lshl_add_u64 v[246:247], s[22:23], 0, v[142:143]
	global_load_lds_dwordx4 v[244:245], off
	s_mov_b32 m0, s51
	s_nop 0
	global_load_lds_dwordx4 v[246:247], off
	s_waitcnt vmcnt(8)
	s_waitcnt lgkmcnt(0)
	s_barrier
; #define PG8_STAGE(bufoff, gbase, voff) do { _Pragma("unroll") for (int _i = 0; _i < 2; ++_i) \
;         __builtin_amdgcn_global_load_lds((const unsigned*)((const char*)(gbase) + (voff)[_i]), (PG8_LAS unsigned*)(lds + (bufoff) + ldsw + _i * 8192), 16, 0, 0); } while (0)
; #define PG8_LDA(dst, b, h) do { _Pragma("unroll") for (int m = 0; m < 4; ++m) _Pragma("unroll") for (int k = 0; k < 2; ++k) dst[m][k] = *(const PG8_LAS bf16x8*)(lds + PG8_SA(b, h) + aoff + m * 2048 + k * 1024); } while (0)
; #define PG8_LDB(dst, b, h) do { _Pragma("unroll") for (int n = 0; n < 2; ++n) _Pragma("unroll") for (int k = 0; k < 2; ++k) dst[n][k] = *(const PG8_LAS bf16x8*)(lds + PG8_SB(b, h) + boff + n * 2048 + k * 1024); } while (0)
; #define PG8_MMA(ai, bj, At, Bt) do { __builtin_amdgcn_s_setprio(1); _Pragma("unroll") for (int m = 0; m < 4; ++m) _Pragma("unroll") for (int n = 0; n < 2; ++n) _Pragma("unroll") for (int k = 0; k < 2; ++k) \
;         acc[ai][bj][m][n] = __builtin_amdgcn_mfma_f32_16x16x32_bf16(Bt[n][k], At[m][k], acc[ai][bj][m][n], 0, 0, 0); __builtin_amdgcn_s_setprio(0); } while (0)
; #define PG8_WAIT_V(n) asm volatile("s_waitcnt vmcnt(" #n ")" ::: "memory")
; #define PG8_WAIT_L(n) asm volatile("s_waitcnt lgkmcnt(" #n ")" ::: "memory")
; #define PG8_BAR __builtin_amdgcn_s_barrier()
; #define PG8_SCHED __builtin_amdgcn_sched_barrier(0)
; template <class Epi, class Sched, bool ALIGN_EPI = false, bool SP2 = false>
; __device__ __forceinline__ void gemm_phase(PG8_LAS unsigned char* lds, const Gemm g, const Sched& S, const Epi& E) {
;     ...
;             PG8_WAIT_V(8); PG8_WAIT_L(0); PG8_BAR; PG8_MMA(1, 0, At, B0); PG8_MMA(1, 1, At, B1); PG8_BAR; PG8_SCHED;
;             PG8_LDB(B0, 1, 0); PG8_LDB(B1, 1, 1); PG8_SCHED; PG8_LDA(At, 1, 0); PG8_STAGE(PG8_SA(0, 1), a2 + hstep, voffA);
;             PG8_WAIT_V(8); PG8_WAIT_L(0); PG8_BAR; PG8_MMA(0, 0, At, B0); PG8_MMA(0, 1, At, B1); PG8_BAR; PG8_SCHED;
	s_setprio 1
	v_mfma_f32_16x16x32_bf16 v[92:95], v[130:133], v[206:209], v[92:95]
	v_mfma_f32_16x16x32_bf16 v[88:91], v[164:167], v[206:209], v[88:91]
	v_mfma_f32_16x16x32_bf16 v[84:87], v[130:133], v[214:217], v[84:87]
	v_mfma_f32_16x16x32_bf16 v[80:83], v[164:167], v[214:217], v[80:83]
	v_mfma_f32_16x16x32_bf16 v[76:79], v[130:133], v[222:225], v[76:79]
	v_mfma_f32_16x16x32_bf16 v[72:75], v[164:167], v[222:225], v[72:75]
	v_mfma_f32_16x16x32_bf16 v[68:71], v[130:133], v[234:237], v[68:71]
	v_mfma_f32_16x16x32_bf16 v[64:67], v[164:167], v[234:237], v[64:67]
	v_mfma_f32_16x16x32_bf16 v[92:95], v[134:137], v[210:213], v[92:95]
	v_mfma_f32_16x16x32_bf16 v[88:91], v[168:171], v[210:213], v[88:91]
	v_mfma_f32_16x16x32_bf16 v[84:87], v[134:137], v[218:221], v[84:87]
	v_mfma_f32_16x16x32_bf16 v[80:83], v[168:171], v[218:221], v[80:83]
	v_mfma_f32_16x16x32_bf16 v[76:79], v[134:137], v[226:229], v[76:79]
	v_mfma_f32_16x16x32_bf16 v[72:75], v[168:171], v[226:229], v[72:75]
	v_mfma_f32_16x16x32_bf16 v[68:71], v[134:137], v[238:241], v[68:71]
	v_mfma_f32_16x16x32_bf16 v[64:67], v[168:171], v[238:241], v[64:67]
	v_mfma_f32_16x16x32_bf16 v[28:31], v[172:175], v[206:209], v[28:31]
	v_mfma_f32_16x16x32_bf16 v[24:27], v[198:201], v[206:209], v[24:27]
	v_mfma_f32_16x16x32_bf16 v[20:23], v[172:175], v[214:217], v[20:23]
	v_mfma_f32_16x16x32_bf16 v[16:19], v[198:201], v[214:217], v[16:19]
	v_mfma_f32_16x16x32_bf16 v[12:15], v[172:175], v[222:225], v[12:15]
	v_mfma_f32_16x16x32_bf16 v[8:11], v[198:201], v[222:225], v[8:11]
	v_mfma_f32_16x16x32_bf16 v[4:7], v[172:175], v[234:237], v[4:7]
	v_mfma_f32_16x16x32_bf16 v[0:3], v[198:201], v[234:237], v[0:3]
	v_mfma_f32_16x16x32_bf16 v[28:31], v[176:179], v[210:213], v[28:31]
	v_mfma_f32_16x16x32_bf16 v[24:27], v[202:205], v[210:213], v[24:27]
	v_mfma_f32_16x16x32_bf16 v[20:23], v[176:179], v[218:221], v[20:23]
	v_mfma_f32_16x16x32_bf16 v[16:19], v[202:205], v[218:221], v[16:19]
	v_mfma_f32_16x16x32_bf16 v[12:15], v[176:179], v[226:229], v[12:15]
	v_mfma_f32_16x16x32_bf16 v[8:11], v[202:205], v[226:229], v[8:11]
	v_mfma_f32_16x16x32_bf16 v[4:7], v[176:179], v[238:241], v[4:7]
	v_mfma_f32_16x16x32_bf16 v[0:3], v[202:205], v[238:241], v[0:3]
	s_setprio 0
	s_barrier
	s_add_i32 s14, 0, 0x18000
	v_add_u32_e32 v112, s14, v160
	s_add_i32 s15, 0, 0x1c000
	ds_read_b128 v[130:133], v112
	ds_read_b128 v[134:137], v112 offset:1024
	ds_read_b128 v[164:167], v112 offset:2048
	ds_read_b128 v[168:171], v112 offset:3072
	v_add_u32_e32 v112, s15, v160
	ds_read_b128 v[172:175], v112
	ds_read_b128 v[176:179], v112 offset:1024
	ds_read_b128 v[198:201], v112 offset:2048
	ds_read_b128 v[202:205], v112 offset:3072
	s_add_u32 s22, s22, s10
	s_addc_u32 s23, s23, s11
	s_mov_b32 m0, s54
	v_lshl_add_u64 v[248:249], s[22:23], 0, v[138:139]
	ds_read_b128 v[206:209], v162 offset:32768
	ds_read_b128 v[210:213], v162 offset:33792
	ds_read_b128 v[214:217], v162 offset:34816
	ds_read_b128 v[218:221], v162 offset:35840
	ds_read_b128 v[222:225], v162 offset:36864
	ds_read_b128 v[226:229], v162 offset:37888
	ds_read_b128 v[234:237], v162 offset:38912
	ds_read_b128 v[238:241], v162 offset:39936
	global_load_lds_dwordx4 v[248:249], off
	v_lshl_add_u64 v[248:249], s[22:23], 0, v[142:143]
	s_mov_b32 m0, s55
	s_nop 0
	global_load_lds_dwordx4 v[248:249], off
	s_waitcnt vmcnt(8)
	s_waitcnt lgkmcnt(0)
	s_barrier
	s_setprio 1
	v_mfma_f32_16x16x32_bf16 v[126:129], v[130:133], v[206:209], v[126:129]
	v_mfma_f32_16x16x32_bf16 v[122:125], v[164:167], v[206:209], v[122:125]
	v_mfma_f32_16x16x32_bf16 v[118:121], v[130:133], v[214:217], v[118:121]
	v_mfma_f32_16x16x32_bf16 v[114:117], v[164:167], v[214:217], v[114:117]
	v_mfma_f32_16x16x32_bf16 v[108:111], v[130:133], v[222:225], v[108:111]
	v_mfma_f32_16x16x32_bf16 v[104:107], v[164:167], v[222:225], v[104:107]
	v_mfma_f32_16x16x32_bf16 v[100:103], v[130:133], v[234:237], v[100:103]
	v_mfma_f32_16x16x32_bf16 v[96:99], v[164:167], v[234:237], v[96:99]
	v_mfma_f32_16x16x32_bf16 v[126:129], v[134:137], v[210:213], v[126:129]
	v_mfma_f32_16x16x32_bf16 v[122:125], v[168:171], v[210:213], v[122:125]
	v_mfma_f32_16x16x32_bf16 v[118:121], v[134:137], v[218:221], v[118:121]
	v_mfma_f32_16x16x32_bf16 v[114:117], v[168:171], v[218:221], v[114:117]
	v_mfma_f32_16x16x32_bf16 v[108:111], v[134:137], v[226:229], v[108:111]
	v_mfma_f32_16x16x32_bf16 v[104:107], v[168:171], v[226:229], v[104:107]
	v_mfma_f32_16x16x32_bf16 v[100:103], v[134:137], v[238:241], v[100:103]
	v_mfma_f32_16x16x32_bf16 v[96:99], v[168:171], v[238:241], v[96:99]
	v_mfma_f32_16x16x32_bf16 v[60:63], v[172:175], v[206:209], v[60:63]
	v_mfma_f32_16x16x32_bf16 v[56:59], v[198:201], v[206:209], v[56:59]
	v_mfma_f32_16x16x32_bf16 v[52:55], v[172:175], v[214:217], v[52:55]
	v_mfma_f32_16x16x32_bf16 v[48:51], v[198:201], v[214:217], v[48:51]
	v_mfma_f32_16x16x32_bf16 v[44:47], v[172:175], v[222:225], v[44:47]
	v_mfma_f32_16x16x32_bf16 v[40:43], v[198:201], v[222:225], v[40:43]
	v_mfma_f32_16x16x32_bf16 v[36:39], v[172:175], v[234:237], v[36:39]
	v_mfma_f32_16x16x32_bf16 v[32:35], v[198:201], v[234:237], v[32:35]
	v_mfma_f32_16x16x32_bf16 v[60:63], v[176:179], v[210:213], v[60:63]
	v_mfma_f32_16x16x32_bf16 v[56:59], v[202:205], v[210:213], v[56:59]
	v_mfma_f32_16x16x32_bf16 v[52:55], v[176:179], v[218:221], v[52:55]
	v_mfma_f32_16x16x32_bf16 v[48:51], v[202:205], v[218:221], v[48:51]
	v_mfma_f32_16x16x32_bf16 v[44:47], v[176:179], v[226:229], v[44:47]
	v_mfma_f32_16x16x32_bf16 v[40:43], v[202:205], v[226:229], v[40:43]
	v_mfma_f32_16x16x32_bf16 v[36:39], v[176:179], v[238:241], v[36:39]
	v_mfma_f32_16x16x32_bf16 v[32:35], v[202:205], v[238:241], v[32:35]
	s_setprio 0
	s_barrier
; #define PG8_STAGE(bufoff, gbase, voff) do { _Pragma("unroll") for (int _i = 0; _i < 2; ++_i) \
;         __builtin_amdgcn_global_load_lds((const unsigned*)((const char*)(gbase) + (voff)[_i]), (PG8_LAS unsigned*)(lds + (bufoff) + ldsw + _i * 8192), 16, 0, 0); } while (0)
; #define PG8_LDA(dst, b, h) do { _Pragma("unroll") for (int m = 0; m < 4; ++m) _Pragma("unroll") for (int k = 0; k < 2; ++k) dst[m][k] = *(const PG8_LAS bf16x8*)(lds + PG8_SA(b, h) + aoff + m * 2048 + k * 1024); } while (0)
; #define PG8_MMA(ai, bj, At, Bt) do { __builtin_amdgcn_s_setprio(1); _Pragma("unroll") for (int m = 0; m < 4; ++m) _Pragma("unroll") for (int n = 0; n < 2; ++n) _Pragma("unroll") for (int k = 0; k < 2; ++k) \
;         acc[ai][bj][m][n] = __builtin_amdgcn_mfma_f32_16x16x32_bf16(Bt[n][k], At[m][k], acc[ai][bj][m][n], 0, 0, 0); __builtin_amdgcn_s_setprio(0); } while (0)
; #define PG8_WAIT_V(n) asm volatile("s_waitcnt vmcnt(" #n ")" ::: "memory")
; #define PG8_WAIT_L(n) asm volatile("s_waitcnt lgkmcnt(" #n ")" ::: "memory")
; #define PG8_BAR __builtin_amdgcn_s_barrier()
; #define PG8_SCHED __builtin_amdgcn_sched_barrier(0)
; template <class Epi, class Sched, bool ALIGN_EPI = false, bool SP2 = false>
; __device__ __forceinline__ void gemm_phase(PG8_LAS unsigned char* lds, const Gemm g, const Sched& S, const Epi& E) {
;     ...
;             PG8_LDA(At, 1, 1); PG8_STAGE(PG8_SB(1, 0), b3, voffB); PG8_STAGE(PG8_SB(1, 1), b3 + hstep, voffB); PG8_STAGE(PG8_SA(1, 0), a3, voffA);
;             PG8_WAIT_V(8); PG8_WAIT_L(0); PG8_BAR; PG8_MMA(1, 0, At, B0); PG8_MMA(1, 1, At, B1); PG8_BAR; PG8_SCHED;
	s_add_i32 s14, s14, s49
	v_lshl_add_u64 v[152:153], v[152:153], 0, s[52:53]
	s_mov_b32 m0, s14
	ds_read_b128 v[206:209], v162 offset:49152
	ds_read_b128 v[210:213], v162 offset:50176
	ds_read_b128 v[214:217], v162 offset:51200
	ds_read_b128 v[218:221], v162 offset:52224
	ds_read_b128 v[222:225], v162 offset:53248
	ds_read_b128 v[226:229], v162 offset:54272
	ds_read_b128 v[234:237], v162 offset:55296
	ds_read_b128 v[238:241], v162 offset:56320
	global_load_lds_dwordx4 v[152:153], off
	v_lshl_add_u64 v[152:153], v[158:159], 0, s[52:53]
	s_add_i32 m0, s14, 0x2000
	s_add_i32 s14, s15, s49
	global_load_lds_dwordx4 v[152:153], off
	v_lshl_add_u64 v[152:153], v[180:181], 0, s[52:53]
	s_mov_b32 m0, s14
	s_nop 0
	global_load_lds_dwordx4 v[152:153], off
	v_lshl_add_u64 v[152:153], v[242:243], 0, s[52:53]
	s_add_i32 m0, s14, 0x2000
	s_nop 0
	global_load_lds_dwordx4 v[152:153], off
	v_lshl_add_u64 v[152:153], v[244:245], 0, s[52:53]
	s_mov_b32 m0, s71
	s_nop 0
	global_load_lds_dwordx4 v[152:153], off
	v_lshl_add_u64 v[152:153], v[246:247], 0, s[52:53]
	s_mov_b32 m0, s77
	s_nop 0
	global_load_lds_dwordx4 v[152:153], off
	s_waitcnt vmcnt(8)
	s_waitcnt lgkmcnt(0)
	s_barrier
	s_setprio 1
	v_mfma_f32_16x16x32_bf16 v[92:95], v[130:133], v[206:209], v[92:95]
	v_mfma_f32_16x16x32_bf16 v[88:91], v[164:167], v[206:209], v[88:91]
	v_mfma_f32_16x16x32_bf16 v[84:87], v[130:133], v[214:217], v[84:87]
	v_mfma_f32_16x16x32_bf16 v[80:83], v[164:167], v[214:217], v[80:83]
	v_mfma_f32_16x16x32_bf16 v[76:79], v[130:133], v[222:225], v[76:79]
	v_mfma_f32_16x16x32_bf16 v[72:75], v[164:167], v[222:225], v[72:75]
	v_mfma_f32_16x16x32_bf16 v[68:71], v[130:133], v[234:237], v[68:71]
	v_mfma_f32_16x16x32_bf16 v[64:67], v[164:167], v[234:237], v[64:67]
	v_mfma_f32_16x16x32_bf16 v[92:95], v[134:137], v[210:213], v[92:95]
	v_mfma_f32_16x16x32_bf16 v[88:91], v[168:171], v[210:213], v[88:91]
	v_mfma_f32_16x16x32_bf16 v[84:87], v[134:137], v[218:221], v[84:87]
	v_mfma_f32_16x16x32_bf16 v[80:83], v[168:171], v[218:221], v[80:83]
	v_mfma_f32_16x16x32_bf16 v[76:79], v[134:137], v[226:229], v[76:79]
	v_mfma_f32_16x16x32_bf16 v[72:75], v[168:171], v[226:229], v[72:75]
	v_mfma_f32_16x16x32_bf16 v[68:71], v[134:137], v[238:241], v[68:71]
	v_mfma_f32_16x16x32_bf16 v[64:67], v[168:171], v[238:241], v[64:67]
	v_mfma_f32_16x16x32_bf16 v[28:31], v[172:175], v[206:209], v[28:31]
	v_mfma_f32_16x16x32_bf16 v[24:27], v[198:201], v[206:209], v[24:27]
	v_mfma_f32_16x16x32_bf16 v[20:23], v[172:175], v[214:217], v[20:23]
	v_mfma_f32_16x16x32_bf16 v[16:19], v[198:201], v[214:217], v[16:19]
	v_mfma_f32_16x16x32_bf16 v[12:15], v[172:175], v[222:225], v[12:15]
	v_mfma_f32_16x16x32_bf16 v[8:11], v[198:201], v[222:225], v[8:11]
	v_mfma_f32_16x16x32_bf16 v[4:7], v[172:175], v[234:237], v[4:7]
	v_mfma_f32_16x16x32_bf16 v[0:3], v[198:201], v[234:237], v[0:3]
	v_mfma_f32_16x16x32_bf16 v[28:31], v[176:179], v[210:213], v[28:31]
	v_mfma_f32_16x16x32_bf16 v[24:27], v[202:205], v[210:213], v[24:27]
	v_mfma_f32_16x16x32_bf16 v[20:23], v[176:179], v[218:221], v[20:23]
	v_mfma_f32_16x16x32_bf16 v[16:19], v[202:205], v[218:221], v[16:19]
	v_mfma_f32_16x16x32_bf16 v[12:15], v[176:179], v[226:229], v[12:15]
	v_mfma_f32_16x16x32_bf16 v[8:11], v[202:205], v[226:229], v[8:11]
	v_mfma_f32_16x16x32_bf16 v[4:7], v[176:179], v[238:241], v[4:7]
	v_mfma_f32_16x16x32_bf16 v[0:3], v[202:205], v[238:241], v[0:3]
	s_setprio 0
	s_barrier
	s_add_u32 s6, s6, 0x100
	s_addc_u32 s7, s7, 0
	s_add_u32 s24, s24, 0x100
	s_addc_u32 s25, s25, 0
	s_cmp_ge_i32 s29, s64
	s_mov_b32 s22, s29
	s_cbranch_scc0 .LBB0_465
	v_readlane_b32 s75, v255, 7

; #define PG8_STAGE(bufoff, gbase, voff) do { _Pragma("unroll") for (int _i = 0; _i < 2; ++_i) \
;         __builtin_amdgcn_global_load_lds((const unsigned*)((const char*)(gbase) + (voff)[_i]), (PG8_LAS unsigned*)(lds + (bufoff) + ldsw + _i * 8192), 16, 0, 0); } while (0)
; #define PG8_LDA(dst, b, h) do { _Pragma("unroll") for (int m = 0; m < 4; ++m) _Pragma("unroll") for (int k = 0; k < 2; ++k) dst[m][k] = *(const PG8_LAS bf16x8*)(lds + PG8_SA(b, h) + aoff + m * 2048 + k * 1024); } while (0)
; #define PG8_LDB(dst, b, h) do { _Pragma("unroll") for (int n = 0; n < 2; ++n) _Pragma("unroll") for (int k = 0; k < 2; ++k) dst[n][k] = *(const PG8_LAS bf16x8*)(lds + PG8_SB(b, h) + boff + n * 2048 + k * 1024); } while (0)
; #define PG8_MMA(ai, bj, At, Bt) do { __builtin_amdgcn_s_setprio(1); _Pragma("unroll") for (int m = 0; m < 4; ++m) _Pragma("unroll") for (int n = 0; n < 2; ++n) _Pragma("unroll") for (int k = 0; k < 2; ++k) \
;         acc[ai][bj][m][n] = __builtin_amdgcn_mfma_f32_16x16x32_bf16(Bt[n][k], At[m][k], acc[ai][bj][m][n], 0, 0, 0); __builtin_amdgcn_s_setprio(0); } while (0)
; #define PG8_WAIT_V(n) asm volatile("s_waitcnt vmcnt(" #n ")" ::: "memory")
; #define PG8_WAIT_L(n) asm volatile("s_waitcnt lgkmcnt(" #n ")" ::: "memory")
; #define PG8_BAR __builtin_amdgcn_s_barrier()
; #define PG8_SCHED __builtin_amdgcn_sched_barrier(0)
; template <class Epi, class Sched, bool ALIGN_EPI = false, bool SP2 = false>
; __device__ __forceinline__ void gemm_phase(PG8_LAS unsigned char* lds, const Gemm g, const Sched& S, const Epi& E) {
;     ...
;         for (int t = 0; t < nt; t += 2) {
;             const bool last = (t == nt - 2);
;             const char* a1 = cA + (size_t)(t + 1) * kstep;
;             const char* a2 = last ? nA : cA + (size_t)(t + 2) * kstep; const char* b2 = last ? nB : cB + (size_t)(t + 2) * kstep;
;             const char* a3 = a2 + kstep; const char* b3 = b2 + kstep;
;             if (last && has_next) S.a_ready(nxt);
;             if constexpr (SP2) {
;             PG8_LDB(B0, 0, 0); PG8_LDB(B1, 0, 1); PG8_SCHED; PG8_LDA(At, 0, 0); PG8_STAGE(PG8_SA(1, 1), a1 + hstep, voffA);
;             PG8_WAIT_V(8); PG8_WAIT_L(0); PG8_BAR; PG8_MMA(0, 0, At, B0); PG8_MMA(0, 1, At, B1); PG8_BAR; PG8_SCHED;
;             PG8_LDA(At, 0, 1); PG8_STAGE(PG8_SB(0, 0), b2, voffB); PG8_STAGE(PG8_SB(0, 1), b2 + hstep, voffB); PG8_STAGE(PG8_SA(0, 0), a2, voffA);
.LBB0_639:
	s_add_i32 s28, s22, 2
	s_add_u32 s29, s0, 0x80
	s_addc_u32 s23, s1, 0
	s_add_i32 s56, 0, 0x10000
	s_cmp_eq_u32 s15, s22
	s_cselect_b32 s23, s7, s23
	s_cselect_b32 s22, s6, s29
	v_add_u32_e32 v149, s56, v147
	s_cselect_b32 s49, s21, s25
	s_cselect_b32 s48, s20, s24
	s_add_i32 s29, 0, 0x14000
	ds_read_b128 v[142:145], v149
	ds_read_b128 v[150:153], v149 offset:1024
	ds_read_b128 v[158:161], v149 offset:2048
	ds_read_b128 v[162:165], v149 offset:3072
	v_add_u32_e32 v149, s29, v147
	ds_read_b128 v[166:169], v149
	ds_read_b128 v[170:173], v149 offset:1024
	ds_read_b128 v[174:177], v149 offset:2048
	ds_read_b128 v[178:181], v149 offset:3072
	v_lshl_add_u64 v[234:235], s[0:1], 0, v[138:139]
	s_add_i32 m0, s71, 0xc000
	ds_read_b128 v[198:201], v148
	ds_read_b128 v[202:205], v148 offset:1024
	ds_read_b128 v[206:209], v148 offset:2048
	ds_read_b128 v[210:213], v148 offset:3072
	ds_read_b128 v[214:217], v148 offset:4096
	ds_read_b128 v[218:221], v148 offset:5120
	ds_read_b128 v[222:225], v148 offset:6144
	ds_read_b128 v[226:229], v148 offset:7168
	global_load_lds_dwordx4 v[234:235], off
	v_lshl_add_u64 v[234:235], s[0:1], 0, v[140:141]
	s_add_i32 m0, s71, 0xe000
	s_nop 0
	global_load_lds_dwordx4 v[234:235], off
	s_waitcnt vmcnt(8)
	s_waitcnt lgkmcnt(0)
	s_barrier
	s_setprio 1
	v_mfma_f32_16x16x32_bf16 v[126:129], v[142:145], v[198:201], v[126:129]
	v_mfma_f32_16x16x32_bf16 v[122:125], v[158:161], v[198:201], v[122:125]
	v_mfma_f32_16x16x32_bf16 v[108:111], v[142:145], v[206:209], v[108:111]
	v_mfma_f32_16x16x32_bf16 v[104:107], v[158:161], v[206:209], v[104:107]
	v_mfma_f32_16x16x32_bf16 v[92:95], v[142:145], v[214:217], v[92:95]
	v_mfma_f32_16x16x32_bf16 v[88:91], v[158:161], v[214:217], v[88:91]
	v_mfma_f32_16x16x32_bf16 v[76:79], v[142:145], v[222:225], v[76:79]
	v_mfma_f32_16x16x32_bf16 v[72:75], v[158:161], v[222:225], v[72:75]
	v_mfma_f32_16x16x32_bf16 v[126:129], v[150:153], v[202:205], v[126:129]
	v_mfma_f32_16x16x32_bf16 v[122:125], v[162:165], v[202:205], v[122:125]
	v_mfma_f32_16x16x32_bf16 v[108:111], v[150:153], v[210:213], v[108:111]
	v_mfma_f32_16x16x32_bf16 v[104:107], v[162:165], v[210:213], v[104:107]
	v_mfma_f32_16x16x32_bf16 v[92:95], v[150:153], v[218:221], v[92:95]
	v_mfma_f32_16x16x32_bf16 v[88:91], v[162:165], v[218:221], v[88:91]
	v_mfma_f32_16x16x32_bf16 v[76:79], v[150:153], v[226:229], v[76:79]
	v_mfma_f32_16x16x32_bf16 v[72:75], v[162:165], v[226:229], v[72:75]
	v_mfma_f32_16x16x32_bf16 v[118:121], v[166:169], v[198:201], v[118:121]
	v_mfma_f32_16x16x32_bf16 v[114:117], v[174:177], v[198:201], v[114:117]
	v_mfma_f32_16x16x32_bf16 v[100:103], v[166:169], v[206:209], v[100:103]
	v_mfma_f32_16x16x32_bf16 v[96:99], v[174:177], v[206:209], v[96:99]
	v_mfma_f32_16x16x32_bf16 v[84:87], v[166:169], v[214:217], v[84:87]
	v_mfma_f32_16x16x32_bf16 v[80:83], v[174:177], v[214:217], v[80:83]
	v_mfma_f32_16x16x32_bf16 v[68:71], v[166:169], v[222:225], v[68:71]
	v_mfma_f32_16x16x32_bf16 v[64:67], v[174:177], v[222:225], v[64:67]
	v_mfma_f32_16x16x32_bf16 v[118:121], v[170:173], v[202:205], v[118:121]
	v_mfma_f32_16x16x32_bf16 v[114:117], v[178:181], v[202:205], v[114:117]
	v_mfma_f32_16x16x32_bf16 v[100:103], v[170:173], v[210:213], v[100:103]
	v_mfma_f32_16x16x32_bf16 v[96:99], v[178:181], v[210:213], v[96:99]
	v_mfma_f32_16x16x32_bf16 v[84:87], v[170:173], v[218:221], v[84:87]
	v_mfma_f32_16x16x32_bf16 v[80:83], v[178:181], v[218:221], v[80:83]
	v_mfma_f32_16x16x32_bf16 v[68:71], v[170:173], v[226:229], v[68:71]
	v_mfma_f32_16x16x32_bf16 v[64:67], v[178:181], v[226:229], v[64:67]
	s_setprio 0
	s_barrier
	s_add_i32 s56, s56, s51
	v_lshl_add_u64 v[234:235], s[48:49], 0, v[134:135]
	s_mov_b32 m0, s56
	ds_read_b128 v[198:201], v148 offset:16384
	ds_read_b128 v[202:205], v148 offset:17408
	ds_read_b128 v[206:209], v148 offset:18432
	ds_read_b128 v[210:213], v148 offset:19456
	ds_read_b128 v[214:217], v148 offset:20480
	ds_read_b128 v[218:221], v148 offset:21504
	ds_read_b128 v[222:225], v148 offset:22528
	ds_read_b128 v[226:229], v148 offset:23552
	global_load_lds_dwordx4 v[234:235], off
	s_add_i32 m0, s56, 0x2000
	v_lshl_add_u64 v[236:237], s[48:49], 0, v[130:131]
	s_add_u32 s48, s48, s10
	s_addc_u32 s49, s49, s11
	s_add_i32 s29, s29, s51
	global_load_lds_dwordx4 v[236:237], off
	v_lshl_add_u64 v[238:239], s[48:49], 0, v[134:135]
	s_mov_b32 m0, s29
	v_lshl_add_u64 v[240:241], s[48:49], 0, v[130:131]
	global_load_lds_dwordx4 v[238:239], off
	s_add_i32 m0, s29, 0x2000
	v_lshl_add_u64 v[242:243], s[22:23], 0, v[136:137]
	global_load_lds_dwordx4 v[240:241], off
	s_mov_b32 m0, s71
	v_lshl_add_u64 v[244:245], s[22:23], 0, v[132:133]
	global_load_lds_dwordx4 v[242:243], off
	s_mov_b32 m0, s77
	s_nop 0
	global_load_lds_dwordx4 v[244:245], off
	s_waitcnt vmcnt(8)
	s_waitcnt lgkmcnt(0)
	s_barrier
; #define PG8_STAGE(bufoff, gbase, voff) do { _Pragma("unroll") for (int _i = 0; _i < 2; ++_i) \
;         __builtin_amdgcn_global_load_lds((const unsigned*)((const char*)(gbase) + (voff)[_i]), (PG8_LAS unsigned*)(lds + (bufoff) + ldsw + _i * 8192), 16, 0, 0); } while (0)
; #define PG8_LDA(dst, b, h) do { _Pragma("unroll") for (int m = 0; m < 4; ++m) _Pragma("unroll") for (int k = 0; k < 2; ++k) dst[m][k] = *(const PG8_LAS bf16x8*)(lds + PG8_SA(b, h) + aoff + m * 2048 + k * 1024); } while (0)
; #define PG8_LDB(dst, b, h) do { _Pragma("unroll") for (int n = 0; n < 2; ++n) _Pragma("unroll") for (int k = 0; k < 2; ++k) dst[n][k] = *(const PG8_LAS bf16x8*)(lds + PG8_SB(b, h) + boff + n * 2048 + k * 1024); } while (0)
; #define PG8_MMA(ai, bj, At, Bt) do { __builtin_amdgcn_s_setprio(1); _Pragma("unroll") for (int m = 0; m < 4; ++m) _Pragma("unroll") for (int n = 0; n < 2; ++n) _Pragma("unroll") for (int k = 0; k < 2; ++k) \
;         acc[ai][bj][m][n] = __builtin_amdgcn_mfma_f32_16x16x32_bf16(Bt[n][k], At[m][k], acc[ai][bj][m][n], 0, 0, 0); __builtin_amdgcn_s_setprio(0); } while (0)
; #define PG8_WAIT_V(n) asm volatile("s_waitcnt vmcnt(" #n ")" ::: "memory")
; #define PG8_WAIT_L(n) asm volatile("s_waitcnt lgkmcnt(" #n ")" ::: "memory")
; #define PG8_BAR __builtin_amdgcn_s_barrier()
; #define PG8_SCHED __builtin_amdgcn_sched_barrier(0)
; template <class Epi, class Sched, bool ALIGN_EPI = false, bool SP2 = false>
; __device__ __forceinline__ void gemm_phase(PG8_LAS unsigned char* lds, const Gemm g, const Sched& S, const Epi& E) {
;     ...
;             PG8_WAIT_V(8); PG8_WAIT_L(0); PG8_BAR; PG8_MMA(1, 0, At, B0); PG8_MMA(1, 1, At, B1); PG8_BAR; PG8_SCHED;
;             PG8_LDB(B0, 1, 0); PG8_LDB(B1, 1, 1); PG8_SCHED; PG8_LDA(At, 1, 0); PG8_STAGE(PG8_SA(0, 1), a2 + hstep, voffA);
;             PG8_WAIT_V(8); PG8_WAIT_L(0); PG8_BAR; PG8_MMA(0, 0, At, B0); PG8_MMA(0, 1, At, B1); PG8_BAR; PG8_SCHED;
	s_setprio 1
	v_mfma_f32_16x16x32_bf16 v[60:63], v[142:145], v[198:201], v[60:63]
	v_mfma_f32_16x16x32_bf16 v[56:59], v[158:161], v[198:201], v[56:59]
	v_mfma_f32_16x16x32_bf16 v[44:47], v[142:145], v[206:209], v[44:47]
	v_mfma_f32_16x16x32_bf16 v[40:43], v[158:161], v[206:209], v[40:43]
	v_mfma_f32_16x16x32_bf16 v[28:31], v[142:145], v[214:217], v[28:31]
	v_mfma_f32_16x16x32_bf16 v[24:27], v[158:161], v[214:217], v[24:27]
	v_mfma_f32_16x16x32_bf16 v[12:15], v[142:145], v[222:225], v[12:15]
	v_mfma_f32_16x16x32_bf16 v[8:11], v[158:161], v[222:225], v[8:11]
	v_mfma_f32_16x16x32_bf16 v[60:63], v[150:153], v[202:205], v[60:63]
	v_mfma_f32_16x16x32_bf16 v[56:59], v[162:165], v[202:205], v[56:59]
	v_mfma_f32_16x16x32_bf16 v[44:47], v[150:153], v[210:213], v[44:47]
	v_mfma_f32_16x16x32_bf16 v[40:43], v[162:165], v[210:213], v[40:43]
	v_mfma_f32_16x16x32_bf16 v[28:31], v[150:153], v[218:221], v[28:31]
	v_mfma_f32_16x16x32_bf16 v[24:27], v[162:165], v[218:221], v[24:27]
	v_mfma_f32_16x16x32_bf16 v[12:15], v[150:153], v[226:229], v[12:15]
	v_mfma_f32_16x16x32_bf16 v[8:11], v[162:165], v[226:229], v[8:11]
	v_mfma_f32_16x16x32_bf16 v[52:55], v[166:169], v[198:201], v[52:55]
	v_mfma_f32_16x16x32_bf16 v[48:51], v[174:177], v[198:201], v[48:51]
	v_mfma_f32_16x16x32_bf16 v[36:39], v[166:169], v[206:209], v[36:39]
	v_mfma_f32_16x16x32_bf16 v[32:35], v[174:177], v[206:209], v[32:35]
	v_mfma_f32_16x16x32_bf16 v[20:23], v[166:169], v[214:217], v[20:23]
	v_mfma_f32_16x16x32_bf16 v[16:19], v[174:177], v[214:217], v[16:19]
	v_mfma_f32_16x16x32_bf16 v[4:7], v[166:169], v[222:225], v[4:7]
	v_mfma_f32_16x16x32_bf16 v[0:3], v[174:177], v[222:225], v[0:3]
	v_mfma_f32_16x16x32_bf16 v[52:55], v[170:173], v[202:205], v[52:55]
	v_mfma_f32_16x16x32_bf16 v[48:51], v[178:181], v[202:205], v[48:51]
	v_mfma_f32_16x16x32_bf16 v[36:39], v[170:173], v[210:213], v[36:39]
	v_mfma_f32_16x16x32_bf16 v[32:35], v[178:181], v[210:213], v[32:35]
	v_mfma_f32_16x16x32_bf16 v[20:23], v[170:173], v[218:221], v[20:23]
	v_mfma_f32_16x16x32_bf16 v[16:19], v[178:181], v[218:221], v[16:19]
	v_mfma_f32_16x16x32_bf16 v[4:7], v[170:173], v[226:229], v[4:7]
	v_mfma_f32_16x16x32_bf16 v[0:3], v[178:181], v[226:229], v[0:3]
	s_setprio 0
	s_barrier
	s_add_i32 s29, 0, 0x18000
	v_add_u32_e32 v149, s29, v147
	s_add_i32 s48, 0, 0x1c000
	ds_read_b128 v[142:145], v149
	ds_read_b128 v[150:153], v149 offset:1024
	ds_read_b128 v[158:161], v149 offset:2048
	ds_read_b128 v[162:165], v149 offset:3072
	v_add_u32_e32 v149, s48, v147
	ds_read_b128 v[166:169], v149
	ds_read_b128 v[170:173], v149 offset:1024
	ds_read_b128 v[174:177], v149 offset:2048
	ds_read_b128 v[178:181], v149 offset:3072
	s_add_u32 s22, s22, s10
	s_addc_u32 s23, s23, s11
	s_mov_b32 m0, s64
	v_lshl_add_u64 v[246:247], s[22:23], 0, v[136:137]
	ds_read_b128 v[198:201], v148 offset:32768
	ds_read_b128 v[202:205], v148 offset:33792
	ds_read_b128 v[206:209], v148 offset:34816
	ds_read_b128 v[210:213], v148 offset:35840
	ds_read_b128 v[214:217], v148 offset:36864
	ds_read_b128 v[218:221], v148 offset:37888
	ds_read_b128 v[222:225], v148 offset:38912
	ds_read_b128 v[226:229], v148 offset:39936
	global_load_lds_dwordx4 v[246:247], off
	v_lshl_add_u64 v[246:247], s[22:23], 0, v[132:133]
	s_mov_b32 m0, s14
	s_nop 0
	global_load_lds_dwordx4 v[246:247], off
	s_waitcnt vmcnt(8)
	s_waitcnt lgkmcnt(0)
	s_barrier
	s_setprio 1
	v_mfma_f32_16x16x32_bf16 v[126:129], v[142:145], v[198:201], v[126:129]
	v_mfma_f32_16x16x32_bf16 v[122:125], v[158:161], v[198:201], v[122:125]
	v_mfma_f32_16x16x32_bf16 v[108:111], v[142:145], v[206:209], v[108:111]
	v_mfma_f32_16x16x32_bf16 v[104:107], v[158:161], v[206:209], v[104:107]
	v_mfma_f32_16x16x32_bf16 v[92:95], v[142:145], v[214:217], v[92:95]
	v_mfma_f32_16x16x32_bf16 v[88:91], v[158:161], v[214:217], v[88:91]
	v_mfma_f32_16x16x32_bf16 v[76:79], v[142:145], v[222:225], v[76:79]
	v_mfma_f32_16x16x32_bf16 v[72:75], v[158:161], v[222:225], v[72:75]
	v_mfma_f32_16x16x32_bf16 v[126:129], v[150:153], v[202:205], v[126:129]
	v_mfma_f32_16x16x32_bf16 v[122:125], v[162:165], v[202:205], v[122:125]
	v_mfma_f32_16x16x32_bf16 v[108:111], v[150:153], v[210:213], v[108:111]
	v_mfma_f32_16x16x32_bf16 v[104:107], v[162:165], v[210:213], v[104:107]
	v_mfma_f32_16x16x32_bf16 v[92:95], v[150:153], v[218:221], v[92:95]
	v_mfma_f32_16x16x32_bf16 v[88:91], v[162:165], v[218:221], v[88:91]
	v_mfma_f32_16x16x32_bf16 v[76:79], v[150:153], v[226:229], v[76:79]
	v_mfma_f32_16x16x32_bf16 v[72:75], v[162:165], v[226:229], v[72:75]
	v_mfma_f32_16x16x32_bf16 v[118:121], v[166:169], v[198:201], v[118:121]
	v_mfma_f32_16x16x32_bf16 v[114:117], v[174:177], v[198:201], v[114:117]
	v_mfma_f32_16x16x32_bf16 v[100:103], v[166:169], v[206:209], v[100:103]
	v_mfma_f32_16x16x32_bf16 v[96:99], v[174:177], v[206:209], v[96:99]
	v_mfma_f32_16x16x32_bf16 v[84:87], v[166:169], v[214:217], v[84:87]
	v_mfma_f32_16x16x32_bf16 v[80:83], v[174:177], v[214:217], v[80:83]
	v_mfma_f32_16x16x32_bf16 v[68:71], v[166:169], v[222:225], v[68:71]
	v_mfma_f32_16x16x32_bf16 v[64:67], v[174:177], v[222:225], v[64:67]
	v_mfma_f32_16x16x32_bf16 v[118:121], v[170:173], v[202:205], v[118:121]
	v_mfma_f32_16x16x32_bf16 v[114:117], v[178:181], v[202:205], v[114:117]
	v_mfma_f32_16x16x32_bf16 v[100:103], v[170:173], v[210:213], v[100:103]
	v_mfma_f32_16x16x32_bf16 v[96:99], v[178:181], v[210:213], v[96:99]
	v_mfma_f32_16x16x32_bf16 v[84:87], v[170:173], v[218:221], v[84:87]
	v_mfma_f32_16x16x32_bf16 v[80:83], v[178:181], v[218:221], v[80:83]
	v_mfma_f32_16x16x32_bf16 v[68:71], v[170:173], v[226:229], v[68:71]
	v_mfma_f32_16x16x32_bf16 v[64:67], v[178:181], v[226:229], v[64:67]
	s_setprio 0
	s_barrier
; #define PG8_STAGE(bufoff, gbase, voff) do { _Pragma("unroll") for (int _i = 0; _i < 2; ++_i) \
;         __builtin_amdgcn_global_load_lds((const unsigned*)((const char*)(gbase) + (voff)[_i]), (PG8_LAS unsigned*)(lds + (bufoff) + ldsw + _i * 8192), 16, 0, 0); } while (0)
; #define PG8_LDA(dst, b, h) do { _Pragma("unroll") for (int m = 0; m < 4; ++m) _Pragma("unroll") for (int k = 0; k < 2; ++k) dst[m][k] = *(const PG8_LAS bf16x8*)(lds + PG8_SA(b, h) + aoff + m * 2048 + k * 1024); } while (0)
; #define PG8_MMA(ai, bj, At, Bt) do { __builtin_amdgcn_s_setprio(1); _Pragma("unroll") for (int m = 0; m < 4; ++m) _Pragma("unroll") for (int n = 0; n < 2; ++n) _Pragma("unroll") for (int k = 0; k < 2; ++k) \
;         acc[ai][bj][m][n] = __builtin_amdgcn_mfma_f32_16x16x32_bf16(Bt[n][k], At[m][k], acc[ai][bj][m][n], 0, 0, 0); __builtin_amdgcn_s_setprio(0); } while (0)
; #define PG8_WAIT_V(n) asm volatile("s_waitcnt vmcnt(" #n ")" ::: "memory")
; #define PG8_WAIT_L(n) asm volatile("s_waitcnt lgkmcnt(" #n ")" ::: "memory")
; #define PG8_BAR __builtin_amdgcn_s_barrier()
; #define PG8_SCHED __builtin_amdgcn_sched_barrier(0)
; template <class Epi, class Sched, bool ALIGN_EPI = false, bool SP2 = false>
; __device__ __forceinline__ void gemm_phase(PG8_LAS unsigned char* lds, const Gemm g, const Sched& S, const Epi& E) {
;     ...
;             PG8_LDA(At, 1, 1); PG8_STAGE(PG8_SB(1, 0), b3, voffB); PG8_STAGE(PG8_SB(1, 1), b3 + hstep, voffB); PG8_STAGE(PG8_SA(1, 0), a3, voffA);
;             PG8_WAIT_V(8); PG8_WAIT_L(0); PG8_BAR; PG8_MMA(1, 0, At, B0); PG8_MMA(1, 1, At, B1); PG8_BAR; PG8_SCHED;
	s_add_i32 s22, s29, s51
	v_lshl_add_u64 v[234:235], v[234:235], 0, s[52:53]
	s_mov_b32 m0, s22
	ds_read_b128 v[198:201], v148 offset:49152
	ds_read_b128 v[202:205], v148 offset:50176
	ds_read_b128 v[206:209], v148 offset:51200
	ds_read_b128 v[210:213], v148 offset:52224
	ds_read_b128 v[214:217], v148 offset:53248
	ds_read_b128 v[218:221], v148 offset:54272
	ds_read_b128 v[222:225], v148 offset:55296
	ds_read_b128 v[226:229], v148 offset:56320
	global_load_lds_dwordx4 v[234:235], off
	v_lshl_add_u64 v[234:235], v[236:237], 0, s[52:53]
	s_add_i32 m0, s22, 0x2000
	s_add_i32 s22, s48, s51
	global_load_lds_dwordx4 v[234:235], off
	v_lshl_add_u64 v[234:235], v[238:239], 0, s[52:53]
	s_mov_b32 m0, s22
	s_nop 0
	global_load_lds_dwordx4 v[234:235], off
	v_lshl_add_u64 v[234:235], v[240:241], 0, s[52:53]
	s_add_i32 m0, s22, 0x2000
	s_nop 0
	global_load_lds_dwordx4 v[234:235], off
	v_lshl_add_u64 v[234:235], v[242:243], 0, s[52:53]
	s_mov_b32 m0, s70
	s_nop 0
	global_load_lds_dwordx4 v[234:235], off
	v_lshl_add_u64 v[234:235], v[244:245], 0, s[52:53]
	s_mov_b32 m0, s79
	s_nop 0
	global_load_lds_dwordx4 v[234:235], off
	s_waitcnt vmcnt(8)
	s_waitcnt lgkmcnt(0)
	s_barrier
	s_setprio 1
	v_mfma_f32_16x16x32_bf16 v[60:63], v[142:145], v[198:201], v[60:63]
	v_mfma_f32_16x16x32_bf16 v[56:59], v[158:161], v[198:201], v[56:59]
	v_mfma_f32_16x16x32_bf16 v[44:47], v[142:145], v[206:209], v[44:47]
	v_mfma_f32_16x16x32_bf16 v[40:43], v[158:161], v[206:209], v[40:43]
	v_mfma_f32_16x16x32_bf16 v[28:31], v[142:145], v[214:217], v[28:31]
	v_mfma_f32_16x16x32_bf16 v[24:27], v[158:161], v[214:217], v[24:27]
	v_mfma_f32_16x16x32_bf16 v[12:15], v[142:145], v[222:225], v[12:15]
	v_mfma_f32_16x16x32_bf16 v[8:11], v[158:161], v[222:225], v[8:11]
	v_mfma_f32_16x16x32_bf16 v[60:63], v[150:153], v[202:205], v[60:63]
	v_mfma_f32_16x16x32_bf16 v[56:59], v[162:165], v[202:205], v[56:59]
	v_mfma_f32_16x16x32_bf16 v[44:47], v[150:153], v[210:213], v[44:47]
	v_mfma_f32_16x16x32_bf16 v[40:43], v[162:165], v[210:213], v[40:43]
	v_mfma_f32_16x16x32_bf16 v[28:31], v[150:153], v[218:221], v[28:31]
	v_mfma_f32_16x16x32_bf16 v[24:27], v[162:165], v[218:221], v[24:27]
	v_mfma_f32_16x16x32_bf16 v[12:15], v[150:153], v[226:229], v[12:15]
	v_mfma_f32_16x16x32_bf16 v[8:11], v[162:165], v[226:229], v[8:11]
	v_mfma_f32_16x16x32_bf16 v[52:55], v[166:169], v[198:201], v[52:55]
	v_mfma_f32_16x16x32_bf16 v[48:51], v[174:177], v[198:201], v[48:51]
	v_mfma_f32_16x16x32_bf16 v[36:39], v[166:169], v[206:209], v[36:39]
	v_mfma_f32_16x16x32_bf16 v[32:35], v[174:177], v[206:209], v[32:35]
	v_mfma_f32_16x16x32_bf16 v[20:23], v[166:169], v[214:217], v[20:23]
	v_mfma_f32_16x16x32_bf16 v[16:19], v[174:177], v[214:217], v[16:19]
	v_mfma_f32_16x16x32_bf16 v[4:7], v[166:169], v[222:225], v[4:7]
	v_mfma_f32_16x16x32_bf16 v[0:3], v[174:177], v[222:225], v[0:3]
	v_mfma_f32_16x16x32_bf16 v[52:55], v[170:173], v[202:205], v[52:55]
	v_mfma_f32_16x16x32_bf16 v[48:51], v[178:181], v[202:205], v[48:51]
	v_mfma_f32_16x16x32_bf16 v[36:39], v[170:173], v[210:213], v[36:39]
	v_mfma_f32_16x16x32_bf16 v[32:35], v[178:181], v[210:213], v[32:35]
	v_mfma_f32_16x16x32_bf16 v[20:23], v[170:173], v[218:221], v[20:23]
	v_mfma_f32_16x16x32_bf16 v[16:19], v[178:181], v[218:221], v[16:19]
	v_mfma_f32_16x16x32_bf16 v[4:7], v[170:173], v[226:229], v[4:7]
	v_mfma_f32_16x16x32_bf16 v[0:3], v[178:181], v[226:229], v[0:3]
	s_setprio 0
	s_barrier
	s_add_u32 s0, s0, 0x100
	s_addc_u32 s1, s1, 0
	s_add_u32 s24, s24, 0x100
	s_addc_u32 s25, s25, 0
	s_cmp_ge_i32 s28, s80
	s_mov_b32 s22, s28
	s_cbranch_scc0 .LBB0_639

; #define PG8_STAGE(bufoff, gbase, voff) do { _Pragma("unroll") for (int _i = 0; _i < 2; ++_i) \
;         __builtin_amdgcn_global_load_lds((const unsigned*)((const char*)(gbase) + (voff)[_i]), (PG8_LAS unsigned*)(lds + (bufoff) + ldsw + _i * 8192), 16, 0, 0); } while (0)
; #define PG8_LDA(dst, b, h) do { _Pragma("unroll") for (int m = 0; m < 4; ++m) _Pragma("unroll") for (int k = 0; k < 2; ++k) dst[m][k] = *(const PG8_LAS bf16x8*)(lds + PG8_SA(b, h) + aoff + m * 2048 + k * 1024); } while (0)
; #define PG8_LDB(dst, b, h) do { _Pragma("unroll") for (int n = 0; n < 2; ++n) _Pragma("unroll") for (int k = 0; k < 2; ++k) dst[n][k] = *(const PG8_LAS bf16x8*)(lds + PG8_SB(b, h) + boff + n * 2048 + k * 1024); } while (0)
; #define PG8_MMA(ai, bj, At, Bt) do { __builtin_amdgcn_s_setprio(1); _Pragma("unroll") for (int m = 0; m < 4; ++m) _Pragma("unroll") for (int n = 0; n < 2; ++n) _Pragma("unroll") for (int k = 0; k < 2; ++k) \
;         acc[ai][bj][m][n] = __builtin_amdgcn_mfma_f32_16x16x32_bf16(Bt[n][k], At[m][k], acc[ai][bj][m][n], 0, 0, 0); __builtin_amdgcn_s_setprio(0); } while (0)
; #define PG8_WAIT_V(n) asm volatile("s_waitcnt vmcnt(" #n ")" ::: "memory")
; #define PG8_WAIT_L(n) asm volatile("s_waitcnt lgkmcnt(" #n ")" ::: "memory")
; #define PG8_BAR __builtin_amdgcn_s_barrier()
; #define PG8_SCHED __builtin_amdgcn_sched_barrier(0)
; template <class Epi, class Sched, bool ALIGN_EPI = false, bool SP2 = false>
; __device__ __forceinline__ void gemm_phase(PG8_LAS unsigned char* lds, const Gemm g, const Sched& S, const Epi& E) {
;     ...
;         for (int t = 0; t < nt; t += 2) {
;             const bool last = (t == nt - 2);
;             const char* a1 = cA + (size_t)(t + 1) * kstep;
;             const char* a2 = last ? nA : cA + (size_t)(t + 2) * kstep; const char* b2 = last ? nB : cB + (size_t)(t + 2) * kstep;
;             const char* a3 = a2 + kstep; const char* b3 = b2 + kstep;
;             if (last && has_next) S.a_ready(nxt);
;             if constexpr (SP2) {
;             PG8_LDB(B0, 0, 0); PG8_LDB(B1, 0, 1); PG8_SCHED; PG8_LDA(At, 0, 0); PG8_STAGE(PG8_SA(1, 1), a1 + hstep, voffA);
;             PG8_WAIT_V(8); PG8_WAIT_L(0); PG8_BAR; PG8_MMA(0, 0, At, B0); PG8_MMA(0, 1, At, B1); PG8_BAR; PG8_SCHED;
;             PG8_LDA(At, 0, 1); PG8_STAGE(PG8_SB(0, 0), b2, voffB); PG8_STAGE(PG8_SB(0, 1), b2 + hstep, voffB); PG8_STAGE(PG8_SA(0, 0), a2, voffA);
.LBB0_754:
	s_add_i32 s80, s22, 2
	s_add_u32 s81, s20, 0x80
	s_addc_u32 s23, s21, 0
	s_add_i32 vcc_lo, 0, 0x10000
	s_cmp_eq_u32 s65, s22
	s_cselect_b32 s23, s7, s23
	s_cselect_b32 s22, s6, s81
	v_add_u32_e32 v152, vcc_lo, v149
	s_cselect_b32 s83, s19, s79
	s_cselect_b32 s82, s18, s77
	s_add_i32 s81, 0, 0x14000
	ds_read_b128 v[136:139], v152
	ds_read_b128 v[140:143], v152 offset:1024
	ds_read_b128 v[144:147], v152 offset:2048
	ds_read_b128 v[158:161], v152 offset:3072
	v_add_u32_e32 v152, s81, v149
	ds_read_b128 v[162:165], v152
	ds_read_b128 v[166:169], v152 offset:1024
	ds_read_b128 v[170:173], v152 offset:2048
	ds_read_b128 v[174:177], v152 offset:3072
	v_lshl_add_u64 v[152:153], s[20:21], 0, v[132:133]
	s_add_i32 m0, s50, 0xc000
	ds_read_b128 v[178:181], v151
	ds_read_b128 v[198:201], v151 offset:1024
	ds_read_b128 v[202:205], v151 offset:2048
	ds_read_b128 v[206:209], v151 offset:3072
	ds_read_b128 v[210:213], v151 offset:4096
	ds_read_b128 v[214:217], v151 offset:5120
	ds_read_b128 v[218:221], v151 offset:6144
	ds_read_b128 v[222:225], v151 offset:7168
	global_load_lds_dwordx4 v[152:153], off
	v_lshl_add_u64 v[152:153], s[20:21], 0, v[134:135]
	s_add_i32 m0, s50, 0xe000
	s_nop 0
	global_load_lds_dwordx4 v[152:153], off
	s_waitcnt vmcnt(8)
	s_waitcnt lgkmcnt(0)
	s_barrier
	s_setprio 1
	v_mfma_f32_16x16x32_bf16 v[126:129], v[136:139], v[178:181], v[126:129]
	v_mfma_f32_16x16x32_bf16 v[122:125], v[144:147], v[178:181], v[122:125]
	v_mfma_f32_16x16x32_bf16 v[118:121], v[136:139], v[202:205], v[118:121]
	v_mfma_f32_16x16x32_bf16 v[114:117], v[144:147], v[202:205], v[114:117]
	v_mfma_f32_16x16x32_bf16 v[104:107], v[136:139], v[210:213], v[104:107]
	v_mfma_f32_16x16x32_bf16 v[96:99], v[144:147], v[210:213], v[96:99]
	v_mfma_f32_16x16x32_bf16 v[88:91], v[136:139], v[218:221], v[88:91]
	v_mfma_f32_16x16x32_bf16 v[80:83], v[144:147], v[218:221], v[80:83]
	v_mfma_f32_16x16x32_bf16 v[126:129], v[140:143], v[198:201], v[126:129]
	v_mfma_f32_16x16x32_bf16 v[122:125], v[158:161], v[198:201], v[122:125]
	v_mfma_f32_16x16x32_bf16 v[118:121], v[140:143], v[206:209], v[118:121]
	v_mfma_f32_16x16x32_bf16 v[114:117], v[158:161], v[206:209], v[114:117]
	v_mfma_f32_16x16x32_bf16 v[104:107], v[140:143], v[214:217], v[104:107]
	v_mfma_f32_16x16x32_bf16 v[96:99], v[158:161], v[214:217], v[96:99]
	v_mfma_f32_16x16x32_bf16 v[88:91], v[140:143], v[222:225], v[88:91]
	v_mfma_f32_16x16x32_bf16 v[80:83], v[158:161], v[222:225], v[80:83]
	v_mfma_f32_16x16x32_bf16 v[108:111], v[162:165], v[178:181], v[108:111]
	v_mfma_f32_16x16x32_bf16 v[100:103], v[170:173], v[178:181], v[100:103]
	v_mfma_f32_16x16x32_bf16 v[92:95], v[162:165], v[202:205], v[92:95]
	v_mfma_f32_16x16x32_bf16 v[84:87], v[170:173], v[202:205], v[84:87]
	v_mfma_f32_16x16x32_bf16 v[76:79], v[162:165], v[210:213], v[76:79]
	v_mfma_f32_16x16x32_bf16 v[72:75], v[170:173], v[210:213], v[72:75]
	v_mfma_f32_16x16x32_bf16 v[68:71], v[162:165], v[218:221], v[68:71]
	v_mfma_f32_16x16x32_bf16 v[64:67], v[170:173], v[218:221], v[64:67]
	v_mfma_f32_16x16x32_bf16 v[108:111], v[166:169], v[198:201], v[108:111]
	v_mfma_f32_16x16x32_bf16 v[100:103], v[174:177], v[198:201], v[100:103]
	v_mfma_f32_16x16x32_bf16 v[92:95], v[166:169], v[206:209], v[92:95]
	v_mfma_f32_16x16x32_bf16 v[84:87], v[174:177], v[206:209], v[84:87]
	v_mfma_f32_16x16x32_bf16 v[76:79], v[166:169], v[214:217], v[76:79]
	v_mfma_f32_16x16x32_bf16 v[72:75], v[174:177], v[214:217], v[72:75]
	v_mfma_f32_16x16x32_bf16 v[68:71], v[166:169], v[222:225], v[68:71]
	v_mfma_f32_16x16x32_bf16 v[64:67], v[174:177], v[222:225], v[64:67]
	s_setprio 0
	s_barrier
	s_add_i32 vcc_lo, vcc_lo, s3
	v_lshl_add_u64 v[152:153], s[82:83], 0, v[112:113]
	s_mov_b32 m0, vcc_lo
	ds_read_b128 v[178:181], v151 offset:16384
	ds_read_b128 v[198:201], v151 offset:17408
	ds_read_b128 v[202:205], v151 offset:18432
	ds_read_b128 v[206:209], v151 offset:19456
	ds_read_b128 v[210:213], v151 offset:20480
	ds_read_b128 v[214:217], v151 offset:21504
	ds_read_b128 v[218:221], v151 offset:22528
	ds_read_b128 v[222:225], v151 offset:23552
	global_load_lds_dwordx4 v[152:153], off
	s_add_i32 m0, vcc_lo, 0x2000
	v_lshl_add_u64 v[226:227], s[82:83], 0, v[130:131]
	s_add_u32 s82, s82, s8
	s_addc_u32 s83, s83, s9
	s_add_i32 s81, s81, s3
	global_load_lds_dwordx4 v[226:227], off
	v_lshl_add_u64 v[228:229], s[82:83], 0, v[112:113]
	s_mov_b32 m0, s81
	v_lshl_add_u64 v[234:235], s[82:83], 0, v[130:131]
	global_load_lds_dwordx4 v[228:229], off
	s_add_i32 m0, s81, 0x2000
	v_lshl_add_u64 v[236:237], s[22:23], 0, v[112:113]
	global_load_lds_dwordx4 v[234:235], off
	s_mov_b32 m0, s50
	v_lshl_add_u64 v[238:239], s[22:23], 0, v[130:131]
	global_load_lds_dwordx4 v[236:237], off
	s_mov_b32 m0, s51
	s_nop 0
	global_load_lds_dwordx4 v[238:239], off
	s_waitcnt vmcnt(8)
	s_waitcnt lgkmcnt(0)
	s_barrier
; #define PG8_STAGE(bufoff, gbase, voff) do { _Pragma("unroll") for (int _i = 0; _i < 2; ++_i) \
;         __builtin_amdgcn_global_load_lds((const unsigned*)((const char*)(gbase) + (voff)[_i]), (PG8_LAS unsigned*)(lds + (bufoff) + ldsw + _i * 8192), 16, 0, 0); } while (0)
; #define PG8_LDA(dst, b, h) do { _Pragma("unroll") for (int m = 0; m < 4; ++m) _Pragma("unroll") for (int k = 0; k < 2; ++k) dst[m][k] = *(const PG8_LAS bf16x8*)(lds + PG8_SA(b, h) + aoff + m * 2048 + k * 1024); } while (0)
; #define PG8_LDB(dst, b, h) do { _Pragma("unroll") for (int n = 0; n < 2; ++n) _Pragma("unroll") for (int k = 0; k < 2; ++k) dst[n][k] = *(const PG8_LAS bf16x8*)(lds + PG8_SB(b, h) + boff + n * 2048 + k * 1024); } while (0)
; #define PG8_MMA(ai, bj, At, Bt) do { __builtin_amdgcn_s_setprio(1); _Pragma("unroll") for (int m = 0; m < 4; ++m) _Pragma("unroll") for (int n = 0; n < 2; ++n) _Pragma("unroll") for (int k = 0; k < 2; ++k) \
;         acc[ai][bj][m][n] = __builtin_amdgcn_mfma_f32_16x16x32_bf16(Bt[n][k], At[m][k], acc[ai][bj][m][n], 0, 0, 0); __builtin_amdgcn_s_setprio(0); } while (0)
; #define PG8_WAIT_V(n) asm volatile("s_waitcnt vmcnt(" #n ")" ::: "memory")
; #define PG8_WAIT_L(n) asm volatile("s_waitcnt lgkmcnt(" #n ")" ::: "memory")
; #define PG8_BAR __builtin_amdgcn_s_barrier()
; #define PG8_SCHED __builtin_amdgcn_sched_barrier(0)
; template <class Epi, class Sched, bool ALIGN_EPI = false, bool SP2 = false>
; __device__ __forceinline__ void gemm_phase(PG8_LAS unsigned char* lds, const Gemm g, const Sched& S, const Epi& E) {
;     ...
;             PG8_WAIT_V(8); PG8_WAIT_L(0); PG8_BAR; PG8_MMA(1, 0, At, B0); PG8_MMA(1, 1, At, B1); PG8_BAR; PG8_SCHED;
;             PG8_LDB(B0, 1, 0); PG8_LDB(B1, 1, 1); PG8_SCHED; PG8_LDA(At, 1, 0); PG8_STAGE(PG8_SA(0, 1), a2 + hstep, voffA);
;             PG8_WAIT_V(8); PG8_WAIT_L(0); PG8_BAR; PG8_MMA(0, 0, At, B0); PG8_MMA(0, 1, At, B1); PG8_BAR; PG8_SCHED;
	s_setprio 1
	v_mfma_f32_16x16x32_bf16 v[60:63], v[136:139], v[178:181], v[60:63]
	v_mfma_f32_16x16x32_bf16 v[56:59], v[144:147], v[178:181], v[56:59]
	v_mfma_f32_16x16x32_bf16 v[52:55], v[136:139], v[202:205], v[52:55]
	v_mfma_f32_16x16x32_bf16 v[48:51], v[144:147], v[202:205], v[48:51]
	v_mfma_f32_16x16x32_bf16 v[40:43], v[136:139], v[210:213], v[40:43]
	v_mfma_f32_16x16x32_bf16 v[32:35], v[144:147], v[210:213], v[32:35]
	v_mfma_f32_16x16x32_bf16 v[24:27], v[136:139], v[218:221], v[24:27]
	v_mfma_f32_16x16x32_bf16 v[16:19], v[144:147], v[218:221], v[16:19]
	v_mfma_f32_16x16x32_bf16 v[60:63], v[140:143], v[198:201], v[60:63]
	v_mfma_f32_16x16x32_bf16 v[56:59], v[158:161], v[198:201], v[56:59]
	v_mfma_f32_16x16x32_bf16 v[52:55], v[140:143], v[206:209], v[52:55]
	v_mfma_f32_16x16x32_bf16 v[48:51], v[158:161], v[206:209], v[48:51]
	v_mfma_f32_16x16x32_bf16 v[40:43], v[140:143], v[214:217], v[40:43]
	v_mfma_f32_16x16x32_bf16 v[32:35], v[158:161], v[214:217], v[32:35]
	v_mfma_f32_16x16x32_bf16 v[24:27], v[140:143], v[222:225], v[24:27]
	v_mfma_f32_16x16x32_bf16 v[16:19], v[158:161], v[222:225], v[16:19]
	v_mfma_f32_16x16x32_bf16 v[44:47], v[162:165], v[178:181], v[44:47]
	v_mfma_f32_16x16x32_bf16 v[36:39], v[170:173], v[178:181], v[36:39]
	v_mfma_f32_16x16x32_bf16 v[28:31], v[162:165], v[202:205], v[28:31]
	v_mfma_f32_16x16x32_bf16 v[20:23], v[170:173], v[202:205], v[20:23]
	v_mfma_f32_16x16x32_bf16 v[12:15], v[162:165], v[210:213], v[12:15]
	v_mfma_f32_16x16x32_bf16 v[8:11], v[170:173], v[210:213], v[8:11]
	v_mfma_f32_16x16x32_bf16 v[4:7], v[162:165], v[218:221], v[4:7]
	v_mfma_f32_16x16x32_bf16 v[0:3], v[170:173], v[218:221], v[0:3]
	v_mfma_f32_16x16x32_bf16 v[44:47], v[166:169], v[198:201], v[44:47]
	v_mfma_f32_16x16x32_bf16 v[36:39], v[174:177], v[198:201], v[36:39]
	v_mfma_f32_16x16x32_bf16 v[28:31], v[166:169], v[206:209], v[28:31]
	v_mfma_f32_16x16x32_bf16 v[20:23], v[174:177], v[206:209], v[20:23]
	v_mfma_f32_16x16x32_bf16 v[12:15], v[166:169], v[214:217], v[12:15]
	v_mfma_f32_16x16x32_bf16 v[8:11], v[174:177], v[214:217], v[8:11]
	v_mfma_f32_16x16x32_bf16 v[4:7], v[166:169], v[222:225], v[4:7]
	v_mfma_f32_16x16x32_bf16 v[0:3], v[174:177], v[222:225], v[0:3]
	s_setprio 0
	s_barrier
	s_add_i32 s81, 0, 0x18000
	s_add_i32 s82, 0, 0x1c000
	v_add_u32_e32 v158, s81, v149
	v_add_u32_e32 v174, s82, v149
	ds_read_b128 v[136:139], v158
	ds_read_b128 v[140:143], v158 offset:1024
	ds_read_b128 v[144:147], v158 offset:2048
	ds_read_b128 v[158:161], v158 offset:3072
	ds_read_b128 v[162:165], v174
	ds_read_b128 v[166:169], v174 offset:1024
	ds_read_b128 v[170:173], v174 offset:2048
	ds_read_b128 v[174:177], v174 offset:3072
	s_add_u32 s22, s22, s8
	s_addc_u32 s23, s23, s9
	s_mov_b32 m0, s54
	v_lshl_add_u64 v[240:241], s[22:23], 0, v[112:113]
	ds_read_b128 v[178:181], v151 offset:32768
	ds_read_b128 v[198:201], v151 offset:33792
	ds_read_b128 v[202:205], v151 offset:34816
	ds_read_b128 v[206:209], v151 offset:35840
	ds_read_b128 v[210:213], v151 offset:36864
	ds_read_b128 v[214:217], v151 offset:37888
	ds_read_b128 v[218:221], v151 offset:38912
	ds_read_b128 v[222:225], v151 offset:39936
	global_load_lds_dwordx4 v[240:241], off
	v_lshl_add_u64 v[240:241], s[22:23], 0, v[130:131]
	s_mov_b32 m0, s55
	s_nop 0
	global_load_lds_dwordx4 v[240:241], off
	s_waitcnt vmcnt(8)
	s_waitcnt lgkmcnt(0)
	s_barrier
	s_setprio 1
	v_mfma_f32_16x16x32_bf16 v[126:129], v[136:139], v[178:181], v[126:129]
	v_mfma_f32_16x16x32_bf16 v[122:125], v[144:147], v[178:181], v[122:125]
	v_mfma_f32_16x16x32_bf16 v[118:121], v[136:139], v[202:205], v[118:121]
	v_mfma_f32_16x16x32_bf16 v[114:117], v[144:147], v[202:205], v[114:117]
	v_mfma_f32_16x16x32_bf16 v[104:107], v[136:139], v[210:213], v[104:107]
	v_mfma_f32_16x16x32_bf16 v[96:99], v[144:147], v[210:213], v[96:99]
	v_mfma_f32_16x16x32_bf16 v[88:91], v[136:139], v[218:221], v[88:91]
	v_mfma_f32_16x16x32_bf16 v[80:83], v[144:147], v[218:221], v[80:83]
	v_mfma_f32_16x16x32_bf16 v[126:129], v[140:143], v[198:201], v[126:129]
	v_mfma_f32_16x16x32_bf16 v[122:125], v[158:161], v[198:201], v[122:125]
	v_mfma_f32_16x16x32_bf16 v[118:121], v[140:143], v[206:209], v[118:121]
	v_mfma_f32_16x16x32_bf16 v[114:117], v[158:161], v[206:209], v[114:117]
	v_mfma_f32_16x16x32_bf16 v[104:107], v[140:143], v[214:217], v[104:107]
	v_mfma_f32_16x16x32_bf16 v[96:99], v[158:161], v[214:217], v[96:99]
	v_mfma_f32_16x16x32_bf16 v[88:91], v[140:143], v[222:225], v[88:91]
	v_mfma_f32_16x16x32_bf16 v[80:83], v[158:161], v[222:225], v[80:83]
	v_mfma_f32_16x16x32_bf16 v[108:111], v[162:165], v[178:181], v[108:111]
	v_mfma_f32_16x16x32_bf16 v[100:103], v[170:173], v[178:181], v[100:103]
	v_mfma_f32_16x16x32_bf16 v[92:95], v[162:165], v[202:205], v[92:95]
	v_mfma_f32_16x16x32_bf16 v[84:87], v[170:173], v[202:205], v[84:87]
	v_mfma_f32_16x16x32_bf16 v[76:79], v[162:165], v[210:213], v[76:79]
	v_mfma_f32_16x16x32_bf16 v[72:75], v[170:173], v[210:213], v[72:75]
	v_mfma_f32_16x16x32_bf16 v[68:71], v[162:165], v[218:221], v[68:71]
	v_mfma_f32_16x16x32_bf16 v[64:67], v[170:173], v[218:221], v[64:67]
	v_mfma_f32_16x16x32_bf16 v[108:111], v[166:169], v[198:201], v[108:111]
	v_mfma_f32_16x16x32_bf16 v[100:103], v[174:177], v[198:201], v[100:103]
	v_mfma_f32_16x16x32_bf16 v[92:95], v[166:169], v[206:209], v[92:95]
	v_mfma_f32_16x16x32_bf16 v[84:87], v[174:177], v[206:209], v[84:87]
	v_mfma_f32_16x16x32_bf16 v[76:79], v[166:169], v[214:217], v[76:79]
	v_mfma_f32_16x16x32_bf16 v[72:75], v[174:177], v[214:217], v[72:75]
	v_mfma_f32_16x16x32_bf16 v[68:71], v[166:169], v[222:225], v[68:71]
	v_mfma_f32_16x16x32_bf16 v[64:67], v[174:177], v[222:225], v[64:67]
	s_setprio 0
	s_barrier
; #define PG8_STAGE(bufoff, gbase, voff) do { _Pragma("unroll") for (int _i = 0; _i < 2; ++_i) \
;         __builtin_amdgcn_global_load_lds((const unsigned*)((const char*)(gbase) + (voff)[_i]), (PG8_LAS unsigned*)(lds + (bufoff) + ldsw + _i * 8192), 16, 0, 0); } while (0)
; #define PG8_LDA(dst, b, h) do { _Pragma("unroll") for (int m = 0; m < 4; ++m) _Pragma("unroll") for (int k = 0; k < 2; ++k) dst[m][k] = *(const PG8_LAS bf16x8*)(lds + PG8_SA(b, h) + aoff + m * 2048 + k * 1024); } while (0)
; #define PG8_MMA(ai, bj, At, Bt) do { __builtin_amdgcn_s_setprio(1); _Pragma("unroll") for (int m = 0; m < 4; ++m) _Pragma("unroll") for (int n = 0; n < 2; ++n) _Pragma("unroll") for (int k = 0; k < 2; ++k) \
;         acc[ai][bj][m][n] = __builtin_amdgcn_mfma_f32_16x16x32_bf16(Bt[n][k], At[m][k], acc[ai][bj][m][n], 0, 0, 0); __builtin_amdgcn_s_setprio(0); } while (0)
; #define PG8_WAIT_V(n) asm volatile("s_waitcnt vmcnt(" #n ")" ::: "memory")
; #define PG8_WAIT_L(n) asm volatile("s_waitcnt lgkmcnt(" #n ")" ::: "memory")
; #define PG8_BAR __builtin_amdgcn_s_barrier()
; #define PG8_SCHED __builtin_amdgcn_sched_barrier(0)
; template <class Epi, class Sched, bool ALIGN_EPI = false, bool SP2 = false>
; __device__ __forceinline__ void gemm_phase(PG8_LAS unsigned char* lds, const Gemm g, const Sched& S, const Epi& E) {
;     ...
;             PG8_LDA(At, 1, 1); PG8_STAGE(PG8_SB(1, 0), b3, voffB); PG8_STAGE(PG8_SB(1, 1), b3 + hstep, voffB); PG8_STAGE(PG8_SA(1, 0), a3, voffA);
;             PG8_WAIT_V(8); PG8_WAIT_L(0); PG8_BAR; PG8_MMA(1, 0, At, B0); PG8_MMA(1, 1, At, B1); PG8_BAR; PG8_SCHED;
	s_add_i32 s22, s81, s3
	v_lshl_add_u64 v[152:153], v[152:153], 0, s[52:53]
	s_mov_b32 m0, s22
	ds_read_b128 v[178:181], v151 offset:49152
	ds_read_b128 v[198:201], v151 offset:50176
	ds_read_b128 v[202:205], v151 offset:51200
	ds_read_b128 v[206:209], v151 offset:52224
	ds_read_b128 v[210:213], v151 offset:53248
	ds_read_b128 v[214:217], v151 offset:54272
	ds_read_b128 v[218:221], v151 offset:55296
	ds_read_b128 v[222:225], v151 offset:56320
	global_load_lds_dwordx4 v[152:153], off
	v_lshl_add_u64 v[152:153], v[226:227], 0, s[52:53]
	s_add_i32 m0, s22, 0x2000
	s_add_i32 s22, s82, s3
	global_load_lds_dwordx4 v[152:153], off
	v_lshl_add_u64 v[152:153], v[228:229], 0, s[52:53]
	s_mov_b32 m0, s22
	s_nop 0
	global_load_lds_dwordx4 v[152:153], off
	v_lshl_add_u64 v[152:153], v[234:235], 0, s[52:53]
	s_add_i32 m0, s22, 0x2000
	s_nop 0
	global_load_lds_dwordx4 v[152:153], off
	v_lshl_add_u64 v[152:153], v[236:237], 0, s[52:53]
	s_mov_b32 m0, s57
	s_nop 0
	global_load_lds_dwordx4 v[152:153], off
	v_lshl_add_u64 v[152:153], v[238:239], 0, s[52:53]
	s_mov_b32 m0, s64
	s_nop 0
	global_load_lds_dwordx4 v[152:153], off
	s_waitcnt vmcnt(8)
	s_waitcnt lgkmcnt(0)
	s_barrier
	s_setprio 1
	v_mfma_f32_16x16x32_bf16 v[60:63], v[136:139], v[178:181], v[60:63]
	v_mfma_f32_16x16x32_bf16 v[56:59], v[144:147], v[178:181], v[56:59]
	v_mfma_f32_16x16x32_bf16 v[52:55], v[136:139], v[202:205], v[52:55]
	v_mfma_f32_16x16x32_bf16 v[48:51], v[144:147], v[202:205], v[48:51]
	v_mfma_f32_16x16x32_bf16 v[40:43], v[136:139], v[210:213], v[40:43]
	v_mfma_f32_16x16x32_bf16 v[32:35], v[144:147], v[210:213], v[32:35]
	v_mfma_f32_16x16x32_bf16 v[24:27], v[136:139], v[218:221], v[24:27]
	v_mfma_f32_16x16x32_bf16 v[16:19], v[144:147], v[218:221], v[16:19]
	v_mfma_f32_16x16x32_bf16 v[60:63], v[140:143], v[198:201], v[60:63]
	v_mfma_f32_16x16x32_bf16 v[56:59], v[158:161], v[198:201], v[56:59]
	v_mfma_f32_16x16x32_bf16 v[52:55], v[140:143], v[206:209], v[52:55]
	v_mfma_f32_16x16x32_bf16 v[48:51], v[158:161], v[206:209], v[48:51]
	v_mfma_f32_16x16x32_bf16 v[40:43], v[140:143], v[214:217], v[40:43]
	v_mfma_f32_16x16x32_bf16 v[32:35], v[158:161], v[214:217], v[32:35]
	v_mfma_f32_16x16x32_bf16 v[24:27], v[140:143], v[222:225], v[24:27]
	v_mfma_f32_16x16x32_bf16 v[16:19], v[158:161], v[222:225], v[16:19]
	v_mfma_f32_16x16x32_bf16 v[44:47], v[162:165], v[178:181], v[44:47]
	v_mfma_f32_16x16x32_bf16 v[36:39], v[170:173], v[178:181], v[36:39]
	v_mfma_f32_16x16x32_bf16 v[28:31], v[162:165], v[202:205], v[28:31]
	v_mfma_f32_16x16x32_bf16 v[20:23], v[170:173], v[202:205], v[20:23]
	v_mfma_f32_16x16x32_bf16 v[12:15], v[162:165], v[210:213], v[12:15]
	v_mfma_f32_16x16x32_bf16 v[8:11], v[170:173], v[210:213], v[8:11]
	v_mfma_f32_16x16x32_bf16 v[4:7], v[162:165], v[218:221], v[4:7]
	v_mfma_f32_16x16x32_bf16 v[0:3], v[170:173], v[218:221], v[0:3]
	v_mfma_f32_16x16x32_bf16 v[44:47], v[166:169], v[198:201], v[44:47]
	v_mfma_f32_16x16x32_bf16 v[36:39], v[174:177], v[198:201], v[36:39]
	v_mfma_f32_16x16x32_bf16 v[28:31], v[166:169], v[206:209], v[28:31]
	v_mfma_f32_16x16x32_bf16 v[20:23], v[174:177], v[206:209], v[20:23]
	v_mfma_f32_16x16x32_bf16 v[12:15], v[166:169], v[214:217], v[12:15]
	v_mfma_f32_16x16x32_bf16 v[8:11], v[174:177], v[214:217], v[8:11]
	v_mfma_f32_16x16x32_bf16 v[4:7], v[166:169], v[222:225], v[4:7]
	v_mfma_f32_16x16x32_bf16 v[0:3], v[174:177], v[222:225], v[0:3]
	s_setprio 0
	s_barrier
	s_add_u32 s20, s20, 0x100
	s_addc_u32 s21, s21, 0
	s_add_u32 s77, s77, 0x100
	s_addc_u32 s79, s79, 0
	s_cmp_ge_i32 s80, s56
	s_mov_b32 s22, s80
	s_cbranch_scc0 .LBB0_754
;     __device__ __forceinline__ void operator()(const f32x4 (&acc)[2][2][4][2], const pg8::Unit& u, int wr, int wc, int fr, int fq) const {
;         const int col0 = u.pn * 256 + wc * 32 + 4 * fq;
; #pragma unroll
;         for (int ai = 0; ai < 2; ++ai)
; #pragma unroll
;             for (int m = 0; m < 4; ++m) {
;                 const size_t off = (size_t)(u.pm * 256 + ai * 128 + wr * 64 + m * 16 + fr) * DM + col0;
; #pragma unroll
;                 for (int bj = 0; bj < 2; ++bj)
; #pragma unroll
;                     for (int n = 0; n < 2; ++n) { const f32x4 b = *(const f32x4*)(base + off + bj * 128 + n * 16); *(f32x4*)(out + off + bj * 128 + n * 16) = b + acc[ai][bj][m][n] * scale; }
	v_pk_mul_f32 v[140:141], v[128:129], 0.5 op_sel_hi:[1,0]
	v_pk_mul_f32 v[142:143], v[126:127], 0.5 op_sel_hi:[1,0]
	v_pk_mul_f32 v[138:139], v[124:125], 0.5 op_sel_hi:[1,0]
	v_pk_mul_f32 v[136:137], v[122:123], 0.5 op_sel_hi:[1,0]
	v_pk_mul_f32 v[146:147], v[110:111], 0.5 op_sel_hi:[1,0]
	v_pk_mul_f32 v[144:145], v[108:109], 0.5 op_sel_hi:[1,0]
	v_pk_mul_f32 v[126:127], v[102:103], 0.5 op_sel_hi:[1,0]
	v_pk_mul_f32 v[128:129], v[100:101], 0.5 op_sel_hi:[1,0]
	v_pk_mul_f32 v[120:121], v[120:121], 0.5 op_sel_hi:[1,0]
	v_pk_mul_f32 v[118:119], v[118:119], 0.5 op_sel_hi:[1,0]
	v_pk_mul_f32 v[116:117], v[116:117], 0.5 op_sel_hi:[1,0]
	v_pk_mul_f32 v[114:115], v[114:115], 0.5 op_sel_hi:[1,0]
	v_pk_mul_f32 v[124:125], v[94:95], 0.5 op_sel_hi:[1,0]
	v_pk_mul_f32 v[122:123], v[92:93], 0.5 op_sel_hi:[1,0]
	v_pk_mul_f32 v[108:109], v[86:87], 0.5 op_sel_hi:[1,0]
	v_pk_mul_f32 v[110:111], v[84:85], 0.5 op_sel_hi:[1,0]
	v_pk_mul_f32 v[100:101], v[106:107], 0.5 op_sel_hi:[1,0]
	v_pk_mul_f32 v[102:103], v[104:105], 0.5 op_sel_hi:[1,0]
	v_pk_mul_f32 v[98:99], v[98:99], 0.5 op_sel_hi:[1,0]
	v_pk_mul_f32 v[96:97], v[96:97], 0.5 op_sel_hi:[1,0]
	v_pk_mul_f32 v[106:107], v[78:79], 0.5 op_sel_hi:[1,0]
	v_pk_mul_f32 v[104:105], v[76:77], 0.5 op_sel_hi:[1,0]
	v_pk_mul_f32 v[92:93], v[74:75], 0.5 op_sel_hi:[1,0]
	v_pk_mul_f32 v[94:95], v[72:73], 0.5 op_sel_hi:[1,0]
	v_pk_mul_f32 v[84:85], v[90:91], 0.5 op_sel_hi:[1,0]
	v_pk_mul_f32 v[86:87], v[88:89], 0.5 op_sel_hi:[1,0]
	v_pk_mul_f32 v[78:79], v[82:83], 0.5 op_sel_hi:[1,0]
	v_pk_mul_f32 v[76:77], v[80:81], 0.5 op_sel_hi:[1,0]
	v_pk_mul_f32 v[90:91], v[70:71], 0.5 op_sel_hi:[1,0]
	v_pk_mul_f32 v[88:89], v[68:69], 0.5 op_sel_hi:[1,0]
	v_pk_mul_f32 v[72:73], v[66:67], 0.5 op_sel_hi:[1,0]
	v_pk_mul_f32 v[74:75], v[64:65], 0.5 op_sel_hi:[1,0]
	v_pk_mul_f32 v[68:69], v[62:63], 0.5 op_sel_hi:[1,0]
	v_pk_mul_f32 v[70:71], v[60:61], 0.5 op_sel_hi:[1,0]
	v_pk_mul_f32 v[66:67], v[58:59], 0.5 op_sel_hi:[1,0]
	v_pk_mul_f32 v[64:65], v[56:57], 0.5 op_sel_hi:[1,0]
	v_pk_mul_f32 v[82:83], v[46:47], 0.5 op_sel_hi:[1,0]
	v_pk_mul_f32 v[80:81], v[44:45], 0.5 op_sel_hi:[1,0]
	v_pk_mul_f32 v[60:61], v[38:39], 0.5 op_sel_hi:[1,0]
	v_pk_mul_f32 v[62:63], v[36:37], 0.5 op_sel_hi:[1,0]
	v_pk_mul_f32 v[54:55], v[54:55], 0.5 op_sel_hi:[1,0]
	v_pk_mul_f32 v[52:53], v[52:53], 0.5 op_sel_hi:[1,0]
	v_pk_mul_f32 v[50:51], v[50:51], 0.5 op_sel_hi:[1,0]
	v_pk_mul_f32 v[48:49], v[48:49], 0.5 op_sel_hi:[1,0]
	v_pk_mul_f32 v[58:59], v[30:31], 0.5 op_sel_hi:[1,0]
	v_pk_mul_f32 v[56:57], v[28:29], 0.5 op_sel_hi:[1,0]
	v_pk_mul_f32 v[44:45], v[22:23], 0.5 op_sel_hi:[1,0]
	v_pk_mul_f32 v[46:47], v[20:21], 0.5 op_sel_hi:[1,0]
	v_pk_mul_f32 v[36:37], v[42:43], 0.5 op_sel_hi:[1,0]
	v_pk_mul_f32 v[38:39], v[40:41], 0.5 op_sel_hi:[1,0]
	v_pk_mul_f32 v[30:31], v[34:35], 0.5 op_sel_hi:[1,0]
	v_pk_mul_f32 v[28:29], v[32:33], 0.5 op_sel_hi:[1,0]
	v_pk_mul_f32 v[34:35], v[14:15], 0.5 op_sel_hi:[1,0]
	v_pk_mul_f32 v[32:33], v[12:13], 0.5 op_sel_hi:[1,0]
	v_pk_mul_f32 v[20:21], v[10:11], 0.5 op_sel_hi:[1,0]
	v_pk_mul_f32 v[22:23], v[8:9], 0.5 op_sel_hi:[1,0]
	v_pk_mul_f32 v[12:13], v[26:27], 0.5 op_sel_hi:[1,0]
	v_pk_mul_f32 v[14:15], v[24:25], 0.5 op_sel_hi:[1,0]
	v_pk_mul_f32 v[10:11], v[18:19], 0.5 op_sel_hi:[1,0]
	v_pk_mul_f32 v[8:9], v[16:17], 0.5 op_sel_hi:[1,0]
	v_pk_mul_f32 v[6:7], v[6:7], 0.5 op_sel_hi:[1,0]
	v_pk_mul_f32 v[4:5], v[4:5], 0.5 op_sel_hi:[1,0]
	v_pk_mul_f32 v[2:3], v[2:3], 0.5 op_sel_hi:[1,0]
	v_pk_mul_f32 v[0:1], v[0:1], 0.5 op_sel_hi:[1,0]

; #define PG8_STAGE(bufoff, gbase, voff) do { _Pragma("unroll") for (int _i = 0; _i < 2; ++_i) \
;         __builtin_amdgcn_global_load_lds((const unsigned*)((const char*)(gbase) + (voff)[_i]), (PG8_LAS unsigned*)(lds + (bufoff) + ldsw + _i * 8192), 16, 0, 0); } while (0)
; #define PG8_LDA(dst, b, h) do { _Pragma("unroll") for (int m = 0; m < 4; ++m) _Pragma("unroll") for (int k = 0; k < 2; ++k) dst[m][k] = *(const PG8_LAS bf16x8*)(lds + PG8_SA(b, h) + aoff + m * 2048 + k * 1024); } while (0)
; #define PG8_LDB(dst, b, h) do { _Pragma("unroll") for (int n = 0; n < 2; ++n) _Pragma("unroll") for (int k = 0; k < 2; ++k) dst[n][k] = *(const PG8_LAS bf16x8*)(lds + PG8_SB(b, h) + boff + n * 2048 + k * 1024); } while (0)
; #define PG8_MMA(ai, bj, At, Bt) do { __builtin_amdgcn_s_setprio(1); _Pragma("unroll") for (int m = 0; m < 4; ++m) _Pragma("unroll") for (int n = 0; n < 2; ++n) _Pragma("unroll") for (int k = 0; k < 2; ++k) \
;         acc[ai][bj][m][n] = __builtin_amdgcn_mfma_f32_16x16x32_bf16(Bt[n][k], At[m][k], acc[ai][bj][m][n], 0, 0, 0); __builtin_amdgcn_s_setprio(0); } while (0)
; #define PG8_WAIT_V(n) asm volatile("s_waitcnt vmcnt(" #n ")" ::: "memory")
; #define PG8_WAIT_L(n) asm volatile("s_waitcnt lgkmcnt(" #n ")" ::: "memory")
; #define PG8_BAR __builtin_amdgcn_s_barrier()
; #define PG8_SCHED __builtin_amdgcn_sched_barrier(0)
; template <class Epi, class Sched, bool ALIGN_EPI = false, bool SP2 = false>
; __device__ __forceinline__ void gemm_phase(PG8_LAS unsigned char* lds, const Gemm g, const Sched& S, const Epi& E) {
;     ...
;         for (int t = 0; t < nt; t += 2) {
;             const bool last = (t == nt - 2);
;             const char* a1 = cA + (size_t)(t + 1) * kstep;
;             const char* a2 = last ? nA : cA + (size_t)(t + 2) * kstep; const char* b2 = last ? nB : cB + (size_t)(t + 2) * kstep;
;             const char* a3 = a2 + kstep; const char* b3 = b2 + kstep;
;             if (last && has_next) S.a_ready(nxt);
;             if constexpr (SP2) {
;             PG8_LDB(B0, 0, 0); PG8_LDB(B1, 0, 1); PG8_SCHED; PG8_LDA(At, 0, 0); PG8_STAGE(PG8_SA(1, 1), a1 + hstep, voffA);
;             PG8_WAIT_V(8); PG8_WAIT_L(0); PG8_BAR; PG8_MMA(0, 0, At, B0); PG8_MMA(0, 1, At, B1); PG8_BAR; PG8_SCHED;
;             PG8_LDA(At, 0, 1); PG8_STAGE(PG8_SB(0, 0), b2, voffB); PG8_STAGE(PG8_SB(0, 1), b2 + hstep, voffB); PG8_STAGE(PG8_SA(0, 0), a2, voffA);
.LBB0_779:
	s_add_i32 s80, s22, 2
	s_add_u32 s81, s20, 0x80
	s_addc_u32 s23, s21, 0
	s_add_i32 vcc_lo, 0, 0x10000
	s_cmp_eq_u32 s65, s22
	s_cselect_b32 s23, s7, s23
	s_cselect_b32 s22, s6, s81
	v_add_u32_e32 v152, vcc_lo, v141
	s_cselect_b32 s83, s19, s79
	s_cselect_b32 s82, s18, s77
	s_add_i32 s81, 0, 0x14000
	ds_read_b128 v[144:147], v152
	ds_read_b128 v[148:151], v152 offset:1024
	ds_read_b128 v[158:161], v152 offset:2048
	ds_read_b128 v[162:165], v152 offset:3072
	v_add_u32_e32 v152, s81, v141
	ds_read_b128 v[166:169], v152
	ds_read_b128 v[170:173], v152 offset:1024
	ds_read_b128 v[174:177], v152 offset:2048
	ds_read_b128 v[178:181], v152 offset:3072
	v_lshl_add_u64 v[152:153], s[20:21], 0, v[136:137]
	s_add_i32 m0, s50, 0xc000
	ds_read_b128 v[198:201], v143
	ds_read_b128 v[202:205], v143 offset:1024
	ds_read_b128 v[206:209], v143 offset:2048
	ds_read_b128 v[210:213], v143 offset:3072
	ds_read_b128 v[214:217], v143 offset:4096
	ds_read_b128 v[218:221], v143 offset:5120
	ds_read_b128 v[222:225], v143 offset:6144
	ds_read_b128 v[226:229], v143 offset:7168
	global_load_lds_dwordx4 v[152:153], off
	v_lshl_add_u64 v[152:153], s[20:21], 0, v[138:139]
	s_add_i32 m0, s50, 0xe000
	s_nop 0
	global_load_lds_dwordx4 v[152:153], off
	s_waitcnt vmcnt(8)
	s_waitcnt lgkmcnt(0)
	s_barrier
	s_setprio 1
	v_mfma_f32_16x16x32_bf16 v[122:125], v[144:147], v[198:201], v[122:125]
	v_mfma_f32_16x16x32_bf16 v[118:121], v[158:161], v[198:201], v[118:121]
	v_mfma_f32_16x16x32_bf16 v[104:107], v[144:147], v[206:209], v[104:107]
	v_mfma_f32_16x16x32_bf16 v[100:103], v[158:161], v[206:209], v[100:103]
	v_mfma_f32_16x16x32_bf16 v[88:91], v[144:147], v[214:217], v[88:91]
	v_mfma_f32_16x16x32_bf16 v[84:87], v[158:161], v[214:217], v[84:87]
	v_mfma_f32_16x16x32_bf16 v[72:75], v[144:147], v[222:225], v[72:75]
	v_mfma_f32_16x16x32_bf16 v[68:71], v[158:161], v[222:225], v[68:71]
	v_mfma_f32_16x16x32_bf16 v[122:125], v[148:151], v[202:205], v[122:125]
	v_mfma_f32_16x16x32_bf16 v[118:121], v[162:165], v[202:205], v[118:121]
	v_mfma_f32_16x16x32_bf16 v[104:107], v[148:151], v[210:213], v[104:107]
	v_mfma_f32_16x16x32_bf16 v[100:103], v[162:165], v[210:213], v[100:103]
	v_mfma_f32_16x16x32_bf16 v[88:91], v[148:151], v[218:221], v[88:91]
	v_mfma_f32_16x16x32_bf16 v[84:87], v[162:165], v[218:221], v[84:87]
	v_mfma_f32_16x16x32_bf16 v[72:75], v[148:151], v[226:229], v[72:75]
	v_mfma_f32_16x16x32_bf16 v[68:71], v[162:165], v[226:229], v[68:71]
	v_mfma_f32_16x16x32_bf16 v[126:129], v[166:169], v[198:201], v[126:129]
	v_mfma_f32_16x16x32_bf16 v[114:117], v[174:177], v[198:201], v[114:117]
	v_mfma_f32_16x16x32_bf16 v[108:111], v[166:169], v[206:209], v[108:111]
	v_mfma_f32_16x16x32_bf16 v[96:99], v[174:177], v[206:209], v[96:99]
	v_mfma_f32_16x16x32_bf16 v[92:95], v[166:169], v[214:217], v[92:95]
	v_mfma_f32_16x16x32_bf16 v[80:83], v[174:177], v[214:217], v[80:83]
	v_mfma_f32_16x16x32_bf16 v[76:79], v[166:169], v[222:225], v[76:79]
	v_mfma_f32_16x16x32_bf16 v[64:67], v[174:177], v[222:225], v[64:67]
	v_mfma_f32_16x16x32_bf16 v[126:129], v[170:173], v[202:205], v[126:129]
	v_mfma_f32_16x16x32_bf16 v[114:117], v[178:181], v[202:205], v[114:117]
	v_mfma_f32_16x16x32_bf16 v[108:111], v[170:173], v[210:213], v[108:111]
	v_mfma_f32_16x16x32_bf16 v[96:99], v[178:181], v[210:213], v[96:99]
	v_mfma_f32_16x16x32_bf16 v[92:95], v[170:173], v[218:221], v[92:95]
	v_mfma_f32_16x16x32_bf16 v[80:83], v[178:181], v[218:221], v[80:83]
	v_mfma_f32_16x16x32_bf16 v[76:79], v[170:173], v[226:229], v[76:79]
	v_mfma_f32_16x16x32_bf16 v[64:67], v[178:181], v[226:229], v[64:67]
	s_setprio 0
	s_barrier
	s_add_i32 vcc_lo, vcc_lo, s3
	v_lshl_add_u64 v[152:153], s[82:83], 0, v[112:113]
	s_mov_b32 m0, vcc_lo
	ds_read_b128 v[198:201], v143 offset:16384
	ds_read_b128 v[202:205], v143 offset:17408
	ds_read_b128 v[206:209], v143 offset:18432
	ds_read_b128 v[210:213], v143 offset:19456
	ds_read_b128 v[214:217], v143 offset:20480
	ds_read_b128 v[218:221], v143 offset:21504
	ds_read_b128 v[222:225], v143 offset:22528
	ds_read_b128 v[226:229], v143 offset:23552
	global_load_lds_dwordx4 v[152:153], off
	s_add_i32 m0, vcc_lo, 0x2000
	v_lshl_add_u64 v[234:235], s[82:83], 0, v[130:131]
	s_add_u32 s82, s82, s8
	s_addc_u32 s83, s83, s9
	s_add_i32 s81, s81, s3
	global_load_lds_dwordx4 v[234:235], off
	v_lshl_add_u64 v[236:237], s[82:83], 0, v[112:113]
	s_mov_b32 m0, s81
	v_lshl_add_u64 v[238:239], s[82:83], 0, v[130:131]
	global_load_lds_dwordx4 v[236:237], off
	s_add_i32 m0, s81, 0x2000
	v_lshl_add_u64 v[240:241], s[22:23], 0, v[134:135]
	global_load_lds_dwordx4 v[238:239], off
	s_mov_b32 m0, s50
	v_lshl_add_u64 v[242:243], s[22:23], 0, v[132:133]
	global_load_lds_dwordx4 v[240:241], off
	s_mov_b32 m0, s51
	s_nop 0
	global_load_lds_dwordx4 v[242:243], off
	s_waitcnt vmcnt(8)
	s_waitcnt lgkmcnt(0)
	s_barrier
; #define PG8_STAGE(bufoff, gbase, voff) do { _Pragma("unroll") for (int _i = 0; _i < 2; ++_i) \
;         __builtin_amdgcn_global_load_lds((const unsigned*)((const char*)(gbase) + (voff)[_i]), (PG8_LAS unsigned*)(lds + (bufoff) + ldsw + _i * 8192), 16, 0, 0); } while (0)
; #define PG8_LDA(dst, b, h) do { _Pragma("unroll") for (int m = 0; m < 4; ++m) _Pragma("unroll") for (int k = 0; k < 2; ++k) dst[m][k] = *(const PG8_LAS bf16x8*)(lds + PG8_SA(b, h) + aoff + m * 2048 + k * 1024); } while (0)
; #define PG8_LDB(dst, b, h) do { _Pragma("unroll") for (int n = 0; n < 2; ++n) _Pragma("unroll") for (int k = 0; k < 2; ++k) dst[n][k] = *(const PG8_LAS bf16x8*)(lds + PG8_SB(b, h) + boff + n * 2048 + k * 1024); } while (0)
; #define PG8_MMA(ai, bj, At, Bt) do { __builtin_amdgcn_s_setprio(1); _Pragma("unroll") for (int m = 0; m < 4; ++m) _Pragma("unroll") for (int n = 0; n < 2; ++n) _Pragma("unroll") for (int k = 0; k < 2; ++k) \
;         acc[ai][bj][m][n] = __builtin_amdgcn_mfma_f32_16x16x32_bf16(Bt[n][k], At[m][k], acc[ai][bj][m][n], 0, 0, 0); __builtin_amdgcn_s_setprio(0); } while (0)
; #define PG8_WAIT_V(n) asm volatile("s_waitcnt vmcnt(" #n ")" ::: "memory")
; #define PG8_WAIT_L(n) asm volatile("s_waitcnt lgkmcnt(" #n ")" ::: "memory")
; #define PG8_BAR __builtin_amdgcn_s_barrier()
; #define PG8_SCHED __builtin_amdgcn_sched_barrier(0)
; template <class Epi, class Sched, bool ALIGN_EPI = false, bool SP2 = false>
; __device__ __forceinline__ void gemm_phase(PG8_LAS unsigned char* lds, const Gemm g, const Sched& S, const Epi& E) {
;     ...
;             PG8_WAIT_V(8); PG8_WAIT_L(0); PG8_BAR; PG8_MMA(1, 0, At, B0); PG8_MMA(1, 1, At, B1); PG8_BAR; PG8_SCHED;
;             PG8_LDB(B0, 1, 0); PG8_LDB(B1, 1, 1); PG8_SCHED; PG8_LDA(At, 1, 0); PG8_STAGE(PG8_SA(0, 1), a2 + hstep, voffA);
;             PG8_WAIT_V(8); PG8_WAIT_L(0); PG8_BAR; PG8_MMA(0, 0, At, B0); PG8_MMA(0, 1, At, B1); PG8_BAR; PG8_SCHED;
	s_setprio 1
	v_mfma_f32_16x16x32_bf16 v[56:59], v[144:147], v[198:201], v[56:59]
	v_mfma_f32_16x16x32_bf16 v[52:55], v[158:161], v[198:201], v[52:55]
	v_mfma_f32_16x16x32_bf16 v[40:43], v[144:147], v[206:209], v[40:43]
	v_mfma_f32_16x16x32_bf16 v[36:39], v[158:161], v[206:209], v[36:39]
	v_mfma_f32_16x16x32_bf16 v[24:27], v[144:147], v[214:217], v[24:27]
	v_mfma_f32_16x16x32_bf16 v[20:23], v[158:161], v[214:217], v[20:23]
	v_mfma_f32_16x16x32_bf16 v[8:11], v[144:147], v[222:225], v[8:11]
	v_mfma_f32_16x16x32_bf16 v[4:7], v[158:161], v[222:225], v[4:7]
	v_mfma_f32_16x16x32_bf16 v[56:59], v[148:151], v[202:205], v[56:59]
	v_mfma_f32_16x16x32_bf16 v[52:55], v[162:165], v[202:205], v[52:55]
	v_mfma_f32_16x16x32_bf16 v[40:43], v[148:151], v[210:213], v[40:43]
	v_mfma_f32_16x16x32_bf16 v[36:39], v[162:165], v[210:213], v[36:39]
	v_mfma_f32_16x16x32_bf16 v[24:27], v[148:151], v[218:221], v[24:27]
	v_mfma_f32_16x16x32_bf16 v[20:23], v[162:165], v[218:221], v[20:23]
	v_mfma_f32_16x16x32_bf16 v[8:11], v[148:151], v[226:229], v[8:11]
	v_mfma_f32_16x16x32_bf16 v[4:7], v[162:165], v[226:229], v[4:7]
	v_mfma_f32_16x16x32_bf16 v[60:63], v[166:169], v[198:201], v[60:63]
	v_mfma_f32_16x16x32_bf16 v[48:51], v[174:177], v[198:201], v[48:51]
	v_mfma_f32_16x16x32_bf16 v[44:47], v[166:169], v[206:209], v[44:47]
	v_mfma_f32_16x16x32_bf16 v[32:35], v[174:177], v[206:209], v[32:35]
	v_mfma_f32_16x16x32_bf16 v[28:31], v[166:169], v[214:217], v[28:31]
	v_mfma_f32_16x16x32_bf16 v[16:19], v[174:177], v[214:217], v[16:19]
	v_mfma_f32_16x16x32_bf16 v[12:15], v[166:169], v[222:225], v[12:15]
	v_mfma_f32_16x16x32_bf16 v[0:3], v[174:177], v[222:225], v[0:3]
	v_mfma_f32_16x16x32_bf16 v[60:63], v[170:173], v[202:205], v[60:63]
	v_mfma_f32_16x16x32_bf16 v[48:51], v[178:181], v[202:205], v[48:51]
	v_mfma_f32_16x16x32_bf16 v[44:47], v[170:173], v[210:213], v[44:47]
	v_mfma_f32_16x16x32_bf16 v[32:35], v[178:181], v[210:213], v[32:35]
	v_mfma_f32_16x16x32_bf16 v[28:31], v[170:173], v[218:221], v[28:31]
	v_mfma_f32_16x16x32_bf16 v[16:19], v[178:181], v[218:221], v[16:19]
	v_mfma_f32_16x16x32_bf16 v[12:15], v[170:173], v[226:229], v[12:15]
	v_mfma_f32_16x16x32_bf16 v[0:3], v[178:181], v[226:229], v[0:3]
	s_setprio 0
	s_barrier
	s_add_i32 s81, 0, 0x18000
	s_add_i32 s82, 0, 0x1c000
	v_add_u32_e32 v162, s81, v141
	v_add_u32_e32 v178, s82, v141
	ds_read_b128 v[144:147], v162
	ds_read_b128 v[148:151], v162 offset:1024
	ds_read_b128 v[158:161], v162 offset:2048
	ds_read_b128 v[162:165], v162 offset:3072
	ds_read_b128 v[166:169], v178
	ds_read_b128 v[170:173], v178 offset:1024
	ds_read_b128 v[174:177], v178 offset:2048
	ds_read_b128 v[178:181], v178 offset:3072
	s_add_u32 s22, s22, s8
	s_addc_u32 s23, s23, s9
	s_mov_b32 m0, s54
	v_lshl_add_u64 v[244:245], s[22:23], 0, v[134:135]
	ds_read_b128 v[198:201], v143 offset:32768
	ds_read_b128 v[202:205], v143 offset:33792
	ds_read_b128 v[206:209], v143 offset:34816
	ds_read_b128 v[210:213], v143 offset:35840
	ds_read_b128 v[214:217], v143 offset:36864
	ds_read_b128 v[218:221], v143 offset:37888
	ds_read_b128 v[222:225], v143 offset:38912
	ds_read_b128 v[226:229], v143 offset:39936
	global_load_lds_dwordx4 v[244:245], off
	v_lshl_add_u64 v[244:245], s[22:23], 0, v[132:133]
	s_mov_b32 m0, s55
	s_nop 0
	global_load_lds_dwordx4 v[244:245], off
	s_waitcnt vmcnt(8)
	s_waitcnt lgkmcnt(0)
	s_barrier
	s_setprio 1
	v_mfma_f32_16x16x32_bf16 v[122:125], v[144:147], v[198:201], v[122:125]
	v_mfma_f32_16x16x32_bf16 v[118:121], v[158:161], v[198:201], v[118:121]
	v_mfma_f32_16x16x32_bf16 v[104:107], v[144:147], v[206:209], v[104:107]
	v_mfma_f32_16x16x32_bf16 v[100:103], v[158:161], v[206:209], v[100:103]
	v_mfma_f32_16x16x32_bf16 v[88:91], v[144:147], v[214:217], v[88:91]
	v_mfma_f32_16x16x32_bf16 v[84:87], v[158:161], v[214:217], v[84:87]
	v_mfma_f32_16x16x32_bf16 v[72:75], v[144:147], v[222:225], v[72:75]
	v_mfma_f32_16x16x32_bf16 v[68:71], v[158:161], v[222:225], v[68:71]
	v_mfma_f32_16x16x32_bf16 v[122:125], v[148:151], v[202:205], v[122:125]
	v_mfma_f32_16x16x32_bf16 v[118:121], v[162:165], v[202:205], v[118:121]
	v_mfma_f32_16x16x32_bf16 v[104:107], v[148:151], v[210:213], v[104:107]
	v_mfma_f32_16x16x32_bf16 v[100:103], v[162:165], v[210:213], v[100:103]
	v_mfma_f32_16x16x32_bf16 v[88:91], v[148:151], v[218:221], v[88:91]
	v_mfma_f32_16x16x32_bf16 v[84:87], v[162:165], v[218:221], v[84:87]
	v_mfma_f32_16x16x32_bf16 v[72:75], v[148:151], v[226:229], v[72:75]
	v_mfma_f32_16x16x32_bf16 v[68:71], v[162:165], v[226:229], v[68:71]
	v_mfma_f32_16x16x32_bf16 v[126:129], v[166:169], v[198:201], v[126:129]
	v_mfma_f32_16x16x32_bf16 v[114:117], v[174:177], v[198:201], v[114:117]
	v_mfma_f32_16x16x32_bf16 v[108:111], v[166:169], v[206:209], v[108:111]
	v_mfma_f32_16x16x32_bf16 v[96:99], v[174:177], v[206:209], v[96:99]
	v_mfma_f32_16x16x32_bf16 v[92:95], v[166:169], v[214:217], v[92:95]
	v_mfma_f32_16x16x32_bf16 v[80:83], v[174:177], v[214:217], v[80:83]
	v_mfma_f32_16x16x32_bf16 v[76:79], v[166:169], v[222:225], v[76:79]
	v_mfma_f32_16x16x32_bf16 v[64:67], v[174:177], v[222:225], v[64:67]
	v_mfma_f32_16x16x32_bf16 v[126:129], v[170:173], v[202:205], v[126:129]
	v_mfma_f32_16x16x32_bf16 v[114:117], v[178:181], v[202:205], v[114:117]
	v_mfma_f32_16x16x32_bf16 v[108:111], v[170:173], v[210:213], v[108:111]
	v_mfma_f32_16x16x32_bf16 v[96:99], v[178:181], v[210:213], v[96:99]
	v_mfma_f32_16x16x32_bf16 v[92:95], v[170:173], v[218:221], v[92:95]
	v_mfma_f32_16x16x32_bf16 v[80:83], v[178:181], v[218:221], v[80:83]
	v_mfma_f32_16x16x32_bf16 v[76:79], v[170:173], v[226:229], v[76:79]
	v_mfma_f32_16x16x32_bf16 v[64:67], v[178:181], v[226:229], v[64:67]
	s_setprio 0
	s_barrier
; #define PG8_STAGE(bufoff, gbase, voff) do { _Pragma("unroll") for (int _i = 0; _i < 2; ++_i) \
;         __builtin_amdgcn_global_load_lds((const unsigned*)((const char*)(gbase) + (voff)[_i]), (PG8_LAS unsigned*)(lds + (bufoff) + ldsw + _i * 8192), 16, 0, 0); } while (0)
; #define PG8_LDA(dst, b, h) do { _Pragma("unroll") for (int m = 0; m < 4; ++m) _Pragma("unroll") for (int k = 0; k < 2; ++k) dst[m][k] = *(const PG8_LAS bf16x8*)(lds + PG8_SA(b, h) + aoff + m * 2048 + k * 1024); } while (0)
; #define PG8_MMA(ai, bj, At, Bt) do { __builtin_amdgcn_s_setprio(1); _Pragma("unroll") for (int m = 0; m < 4; ++m) _Pragma("unroll") for (int n = 0; n < 2; ++n) _Pragma("unroll") for (int k = 0; k < 2; ++k) \
;         acc[ai][bj][m][n] = __builtin_amdgcn_mfma_f32_16x16x32_bf16(Bt[n][k], At[m][k], acc[ai][bj][m][n], 0, 0, 0); __builtin_amdgcn_s_setprio(0); } while (0)
; #define PG8_WAIT_V(n) asm volatile("s_waitcnt vmcnt(" #n ")" ::: "memory")
; #define PG8_WAIT_L(n) asm volatile("s_waitcnt lgkmcnt(" #n ")" ::: "memory")
; #define PG8_BAR __builtin_amdgcn_s_barrier()
; #define PG8_SCHED __builtin_amdgcn_sched_barrier(0)
; template <class Epi, class Sched, bool ALIGN_EPI = false, bool SP2 = false>
; __device__ __forceinline__ void gemm_phase(PG8_LAS unsigned char* lds, const Gemm g, const Sched& S, const Epi& E) {
;     ...
;             PG8_LDA(At, 1, 1); PG8_STAGE(PG8_SB(1, 0), b3, voffB); PG8_STAGE(PG8_SB(1, 1), b3 + hstep, voffB); PG8_STAGE(PG8_SA(1, 0), a3, voffA);
;             PG8_WAIT_V(8); PG8_WAIT_L(0); PG8_BAR; PG8_MMA(1, 0, At, B0); PG8_MMA(1, 1, At, B1); PG8_BAR; PG8_SCHED;
	s_add_i32 s22, s81, s3
	v_lshl_add_u64 v[152:153], v[152:153], 0, s[52:53]
	s_mov_b32 m0, s22
	ds_read_b128 v[198:201], v143 offset:49152
	ds_read_b128 v[202:205], v143 offset:50176
	ds_read_b128 v[206:209], v143 offset:51200
	ds_read_b128 v[210:213], v143 offset:52224
	ds_read_b128 v[214:217], v143 offset:53248
	ds_read_b128 v[218:221], v143 offset:54272
	ds_read_b128 v[222:225], v143 offset:55296
	ds_read_b128 v[226:229], v143 offset:56320
	global_load_lds_dwordx4 v[152:153], off
	v_lshl_add_u64 v[152:153], v[234:235], 0, s[52:53]
	s_add_i32 m0, s22, 0x2000
	s_add_i32 s22, s82, s3
	global_load_lds_dwordx4 v[152:153], off
	v_lshl_add_u64 v[152:153], v[236:237], 0, s[52:53]
	s_mov_b32 m0, s22
	s_nop 0
	global_load_lds_dwordx4 v[152:153], off
	v_lshl_add_u64 v[152:153], v[238:239], 0, s[52:53]
	s_add_i32 m0, s22, 0x2000
	s_nop 0
	global_load_lds_dwordx4 v[152:153], off
	v_lshl_add_u64 v[152:153], v[240:241], 0, s[52:53]
	s_mov_b32 m0, s56
	s_nop 0
	global_load_lds_dwordx4 v[152:153], off
	v_lshl_add_u64 v[152:153], v[242:243], 0, s[52:53]
	s_mov_b32 m0, s57
	s_nop 0
	global_load_lds_dwordx4 v[152:153], off
	s_waitcnt vmcnt(8)
	s_waitcnt lgkmcnt(0)
	s_barrier
	s_setprio 1
	v_mfma_f32_16x16x32_bf16 v[56:59], v[144:147], v[198:201], v[56:59]
	v_mfma_f32_16x16x32_bf16 v[52:55], v[158:161], v[198:201], v[52:55]
	v_mfma_f32_16x16x32_bf16 v[40:43], v[144:147], v[206:209], v[40:43]
	v_mfma_f32_16x16x32_bf16 v[36:39], v[158:161], v[206:209], v[36:39]
	v_mfma_f32_16x16x32_bf16 v[24:27], v[144:147], v[214:217], v[24:27]
	v_mfma_f32_16x16x32_bf16 v[20:23], v[158:161], v[214:217], v[20:23]
	v_mfma_f32_16x16x32_bf16 v[8:11], v[144:147], v[222:225], v[8:11]
	v_mfma_f32_16x16x32_bf16 v[4:7], v[158:161], v[222:225], v[4:7]
	v_mfma_f32_16x16x32_bf16 v[56:59], v[148:151], v[202:205], v[56:59]
	v_mfma_f32_16x16x32_bf16 v[52:55], v[162:165], v[202:205], v[52:55]
	v_mfma_f32_16x16x32_bf16 v[40:43], v[148:151], v[210:213], v[40:43]
	v_mfma_f32_16x16x32_bf16 v[36:39], v[162:165], v[210:213], v[36:39]
	v_mfma_f32_16x16x32_bf16 v[24:27], v[148:151], v[218:221], v[24:27]
	v_mfma_f32_16x16x32_bf16 v[20:23], v[162:165], v[218:221], v[20:23]
	v_mfma_f32_16x16x32_bf16 v[8:11], v[148:151], v[226:229], v[8:11]
	v_mfma_f32_16x16x32_bf16 v[4:7], v[162:165], v[226:229], v[4:7]
	v_mfma_f32_16x16x32_bf16 v[60:63], v[166:169], v[198:201], v[60:63]
	v_mfma_f32_16x16x32_bf16 v[48:51], v[174:177], v[198:201], v[48:51]
	v_mfma_f32_16x16x32_bf16 v[44:47], v[166:169], v[206:209], v[44:47]
	v_mfma_f32_16x16x32_bf16 v[32:35], v[174:177], v[206:209], v[32:35]
	v_mfma_f32_16x16x32_bf16 v[28:31], v[166:169], v[214:217], v[28:31]
	v_mfma_f32_16x16x32_bf16 v[16:19], v[174:177], v[214:217], v[16:19]
	v_mfma_f32_16x16x32_bf16 v[12:15], v[166:169], v[222:225], v[12:15]
	v_mfma_f32_16x16x32_bf16 v[0:3], v[174:177], v[222:225], v[0:3]
	v_mfma_f32_16x16x32_bf16 v[60:63], v[170:173], v[202:205], v[60:63]
	v_mfma_f32_16x16x32_bf16 v[48:51], v[178:181], v[202:205], v[48:51]
	v_mfma_f32_16x16x32_bf16 v[44:47], v[170:173], v[210:213], v[44:47]
	v_mfma_f32_16x16x32_bf16 v[32:35], v[178:181], v[210:213], v[32:35]
	v_mfma_f32_16x16x32_bf16 v[28:31], v[170:173], v[218:221], v[28:31]
	v_mfma_f32_16x16x32_bf16 v[16:19], v[178:181], v[218:221], v[16:19]
	v_mfma_f32_16x16x32_bf16 v[12:15], v[170:173], v[226:229], v[12:15]
	v_mfma_f32_16x16x32_bf16 v[0:3], v[178:181], v[226:229], v[0:3]
	s_setprio 0
	s_barrier
	s_add_u32 s20, s20, 0x100
	s_addc_u32 s21, s21, 0
	s_add_u32 s77, s77, 0x100
	s_addc_u32 s79, s79, 0
	s_cmp_ge_i32 s80, s64
	s_mov_b32 s22, s80
	s_cbranch_scc0 .LBB0_779
